# speedup vs baseline: 1.0300x; 1.0300x over previous
.LBB0_252:
	s_or_b64 exec, exec, s[10:11]
	v_add_u32_e32 v0, s53, v208
	v_add_u32_e32 v34, 0x80, v0
	v_cmp_le_i32_e32 vcc, v34, v157
	s_mov_b64 s[40:41], 0
	s_and_saveexec_b64 s[10:11], vcc
	s_cbranch_execz .LBB0_262
	v_add_u32_e32 v194, v191, v203
	v_add_u32_e32 v46, s33, v189
	ds_read_b128 v[220:223], v194
	ds_read_b128 v[82:85], v46 offset:35840
	ds_read_b128 v[86:89], v46 offset:35856
	ds_read_b128 v[90:93], v46 offset:35904
	ds_read_b128 v[94:97], v46 offset:35920
	ds_read_b128 v[224:227], v194 offset:4608
	ds_read_b128 v[66:69], v46 offset:35968
	ds_read_b128 v[70:73], v46 offset:35984
	ds_read_b128 v[74:77], v46 offset:36032
	ds_read_b128 v[78:81], v46 offset:36048
	ds_read_b128 v[228:231], v194 offset:9216
	ds_read_b128 v[50:53], v46 offset:36096
	ds_read_b128 v[54:57], v46 offset:36112
	ds_read_b128 v[58:61], v46 offset:36160
	ds_read_b128 v[62:65], v46 offset:36176
	ds_read_b128 v[232:235], v194 offset:13824
	ds_read_b128 v[34:37], v46 offset:36224
	ds_read_b128 v[38:41], v46 offset:36240
	ds_read_b128 v[42:45], v46 offset:36288
	ds_read_b128 v[46:49], v46 offset:36304
	ds_read_b128 v[236:239], v194 offset:32
	ds_read_b128 v[240:243], v194 offset:4640
	ds_read_b128 v[244:247], v194 offset:9248
	v_add_u32_e32 v0, 0xff, v0
	v_cmp_gt_i32_e32 vcc, v0, v160
	s_waitcnt lgkmcnt(15)
	v_mfma_f32_32x32x16_bf16 v[82:97], v[220:223], v[98:101], v[82:97]
	ds_read_b128 v[220:223], v194 offset:13856
	s_waitcnt lgkmcnt(14)
	v_mfma_f32_32x32x16_bf16 v[66:81], v[224:227], v[98:101], v[66:81]
	ds_read_b128 v[224:227], v194 offset:64
	s_waitcnt lgkmcnt(10)
	v_mfma_f32_32x32x16_bf16 v[50:65], v[228:231], v[98:101], v[50:65]
	ds_read_b128 v[228:231], v194 offset:4672
	s_waitcnt lgkmcnt(6)
	v_mfma_f32_32x32x16_bf16 v[34:49], v[232:235], v[98:101], v[34:49]
	ds_read_b128 v[232:235], v194 offset:9280
	s_waitcnt lgkmcnt(6)
	v_mfma_f32_32x32x16_bf16 v[82:97], v[236:239], v[102:105], v[82:97]
	ds_read_b128 v[236:239], v194 offset:13888
	s_waitcnt lgkmcnt(6)
	v_mfma_f32_32x32x16_bf16 v[66:81], v[240:243], v[102:105], v[66:81]
	ds_read_b128 v[240:243], v194 offset:96
	s_waitcnt lgkmcnt(6)
	v_mfma_f32_32x32x16_bf16 v[50:65], v[244:247], v[102:105], v[50:65]
	ds_read_b128 v[244:247], v194 offset:4704
	s_waitcnt lgkmcnt(6)
	v_mfma_f32_32x32x16_bf16 v[34:49], v[220:223], v[102:105], v[34:49]
	ds_read_b128 v[220:223], v194 offset:9312
	s_waitcnt lgkmcnt(6)
	v_mfma_f32_32x32x16_bf16 v[82:97], v[224:227], v[106:109], v[82:97]
	ds_read_b128 v[224:227], v194 offset:13920
	s_waitcnt lgkmcnt(6)
	v_mfma_f32_32x32x16_bf16 v[66:81], v[228:231], v[106:109], v[66:81]
	s_waitcnt lgkmcnt(5)
	v_mfma_f32_32x32x16_bf16 v[50:65], v[232:235], v[106:109], v[50:65]
	s_waitcnt lgkmcnt(4)
	v_mfma_f32_32x32x16_bf16 v[34:49], v[236:239], v[106:109], v[34:49]
	s_waitcnt lgkmcnt(3)
	v_mfma_f32_32x32x16_bf16 v[82:97], v[240:243], v[110:113], v[82:97]
	s_waitcnt lgkmcnt(2)
	v_mfma_f32_32x32x16_bf16 v[66:81], v[244:247], v[110:113], v[66:81]
	s_waitcnt lgkmcnt(1)
	v_mfma_f32_32x32x16_bf16 v[50:65], v[220:223], v[110:113], v[50:65]
	s_waitcnt lgkmcnt(0)
	v_mfma_f32_32x32x16_bf16 v[34:49], v[224:227], v[110:113], v[34:49]
	s_and_saveexec_b64 s[40:41], vcc
	s_cbranch_execz .LBB0_255
	v_add_u32_e32 v0, s53, v155
	v_add_u32_e32 v194, 0x80, v0
	v_cmp_lt_i32_e32 vcc, v194, v162
	s_nop 1
	v_cndmask_b32_e32 v83, v207, v83, vcc
	v_cmp_le_i32_e32 vcc, v194, v162
	v_add_u32_e32 v194, 0x82, v0
	s_nop 0
	v_cndmask_b32_e32 v82, v207, v82, vcc
	v_cmp_le_i32_e32 vcc, v194, v162
	v_add_u32_e32 v194, 0x83, v0
	s_nop 0
	v_cndmask_b32_e32 v84, v207, v84, vcc
	v_cmp_le_i32_e32 vcc, v194, v162
	v_add_u32_e32 v194, 0x84, v0
	s_nop 0
	v_cndmask_b32_e32 v85, v207, v85, vcc
	v_cmp_le_i32_e32 vcc, v194, v162
	v_add_u32_e32 v194, 0x85, v0
	s_nop 0
	v_cndmask_b32_e32 v86, v207, v86, vcc
	v_cmp_le_i32_e32 vcc, v194, v162
	v_add_u32_e32 v194, 0x86, v0
	s_nop 0
	v_cndmask_b32_e32 v87, v207, v87, vcc
	v_cmp_le_i32_e32 vcc, v194, v162
	v_add_u32_e32 v194, 0x87, v0
	s_nop 0
	v_cndmask_b32_e32 v88, v207, v88, vcc
	v_cmp_le_i32_e32 vcc, v194, v162
	v_add_u32_e32 v194, 0x90, v0
	s_nop 0
	v_cndmask_b32_e32 v89, v207, v89, vcc
	v_cmp_le_i32_e32 vcc, v194, v162
	v_add_u32_e32 v194, 0x91, v0
	s_nop 0
	v_cndmask_b32_e32 v90, v207, v90, vcc
	v_cmp_le_i32_e32 vcc, v194, v162
	v_add_u32_e32 v194, 0x92, v0
	s_nop 0
	v_cndmask_b32_e32 v91, v207, v91, vcc
	v_cmp_le_i32_e32 vcc, v194, v162
	v_add_u32_e32 v194, 0x93, v0
	s_nop 0
	v_cndmask_b32_e32 v92, v207, v92, vcc
	v_cmp_le_i32_e32 vcc, v194, v162
	v_add_u32_e32 v194, 0x94, v0
	s_nop 0
	v_cndmask_b32_e32 v93, v207, v93, vcc
	v_cmp_le_i32_e32 vcc, v194, v162
	v_add_u32_e32 v194, 0x95, v0
	s_nop 0
	v_cndmask_b32_e32 v94, v207, v94, vcc
	v_cmp_le_i32_e32 vcc, v194, v162
	v_add_u32_e32 v194, 0x96, v0
	s_nop 0
	v_cndmask_b32_e32 v95, v207, v95, vcc
	v_cmp_le_i32_e32 vcc, v194, v162
	v_add_u32_e32 v194, 0x97, v0
	s_nop 0
	v_cndmask_b32_e32 v96, v207, v96, vcc
	v_cmp_le_i32_e32 vcc, v194, v162
	v_add_u32_e32 v194, 0xa0, v0
	s_nop 0
	v_cndmask_b32_e32 v97, v207, v97, vcc
	v_cmp_le_i32_e32 vcc, v194, v162
	v_add_u32_e32 v194, 0xa1, v0
	s_nop 0
	v_cndmask_b32_e32 v66, v207, v66, vcc
	v_cmp_le_i32_e32 vcc, v194, v162
	v_add_u32_e32 v194, 0xa2, v0
	s_nop 0
	v_cndmask_b32_e32 v67, v207, v67, vcc
	v_cmp_le_i32_e32 vcc, v194, v162
	v_add_u32_e32 v194, 0xa3, v0
	s_nop 0
	v_cndmask_b32_e32 v68, v207, v68, vcc
	v_cmp_le_i32_e32 vcc, v194, v162
	v_add_u32_e32 v194, 0xa4, v0
	s_nop 0
	v_cndmask_b32_e32 v69, v207, v69, vcc
	v_cmp_le_i32_e32 vcc, v194, v162
	v_add_u32_e32 v194, 0xa5, v0
	s_nop 0
	v_cndmask_b32_e32 v70, v207, v70, vcc
	v_cmp_le_i32_e32 vcc, v194, v162
	v_add_u32_e32 v194, 0xa6, v0
	s_nop 0
	v_cndmask_b32_e32 v71, v207, v71, vcc
	v_cmp_le_i32_e32 vcc, v194, v162
	v_add_u32_e32 v194, 0xa7, v0
	s_nop 0
	v_cndmask_b32_e32 v72, v207, v72, vcc
	v_cmp_le_i32_e32 vcc, v194, v162
	v_add_u32_e32 v194, 0xb0, v0
	s_nop 0
	v_cndmask_b32_e32 v73, v207, v73, vcc
	v_cmp_le_i32_e32 vcc, v194, v162
	v_add_u32_e32 v194, 0xb1, v0
	s_nop 0
	v_cndmask_b32_e32 v74, v207, v74, vcc
	v_cmp_le_i32_e32 vcc, v194, v162
	v_add_u32_e32 v194, 0xb2, v0
	s_nop 0
	v_cndmask_b32_e32 v75, v207, v75, vcc
	v_cmp_le_i32_e32 vcc, v194, v162
	v_add_u32_e32 v194, 0xb3, v0
	s_nop 0
	v_cndmask_b32_e32 v76, v207, v76, vcc
	v_cmp_le_i32_e32 vcc, v194, v162
	v_add_u32_e32 v194, 0xb4, v0
	s_nop 0
	v_cndmask_b32_e32 v77, v207, v77, vcc
	v_cmp_le_i32_e32 vcc, v194, v162
	v_add_u32_e32 v194, 0xb5, v0
	s_nop 0
	v_cndmask_b32_e32 v78, v207, v78, vcc
	v_cmp_le_i32_e32 vcc, v194, v162
	v_add_u32_e32 v194, 0xb6, v0
	s_nop 0
	v_cndmask_b32_e32 v79, v207, v79, vcc
	v_cmp_le_i32_e32 vcc, v194, v162
	v_add_u32_e32 v194, 0xb7, v0
	s_nop 0
	v_cndmask_b32_e32 v80, v207, v80, vcc
	v_cmp_le_i32_e32 vcc, v194, v162
	v_add_u32_e32 v194, 0xc0, v0
	s_nop 0
	v_cndmask_b32_e32 v81, v207, v81, vcc
	v_cmp_le_i32_e32 vcc, v194, v162
	v_add_u32_e32 v194, 0xc1, v0
	s_nop 0
	v_cndmask_b32_e32 v50, v207, v50, vcc
	v_cmp_le_i32_e32 vcc, v194, v162
	v_add_u32_e32 v194, 0xc2, v0
	s_nop 0
	v_cndmask_b32_e32 v51, v207, v51, vcc
	v_cmp_le_i32_e32 vcc, v194, v162
	v_add_u32_e32 v194, 0xc3, v0
	s_nop 0
	v_cndmask_b32_e32 v52, v207, v52, vcc
	v_cmp_le_i32_e32 vcc, v194, v162
	v_add_u32_e32 v194, 0xc4, v0
	s_nop 0
	v_cndmask_b32_e32 v53, v207, v53, vcc
	v_cmp_le_i32_e32 vcc, v194, v162
	v_add_u32_e32 v194, 0xc5, v0
	s_nop 0
	v_cndmask_b32_e32 v54, v207, v54, vcc
	v_cmp_le_i32_e32 vcc, v194, v162
	v_add_u32_e32 v194, 0xc6, v0
	s_nop 0
	v_cndmask_b32_e32 v55, v207, v55, vcc
	v_cmp_le_i32_e32 vcc, v194, v162
	v_add_u32_e32 v194, 0xc7, v0
	s_nop 0
	v_cndmask_b32_e32 v56, v207, v56, vcc
	v_cmp_le_i32_e32 vcc, v194, v162
	v_add_u32_e32 v194, 0xd0, v0
	s_nop 0
	v_cndmask_b32_e32 v57, v207, v57, vcc
	v_cmp_le_i32_e32 vcc, v194, v162
	v_add_u32_e32 v194, 0xd1, v0
	s_nop 0
	v_cndmask_b32_e32 v58, v207, v58, vcc
	v_cmp_le_i32_e32 vcc, v194, v162
	v_add_u32_e32 v194, 0xd2, v0
	s_nop 0
	v_cndmask_b32_e32 v59, v207, v59, vcc
	v_cmp_le_i32_e32 vcc, v194, v162
	v_add_u32_e32 v194, 0xd3, v0
	s_nop 0
	v_cndmask_b32_e32 v60, v207, v60, vcc
	v_cmp_le_i32_e32 vcc, v194, v162
	v_add_u32_e32 v194, 0xd4, v0
	s_nop 0
	v_cndmask_b32_e32 v61, v207, v61, vcc
	v_cmp_le_i32_e32 vcc, v194, v162
	v_add_u32_e32 v194, 0xd5, v0
	s_nop 0
	v_cndmask_b32_e32 v62, v207, v62, vcc
	v_cmp_le_i32_e32 vcc, v194, v162
	v_add_u32_e32 v194, 0xd6, v0
	s_nop 0
	v_cndmask_b32_e32 v63, v207, v63, vcc
	v_cmp_le_i32_e32 vcc, v194, v162
	v_add_u32_e32 v194, 0xd7, v0
	s_nop 0
	v_cndmask_b32_e32 v64, v207, v64, vcc
	v_cmp_le_i32_e32 vcc, v194, v162
	v_add_u32_e32 v194, 0xe0, v0
	s_nop 0
	v_cndmask_b32_e32 v65, v207, v65, vcc
	v_cmp_le_i32_e32 vcc, v194, v162
	v_add_u32_e32 v194, 0xe1, v0
	s_nop 0
	v_cndmask_b32_e32 v34, v207, v34, vcc
	v_cmp_le_i32_e32 vcc, v194, v162
	v_add_u32_e32 v194, 0xe2, v0
	s_nop 0
	v_cndmask_b32_e32 v35, v207, v35, vcc
	v_cmp_le_i32_e32 vcc, v194, v162
	v_add_u32_e32 v194, 0xe3, v0
	s_nop 0
	v_cndmask_b32_e32 v36, v207, v36, vcc
	v_cmp_le_i32_e32 vcc, v194, v162
	v_add_u32_e32 v194, 0xe4, v0
	s_nop 0
	v_cndmask_b32_e32 v37, v207, v37, vcc
	v_cmp_le_i32_e32 vcc, v194, v162
	v_add_u32_e32 v194, 0xe5, v0
	s_nop 0
	v_cndmask_b32_e32 v38, v207, v38, vcc
	v_cmp_le_i32_e32 vcc, v194, v162
	v_add_u32_e32 v194, 0xe6, v0
	s_nop 0
	v_cndmask_b32_e32 v39, v207, v39, vcc
	v_cmp_le_i32_e32 vcc, v194, v162
	v_add_u32_e32 v194, 0xe7, v0
	s_nop 0
	v_cndmask_b32_e32 v40, v207, v40, vcc
	v_cmp_le_i32_e32 vcc, v194, v162
	v_add_u32_e32 v194, 0xf0, v0
	s_nop 0
	v_cndmask_b32_e32 v41, v207, v41, vcc
	v_cmp_le_i32_e32 vcc, v194, v162
	v_add_u32_e32 v194, 0xf1, v0
	s_nop 0
	v_cndmask_b32_e32 v42, v207, v42, vcc
	v_cmp_le_i32_e32 vcc, v194, v162
	v_add_u32_e32 v194, 0xf2, v0
	s_nop 0
	v_cndmask_b32_e32 v43, v207, v43, vcc
	v_cmp_le_i32_e32 vcc, v194, v162
	v_add_u32_e32 v194, 0xf3, v0
	s_nop 0
	v_cndmask_b32_e32 v44, v207, v44, vcc
	v_cmp_le_i32_e32 vcc, v194, v162
	v_add_u32_e32 v194, 0xf4, v0
	s_nop 0
	v_cndmask_b32_e32 v45, v207, v45, vcc
	v_cmp_le_i32_e32 vcc, v194, v162
	v_add_u32_e32 v194, 0xf5, v0
	s_nop 0
	v_cndmask_b32_e32 v46, v207, v46, vcc
	v_cmp_le_i32_e32 vcc, v194, v162
	v_add_u32_e32 v194, 0xf6, v0
	v_add_u32_e32 v0, 0xf7, v0
	v_cndmask_b32_e32 v47, v207, v47, vcc
	v_cmp_le_i32_e32 vcc, v194, v162
	s_nop 1
	v_cndmask_b32_e32 v48, v207, v48, vcc
	v_cmp_le_i32_e32 vcc, v0, v162
	s_nop 1
	v_cndmask_b32_e32 v49, v207, v49, vcc

.LBB0_270:
	s_or_b64 exec, exec, s[40:41]
	v_add_u32_e32 v177, s53, v208
	v_cmp_le_i32_e32 vcc, v177, v157
	s_mov_b64 s[42:43], 0
	s_and_saveexec_b64 s[40:41], vcc
	s_cbranch_execz .LBB0_280
	v_add_u32_e32 v194, v191, v203
	v_add_u32_e32 v46, s47, v189
	ds_read_b128 v[220:223], v194 offset:39936
	ds_read_b128 v[82:85], v46
	ds_read_b128 v[86:89], v46 offset:16
	ds_read_b128 v[90:93], v46 offset:64
	ds_read_b128 v[94:97], v46 offset:80
	ds_read_b128 v[224:227], v194 offset:44544
	ds_read_b128 v[66:69], v46 offset:128
	ds_read_b128 v[70:73], v46 offset:144
	ds_read_b128 v[74:77], v46 offset:192
	ds_read_b128 v[78:81], v46 offset:208
	ds_read_b128 v[228:231], v194 offset:49152
	ds_read_b128 v[50:53], v46 offset:256
	ds_read_b128 v[54:57], v46 offset:272
	ds_read_b128 v[58:61], v46 offset:320
	ds_read_b128 v[62:65], v46 offset:336
	ds_read_b128 v[232:235], v194 offset:53760
	ds_read_b128 v[34:37], v46 offset:384
	ds_read_b128 v[38:41], v46 offset:400
	ds_read_b128 v[42:45], v46 offset:448
	ds_read_b128 v[46:49], v46 offset:464
	ds_read_b128 v[236:239], v194 offset:39968
	ds_read_b128 v[240:243], v194 offset:44576
	ds_read_b128 v[244:247], v194 offset:49184
	v_add_u32_e32 v177, 0x7f, v177
	v_cmp_gt_i32_e32 vcc, v177, v160
	s_waitcnt lgkmcnt(15)
	v_mfma_f32_32x32x16_bf16 v[82:97], v[220:223], v[98:101], v[82:97]
	ds_read_b128 v[220:223], v194 offset:53792
	s_waitcnt lgkmcnt(14)
	v_mfma_f32_32x32x16_bf16 v[66:81], v[224:227], v[98:101], v[66:81]
	ds_read_b128 v[224:227], v194 offset:40000
	s_waitcnt lgkmcnt(10)
	v_mfma_f32_32x32x16_bf16 v[50:65], v[228:231], v[98:101], v[50:65]
	ds_read_b128 v[228:231], v194 offset:44608
	s_waitcnt lgkmcnt(6)
	v_mfma_f32_32x32x16_bf16 v[34:49], v[232:235], v[98:101], v[34:49]
	ds_read_b128 v[232:235], v194 offset:49216
	s_waitcnt lgkmcnt(6)
	v_mfma_f32_32x32x16_bf16 v[82:97], v[236:239], v[102:105], v[82:97]
	ds_read_b128 v[236:239], v194 offset:53824
	s_waitcnt lgkmcnt(6)
	v_mfma_f32_32x32x16_bf16 v[66:81], v[240:243], v[102:105], v[66:81]
	ds_read_b128 v[240:243], v194 offset:40032
	s_waitcnt lgkmcnt(6)
	v_mfma_f32_32x32x16_bf16 v[50:65], v[244:247], v[102:105], v[50:65]
	ds_read_b128 v[244:247], v194 offset:44640
	s_waitcnt lgkmcnt(6)
	v_mfma_f32_32x32x16_bf16 v[34:49], v[220:223], v[102:105], v[34:49]
	ds_read_b128 v[220:223], v194 offset:49248
	s_waitcnt lgkmcnt(6)
	v_mfma_f32_32x32x16_bf16 v[82:97], v[224:227], v[106:109], v[82:97]
	ds_read_b128 v[224:227], v194 offset:53856
	s_waitcnt lgkmcnt(6)
	v_mfma_f32_32x32x16_bf16 v[66:81], v[228:231], v[106:109], v[66:81]
	s_waitcnt lgkmcnt(5)
	v_mfma_f32_32x32x16_bf16 v[50:65], v[232:235], v[106:109], v[50:65]
	s_waitcnt lgkmcnt(4)
	v_mfma_f32_32x32x16_bf16 v[34:49], v[236:239], v[106:109], v[34:49]
	s_waitcnt lgkmcnt(3)
	v_mfma_f32_32x32x16_bf16 v[82:97], v[240:243], v[110:113], v[82:97]
	s_waitcnt lgkmcnt(2)
	v_mfma_f32_32x32x16_bf16 v[66:81], v[244:247], v[110:113], v[66:81]
	s_waitcnt lgkmcnt(1)
	v_mfma_f32_32x32x16_bf16 v[50:65], v[220:223], v[110:113], v[50:65]
	s_waitcnt lgkmcnt(0)
	v_mfma_f32_32x32x16_bf16 v[34:49], v[224:227], v[110:113], v[34:49]
	s_and_saveexec_b64 s[42:43], vcc
	s_cbranch_execz .LBB0_273
	v_add_u32_e32 v177, s53, v155
	v_cmp_lt_i32_e32 vcc, v177, v162
	v_add_u32_e32 v194, 2, v177
	s_nop 0
	v_cndmask_b32_e32 v83, v207, v83, vcc
	v_cmp_le_i32_e32 vcc, v177, v162
	s_nop 1
	v_cndmask_b32_e32 v82, v207, v82, vcc
	v_cmp_le_i32_e32 vcc, v194, v162
	v_add_u32_e32 v194, 3, v177
	s_nop 0
	v_cndmask_b32_e32 v84, v207, v84, vcc
	v_cmp_le_i32_e32 vcc, v194, v162
	v_add_u32_e32 v194, 4, v177
	s_nop 0
	v_cndmask_b32_e32 v85, v207, v85, vcc
	v_cmp_le_i32_e32 vcc, v194, v162
	v_add_u32_e32 v194, 5, v177
	s_nop 0
	v_cndmask_b32_e32 v86, v207, v86, vcc
	v_cmp_le_i32_e32 vcc, v194, v162
	v_add_u32_e32 v194, 6, v177
	s_nop 0
	v_cndmask_b32_e32 v87, v207, v87, vcc
	v_cmp_le_i32_e32 vcc, v194, v162
	v_add_u32_e32 v194, 7, v177
	s_nop 0
	v_cndmask_b32_e32 v88, v207, v88, vcc
	v_cmp_le_i32_e32 vcc, v194, v162
	v_add_u32_e32 v194, 16, v177
	s_nop 0
	v_cndmask_b32_e32 v89, v207, v89, vcc
	v_cmp_le_i32_e32 vcc, v194, v162
	v_add_u32_e32 v194, 17, v177
	s_nop 0
	v_cndmask_b32_e32 v90, v207, v90, vcc
	v_cmp_le_i32_e32 vcc, v194, v162
	v_add_u32_e32 v194, 18, v177
	s_nop 0
	v_cndmask_b32_e32 v91, v207, v91, vcc
	v_cmp_le_i32_e32 vcc, v194, v162
	v_add_u32_e32 v194, 19, v177
	s_nop 0
	v_cndmask_b32_e32 v92, v207, v92, vcc
	v_cmp_le_i32_e32 vcc, v194, v162
	v_add_u32_e32 v194, 20, v177
	s_nop 0
	v_cndmask_b32_e32 v93, v207, v93, vcc
	v_cmp_le_i32_e32 vcc, v194, v162
	v_add_u32_e32 v194, 21, v177
	s_nop 0
	v_cndmask_b32_e32 v94, v207, v94, vcc
	v_cmp_le_i32_e32 vcc, v194, v162
	v_add_u32_e32 v194, 22, v177
	s_nop 0
	v_cndmask_b32_e32 v95, v207, v95, vcc
	v_cmp_le_i32_e32 vcc, v194, v162
	v_add_u32_e32 v194, 23, v177
	s_nop 0
	v_cndmask_b32_e32 v96, v207, v96, vcc
	v_cmp_le_i32_e32 vcc, v194, v162
	v_add_u32_e32 v194, 32, v177
	s_nop 0
	v_cndmask_b32_e32 v97, v207, v97, vcc
	v_cmp_le_i32_e32 vcc, v194, v162
	v_add_u32_e32 v194, 33, v177
	s_nop 0
	v_cndmask_b32_e32 v66, v207, v66, vcc
	v_cmp_le_i32_e32 vcc, v194, v162
	v_add_u32_e32 v194, 34, v177
	s_nop 0
	v_cndmask_b32_e32 v67, v207, v67, vcc
	v_cmp_le_i32_e32 vcc, v194, v162
	v_add_u32_e32 v194, 35, v177
	s_nop 0
	v_cndmask_b32_e32 v68, v207, v68, vcc
	v_cmp_le_i32_e32 vcc, v194, v162
	v_add_u32_e32 v194, 36, v177
	s_nop 0
	v_cndmask_b32_e32 v69, v207, v69, vcc
	v_cmp_le_i32_e32 vcc, v194, v162
	v_add_u32_e32 v194, 37, v177
	s_nop 0
	v_cndmask_b32_e32 v70, v207, v70, vcc
	v_cmp_le_i32_e32 vcc, v194, v162
	v_add_u32_e32 v194, 38, v177
	s_nop 0
	v_cndmask_b32_e32 v71, v207, v71, vcc
	v_cmp_le_i32_e32 vcc, v194, v162
	v_add_u32_e32 v194, 39, v177
	s_nop 0
	v_cndmask_b32_e32 v72, v207, v72, vcc
	v_cmp_le_i32_e32 vcc, v194, v162
	v_add_u32_e32 v194, 48, v177
	s_nop 0
	v_cndmask_b32_e32 v73, v207, v73, vcc
	v_cmp_le_i32_e32 vcc, v194, v162
	v_add_u32_e32 v194, 49, v177
	s_nop 0
	v_cndmask_b32_e32 v74, v207, v74, vcc
	v_cmp_le_i32_e32 vcc, v194, v162
	v_add_u32_e32 v194, 50, v177
	s_nop 0
	v_cndmask_b32_e32 v75, v207, v75, vcc
	v_cmp_le_i32_e32 vcc, v194, v162
	v_add_u32_e32 v194, 51, v177
	s_nop 0
	v_cndmask_b32_e32 v76, v207, v76, vcc
	v_cmp_le_i32_e32 vcc, v194, v162
	v_add_u32_e32 v194, 52, v177
	s_nop 0
	v_cndmask_b32_e32 v77, v207, v77, vcc
	v_cmp_le_i32_e32 vcc, v194, v162
	v_add_u32_e32 v194, 53, v177
	s_nop 0
	v_cndmask_b32_e32 v78, v207, v78, vcc
	v_cmp_le_i32_e32 vcc, v194, v162
	v_add_u32_e32 v194, 54, v177
	s_nop 0
	v_cndmask_b32_e32 v79, v207, v79, vcc
	v_cmp_le_i32_e32 vcc, v194, v162
	v_add_u32_e32 v194, 55, v177
	s_nop 0
	v_cndmask_b32_e32 v80, v207, v80, vcc
	v_cmp_le_i32_e32 vcc, v194, v162
	v_add_u32_e32 v194, 64, v177
	s_nop 0
	v_cndmask_b32_e32 v81, v207, v81, vcc
	v_cmp_le_i32_e32 vcc, v194, v162
	v_add_u32_e32 v194, 0x41, v177
	s_nop 0
	v_cndmask_b32_e32 v50, v207, v50, vcc
	v_cmp_le_i32_e32 vcc, v194, v162
	v_add_u32_e32 v194, 0x42, v177
	s_nop 0
	v_cndmask_b32_e32 v51, v207, v51, vcc
	v_cmp_le_i32_e32 vcc, v194, v162
	v_add_u32_e32 v194, 0x43, v177
	s_nop 0
	v_cndmask_b32_e32 v52, v207, v52, vcc
	v_cmp_le_i32_e32 vcc, v194, v162
	v_add_u32_e32 v194, 0x44, v177
	s_nop 0
	v_cndmask_b32_e32 v53, v207, v53, vcc
	v_cmp_le_i32_e32 vcc, v194, v162
	v_add_u32_e32 v194, 0x45, v177
	s_nop 0
	v_cndmask_b32_e32 v54, v207, v54, vcc
	v_cmp_le_i32_e32 vcc, v194, v162
	v_add_u32_e32 v194, 0x46, v177
	s_nop 0
	v_cndmask_b32_e32 v55, v207, v55, vcc
	v_cmp_le_i32_e32 vcc, v194, v162
	v_add_u32_e32 v194, 0x47, v177
	s_nop 0
	v_cndmask_b32_e32 v56, v207, v56, vcc
	v_cmp_le_i32_e32 vcc, v194, v162
	v_add_u32_e32 v194, 0x50, v177
	s_nop 0
	v_cndmask_b32_e32 v57, v207, v57, vcc
	v_cmp_le_i32_e32 vcc, v194, v162
	v_add_u32_e32 v194, 0x51, v177
	s_nop 0
	v_cndmask_b32_e32 v58, v207, v58, vcc
	v_cmp_le_i32_e32 vcc, v194, v162
	v_add_u32_e32 v194, 0x52, v177
	s_nop 0
	v_cndmask_b32_e32 v59, v207, v59, vcc
	v_cmp_le_i32_e32 vcc, v194, v162
	v_add_u32_e32 v194, 0x53, v177
	s_nop 0
	v_cndmask_b32_e32 v60, v207, v60, vcc
	v_cmp_le_i32_e32 vcc, v194, v162
	v_add_u32_e32 v194, 0x54, v177
	s_nop 0
	v_cndmask_b32_e32 v61, v207, v61, vcc
	v_cmp_le_i32_e32 vcc, v194, v162
	v_add_u32_e32 v194, 0x55, v177
	s_nop 0
	v_cndmask_b32_e32 v62, v207, v62, vcc
	v_cmp_le_i32_e32 vcc, v194, v162
	v_add_u32_e32 v194, 0x56, v177
	s_nop 0
	v_cndmask_b32_e32 v63, v207, v63, vcc
	v_cmp_le_i32_e32 vcc, v194, v162
	v_add_u32_e32 v194, 0x57, v177
	s_nop 0
	v_cndmask_b32_e32 v64, v207, v64, vcc
	v_cmp_le_i32_e32 vcc, v194, v162
	v_add_u32_e32 v194, 0x60, v177
	s_nop 0
	v_cndmask_b32_e32 v65, v207, v65, vcc
	v_cmp_le_i32_e32 vcc, v194, v162
	v_add_u32_e32 v194, 0x61, v177
	s_nop 0
	v_cndmask_b32_e32 v34, v207, v34, vcc
	v_cmp_le_i32_e32 vcc, v194, v162
	v_add_u32_e32 v194, 0x62, v177
	s_nop 0
	v_cndmask_b32_e32 v35, v207, v35, vcc
	v_cmp_le_i32_e32 vcc, v194, v162
	v_add_u32_e32 v194, 0x63, v177
	s_nop 0
	v_cndmask_b32_e32 v36, v207, v36, vcc
	v_cmp_le_i32_e32 vcc, v194, v162
	v_add_u32_e32 v194, 0x64, v177
	s_nop 0
	v_cndmask_b32_e32 v37, v207, v37, vcc
	v_cmp_le_i32_e32 vcc, v194, v162
	v_add_u32_e32 v194, 0x65, v177
	s_nop 0
	v_cndmask_b32_e32 v38, v207, v38, vcc
	v_cmp_le_i32_e32 vcc, v194, v162
	v_add_u32_e32 v194, 0x66, v177
	s_nop 0
	v_cndmask_b32_e32 v39, v207, v39, vcc
	v_cmp_le_i32_e32 vcc, v194, v162
	v_add_u32_e32 v194, 0x67, v177
	s_nop 0
	v_cndmask_b32_e32 v40, v207, v40, vcc
	v_cmp_le_i32_e32 vcc, v194, v162
	v_add_u32_e32 v194, 0x70, v177
	s_nop 0
	v_cndmask_b32_e32 v41, v207, v41, vcc
	v_cmp_le_i32_e32 vcc, v194, v162
	v_add_u32_e32 v194, 0x71, v177
	s_nop 0
	v_cndmask_b32_e32 v42, v207, v42, vcc
	v_cmp_le_i32_e32 vcc, v194, v162
	v_add_u32_e32 v194, 0x72, v177
	s_nop 0
	v_cndmask_b32_e32 v43, v207, v43, vcc
	v_cmp_le_i32_e32 vcc, v194, v162
	v_add_u32_e32 v194, 0x73, v177
	s_nop 0
	v_cndmask_b32_e32 v44, v207, v44, vcc
	v_cmp_le_i32_e32 vcc, v194, v162
	v_add_u32_e32 v194, 0x74, v177
	s_nop 0
	v_cndmask_b32_e32 v45, v207, v45, vcc
	v_cmp_le_i32_e32 vcc, v194, v162
	v_add_u32_e32 v194, 0x75, v177
	s_nop 0
	v_cndmask_b32_e32 v46, v207, v46, vcc
	v_cmp_le_i32_e32 vcc, v194, v162
	v_add_u32_e32 v194, 0x76, v177
	v_add_u32_e32 v177, 0x77, v177
	v_cndmask_b32_e32 v47, v207, v47, vcc
	v_cmp_le_i32_e32 vcc, v194, v162
	s_nop 1
	v_cndmask_b32_e32 v48, v207, v48, vcc
	v_cmp_le_i32_e32 vcc, v177, v162
	s_nop 1
	v_cndmask_b32_e32 v49, v207, v49, vcc

; DI_ float bf_lo(unsigned w) { return __uint_as_float(w << 16); }
; DI_ float bf_hi(unsigned w) { return __uint_as_float(w & 0xffff0000u); }
; template <int NS>
; DI_ void skinny_pass_bf16(const bf16_t* XBrows, int nrows, const float* WsT, float* sk_out, int gw, int NGW, int lane) {
;     for (int row = gw; row < nrows; row += 4 * NGW) {
;         float v[4][16];
; #pragma unroll
;         for (int r = 0; r < 4; ++r) { const int rr = row + r * NGW < nrows ? row + r * NGW : row; const u32x2* rp = (const u32x2*)(XBrows + (size_t)rr * D) + lane;
; #pragma unroll
;             for (int j = 0; j < 4; ++j) { const u32x2 w = rp[64 * j]; v[r][4 * j] = bf_lo(w.x); v[r][4 * j + 1] = bf_hi(w.x); v[r][4 * j + 2] = bf_lo(w.y); v[r][4 * j + 3] = bf_hi(w.y); } }
.LBB0_471:
	s_ashr_i32 s65, s64, 31
	s_lshl_b64 s[4:5], s[64:65], 7
	s_ashr_i32 s1, s0, 31
	v_lshl_add_u64 v[134:135], v[132:133], 0, s[4:5]
	s_lshl_b64 s[4:5], s[0:1], 7
	s_ashr_i32 s7, s6, 31
	v_lshl_add_u64 v[136:137], v[132:133], 0, s[4:5]
	s_lshl_b64 s[4:5], s[6:7], 7
	s_ashr_i32 s51, s50, 31
	v_lshl_add_u64 v[138:139], v[132:133], 0, s[4:5]
	s_lshl_b64 s[4:5], s[50:51], 7
	v_lshl_add_u64 v[140:141], v[132:133], 0, s[4:5]
	s_lshl_b64 s[4:5], s[64:65], 11
	s_waitcnt lgkmcnt(0)
	v_lshl_add_u64 v[0:1], v[130:131], 0, s[4:5]
	s_add_i32 s1, s64, s94
	s_cmpk_gt_i32 s1, 0x3fff
	s_cselect_b64 s[10:11], -1, 0
	s_and_b64 s[4:5], s[10:11], exec
	s_cselect_b32 s4, s64, s1
	s_ashr_i32 s5, s4, 31
	s_lshl_b64 s[4:5], s[4:5], 11
	v_lshl_add_u64 v[242:243], v[130:131], 0, s[4:5]
	s_add_i32 s1, s1, s94
	s_cmpk_gt_i32 s1, 0x3fff
	s_cselect_b64 s[40:41], -1, 0
	s_and_b64 s[4:5], s[40:41], exec
	s_cselect_b32 s4, s64, s1
	s_ashr_i32 s5, s4, 31
	s_lshl_b64 s[4:5], s[4:5], 11
	v_lshl_add_u64 v[244:245], v[130:131], 0, s[4:5]
	s_add_i32 s1, s1, s94
	s_cmpk_gt_i32 s1, 0x3fff
	s_cselect_b64 s[18:19], -1, 0
	s_and_b64 s[4:5], s[18:19], exec
	s_cselect_b32 s4, s64, s1
	s_ashr_i32 s5, s4, 31
	s_lshl_b64 s[4:5], s[4:5], 11
	v_lshl_add_u64 v[246:247], v[130:131], 0, s[4:5]
	s_nor_b64 s[64:65], s[44:45], s[10:11]
	s_nor_b64 s[96:97], s[44:45], s[40:41]
	s_nor_b64 s[40:41], s[44:45], s[18:19]
	s_mov_b64 s[10:11], 0
	v_mov_b32_e32 v236, v49
	global_load_dwordx2 v[150:151], v[0:1], off
	global_load_dwordx2 v[154:155], v[0:1], off offset:512
	global_load_dwordx2 v[158:159], v[0:1], off offset:1024
	global_load_dwordx2 v[162:163], v[0:1], off offset:1536
	global_load_dwordx2 v[166:167], v[242:243], off
	global_load_dwordx2 v[178:179], v[242:243], off offset:512
	global_load_dwordx2 v[182:183], v[242:243], off offset:1024
	global_load_dwordx2 v[188:189], v[242:243], off offset:1536
	global_load_dwordx2 v[206:207], v[244:245], off
	global_load_dwordx2 v[210:211], v[244:245], off offset:512
	global_load_dwordx2 v[214:215], v[244:245], off offset:1024
	global_load_dwordx2 v[218:219], v[244:245], off offset:1536
	global_load_dwordx2 v[222:223], v[246:247], off
	global_load_dwordx2 v[226:227], v[246:247], off offset:512
	global_load_dwordx2 v[230:231], v[246:247], off offset:1024
	global_load_dwordx2 v[234:235], v[246:247], off offset:1536
	s_waitcnt vmcnt(15)
	v_lshlrev_b32_e32 v148, 16, v150
	v_and_b32_e32 v149, 0xffff0000, v150
	v_lshlrev_b32_e32 v150, 16, v151
	v_and_b32_e32 v151, 0xffff0000, v151
	s_waitcnt vmcnt(14)
	v_lshlrev_b32_e32 v152, 16, v154
	v_and_b32_e32 v153, 0xffff0000, v154
	v_lshlrev_b32_e32 v154, 16, v155
	v_and_b32_e32 v155, 0xffff0000, v155
	s_waitcnt vmcnt(13)
	v_lshlrev_b32_e32 v156, 16, v158
	v_and_b32_e32 v157, 0xffff0000, v158
	v_lshlrev_b32_e32 v158, 16, v159
	v_and_b32_e32 v159, 0xffff0000, v159
	s_waitcnt vmcnt(12)
	v_lshlrev_b32_e32 v160, 16, v162
	v_and_b32_e32 v161, 0xffff0000, v162
	v_lshlrev_b32_e32 v162, 16, v163
	v_and_b32_e32 v163, 0xffff0000, v163
	s_waitcnt vmcnt(11)
	v_lshlrev_b32_e32 v164, 16, v166
	v_and_b32_e32 v165, 0xffff0000, v166
	v_lshlrev_b32_e32 v166, 16, v167
	v_and_b32_e32 v167, 0xffff0000, v167
	s_waitcnt vmcnt(10)
	v_lshlrev_b32_e32 v177, 16, v178
	v_and_b32_e32 v178, 0xffff0000, v178
	v_and_b32_e32 v180, 0xffff0000, v179
	v_lshlrev_b32_e32 v179, 16, v179
	s_waitcnt vmcnt(9)
	v_lshlrev_b32_e32 v181, 16, v182
	v_and_b32_e32 v182, 0xffff0000, v182
	v_and_b32_e32 v184, 0xffff0000, v183
	v_lshlrev_b32_e32 v183, 16, v183
	s_waitcnt vmcnt(8)
	v_lshlrev_b32_e32 v185, 16, v188
	v_and_b32_e32 v186, 0xffff0000, v188
	v_lshlrev_b32_e32 v188, 16, v189
	v_and_b32_e32 v189, 0xffff0000, v189
	s_waitcnt vmcnt(7)
	v_lshlrev_b32_e32 v190, 16, v206
	v_and_b32_e32 v191, 0xffff0000, v206
	v_lshlrev_b32_e32 v206, 16, v207
	v_and_b32_e32 v207, 0xffff0000, v207
	s_waitcnt vmcnt(6)
	v_lshlrev_b32_e32 v208, 16, v210
	v_and_b32_e32 v209, 0xffff0000, v210
	v_lshlrev_b32_e32 v210, 16, v211
	v_and_b32_e32 v211, 0xffff0000, v211
	s_waitcnt vmcnt(5)
	v_lshlrev_b32_e32 v212, 16, v214
	v_and_b32_e32 v213, 0xffff0000, v214
	v_lshlrev_b32_e32 v214, 16, v215
	v_and_b32_e32 v215, 0xffff0000, v215
	s_waitcnt vmcnt(4)
	v_lshlrev_b32_e32 v216, 16, v218
	v_and_b32_e32 v217, 0xffff0000, v218
	v_lshlrev_b32_e32 v218, 16, v219
	v_and_b32_e32 v219, 0xffff0000, v219
	s_waitcnt vmcnt(3)
	v_lshlrev_b32_e32 v220, 16, v222
	v_and_b32_e32 v221, 0xffff0000, v222
	v_lshlrev_b32_e32 v222, 16, v223
	v_and_b32_e32 v223, 0xffff0000, v223
	s_waitcnt vmcnt(2)
	v_lshlrev_b32_e32 v224, 16, v226
	v_and_b32_e32 v225, 0xffff0000, v226
	v_lshlrev_b32_e32 v226, 16, v227
	v_and_b32_e32 v227, 0xffff0000, v227
	s_waitcnt vmcnt(1)
	v_lshlrev_b32_e32 v228, 16, v230
	v_and_b32_e32 v229, 0xffff0000, v230
	v_lshlrev_b32_e32 v230, 16, v231
	v_and_b32_e32 v231, 0xffff0000, v231
	s_waitcnt vmcnt(0)
	v_lshlrev_b32_e32 v232, 16, v234
	v_and_b32_e32 v233, 0xffff0000, v234
	v_lshlrev_b32_e32 v234, 16, v235
	v_and_b32_e32 v235, 0xffff0000, v235
	s_branch .LBB0_473

; DI_ float silu_f(float v) { return v / (1.f + __expf(-v)); }
; DI_ void ssm_conv_tile(int tile, const unsigned char* buf, unsigned char* obuf, const float* cw, const float* cbias, bf16_t* xsT, bf16_t* Btok, bf16_t* BT, bf16_t* Ctok, int tid) {
;     const int ct = tile & 63, tt = tile >> 6, ch0 = ct * 64, tb = tt * 128;
;     const int ch = tid & 63, run = tid >> 6, tl0 = run * 16, chg = ch0 + ch;
;     const float w0 = cw[chg], w1 = cw[4096 + chg], w2 = cw[2 * 4096 + chg], w3 = cw[3 * 4096 + chg], bb = cbias[chg];
;     const bf16_t* col = (const bf16_t*)buf + ch;
;     float x0 = __uint_as_float((unsigned)col[(tl0 + 0) * 64] << 16), x1 = __uint_as_float((unsigned)col[(tl0 + 1) * 64] << 16), x2 = __uint_as_float((unsigned)col[(tl0 + 2) * 64] << 16);
;     float y[16];
; #pragma unroll
;     for (int i = 0; i < 16; ++i) { const float x3 = __uint_as_float((unsigned)col[(tl0 + 3 + i) * 64] << 16); const float v = bb + w0 * x0 + w1 * x1 + w2 * x2 + w3 * x3; y[i] = silu_f(v); x0 = x1; x1 = x2; x2 = x3; }
.LBB0_565:
	s_and_b32 s8, s26, 0xfc0
	v_or_b32_e32 v36, s8, v25
	v_lshlrev_b32_e32 v46, 2, v36
	v_mov_b32_e32 v47, v48
	v_lshl_add_u64 v[50:51], s[68:69], 0, v[46:47]
	v_add_co_u32_e32 v52, vcc, 0x4000, v50
	global_load_dword v36, v46, s[68:69]
	s_nop 0
	v_addc_co_u32_e32 v53, vcc, 0, v51, vcc
	global_load_dword v38, v[52:53], off
	v_add_co_u32_e32 v52, vcc, 0x8000, v50
	s_cmpk_lt_u32 s8, 0xc00
	s_nop 0
	v_addc_co_u32_e32 v53, vcc, 0, v51, vcc
	v_add_co_u32_e32 v50, vcc, 0xc000, v50
	global_load_dword v40, v[52:53], off
	s_nop 0
	v_addc_co_u32_e32 v51, vcc, 0, v51, vcc
	global_load_dword v42, v[50:51], off
	global_load_dword v44, v46, s[70:71]
	ds_read_u16 v37, v39 offset:1792
	ds_read_u16 v49, v39 offset:2048
	ds_read_u16 v47, v43
	s_cselect_b64 s[10:11], -1, 0
	s_cmpk_gt_u32 s8, 0xbff
	s_waitcnt lgkmcnt(2)
	v_lshlrev_b32_e32 v46, 16, v37
	s_waitcnt lgkmcnt(1)
	v_lshlrev_b32_e32 v51, 16, v49
	ds_read_u16 v37, v39 offset:2176
	ds_read_u16 v49, v39 offset:2304
	s_waitcnt lgkmcnt(2)
	v_lshlrev_b32_e32 v47, 16, v47
	v_mov_b32_e32 v50, v47
	v_mov_b32_e32 v54, v51
	s_waitcnt lgkmcnt(1)
	v_lshlrev_b32_e32 v55, 16, v37
	s_waitcnt lgkmcnt(0)
	v_lshlrev_b32_e32 v53, 16, v49
	ds_read_u16 v37, v39 offset:1536
	ds_read_u16 v49, v39 offset:1664
	s_waitcnt lgkmcnt(1)
	v_lshlrev_b32_e32 v58, 16, v37
	s_waitcnt lgkmcnt(0)
	v_lshlrev_b32_e32 v59, 16, v49
	s_waitcnt vmcnt(0)
	v_pk_fma_f32 v[56:57], v[36:37], v[58:59], v[44:45] op_sel_hi:[0,1,0]
	ds_read_u16 v37, v39 offset:1280
	ds_read_u16 v49, v39 offset:1408
	s_waitcnt lgkmcnt(1)
	v_lshlrev_b32_e32 v62, 16, v37
	s_waitcnt lgkmcnt(0)
	v_lshlrev_b32_e32 v63, 16, v49
	v_pk_fma_f32 v[60:61], v[36:37], v[62:63], v[44:45] op_sel_hi:[0,1,0]
	ds_read_u16 v37, v39 offset:1024
	ds_read_u16 v49, v39 offset:1152
	s_waitcnt lgkmcnt(1)
	v_lshlrev_b32_e32 v66, 16, v37
	s_waitcnt lgkmcnt(0)
	v_lshlrev_b32_e32 v67, 16, v49
	v_pk_fma_f32 v[64:65], v[36:37], v[66:67], v[44:45] op_sel_hi:[0,1,0]
	ds_read_u16 v37, v39 offset:768
	ds_read_u16 v49, v39 offset:896
	s_waitcnt lgkmcnt(1)
	v_lshlrev_b32_e32 v70, 16, v37
	s_waitcnt lgkmcnt(0)
	v_lshlrev_b32_e32 v71, 16, v49
	v_pk_fma_f32 v[68:69], v[36:37], v[70:71], v[44:45] op_sel_hi:[0,1,0]
	ds_read_u16 v37, v39 offset:512
	ds_read_u16 v49, v39 offset:640
	s_waitcnt lgkmcnt(1)
	v_lshlrev_b32_e32 v74, 16, v37
	s_waitcnt lgkmcnt(0)
	v_lshlrev_b32_e32 v75, 16, v49
	v_pk_fma_f32 v[72:73], v[36:37], v[74:75], v[44:45] op_sel_hi:[0,1,0]
	ds_read_u16 v37, v39 offset:256
	ds_read_u16 v49, v39 offset:384
	s_waitcnt lgkmcnt(1)
	v_lshlrev_b32_e32 v88, 16, v37
	s_waitcnt lgkmcnt(0)
	v_lshlrev_b32_e32 v89, 16, v49
	v_pk_fma_f32 v[76:77], v[36:37], v[88:89], v[44:45] op_sel_hi:[0,1,0]
	ds_read_u16 v37, v39
	ds_read_u16 v49, v39 offset:128
	v_pk_mov_b32 v[94:95], v[88:89], v[74:75] op_sel:[1,0]
	s_waitcnt lgkmcnt(1)
	v_lshlrev_b32_e32 v90, 16, v37
	s_waitcnt lgkmcnt(0)
; DI_ unsigned pk2(float lo, float hi) { typedef float f2 __attribute__((ext_vector_type(2))); typedef __bf16 b2 __attribute__((ext_vector_type(2))); f2 v = {lo, hi}; b2 b = __builtin_convertvector(v, b2); return __builtin_bit_cast(unsigned, b); }
; DI_ float silu_f(float v) { return v / (1.f + __expf(-v)); }
; DI_ void ssm_conv_tile(int tile, const unsigned char* buf, unsigned char* obuf, const float* cw, const float* cbias, bf16_t* xsT, bf16_t* Btok, bf16_t* BT, bf16_t* Ctok, int tid) {
;     ...
;     for (int i = 0; i < 16; ++i) { const float x3 = __uint_as_float((unsigned)col[(tl0 + 3 + i) * 64] << 16); const float v = bb + w0 * x0 + w1 * x1 + w2 * x2 + w3 * x3; y[i] = silu_f(v); x0 = x1; x1 = x2; x2 = x3; }
;     u32x4 o0, o1; o0.x = pk2(y[0], y[1]); o0.y = pk2(y[2], y[3]); o0.z = pk2(y[4], y[5]); o0.w = pk2(y[6], y[7]); o1.x = pk2(y[8], y[9]); o1.y = pk2(y[10], y[11]); o1.z = pk2(y[12], y[13]); o1.w = pk2(y[14], y[15]);
;     const int tg0 = tb + tl0;
;     unsigned char* obuf2 = obuf + 16384;
;     const bool chmaj = ch0 < 3072, tokmaj = ch0 >= 2048;
;     if (chmaj) { *(u32x4*)(obuf2 + ch * 272 + tl0 * 2) = o0; *(u32x4*)(obuf2 + ch * 272 + tl0 * 2 + 16) = o1; }
	v_lshlrev_b32_e32 v91, 16, v49
	v_pk_fma_f32 v[92:93], v[36:37], v[90:91], v[44:45] op_sel_hi:[0,1,0]
	v_pk_mov_b32 v[90:91], v[90:91], v[88:89] op_sel:[1,0]
	v_pk_fma_f32 v[76:77], v[38:39], v[94:95], v[76:77] op_sel_hi:[0,1,1]
	v_pk_fma_f32 v[90:91], v[38:39], v[90:91], v[92:93] op_sel_hi:[0,1,1]
	v_pk_fma_f32 v[88:89], v[40:41], v[88:89], v[90:91] op_sel_hi:[0,1,1]
	v_pk_fma_f32 v[88:89], v[42:43], v[94:95], v[88:89] op_sel_hi:[0,1,1]
	v_mul_f32_e32 v37, 0xbfb8aa3b, v88
	v_exp_f32_e32 v90, v37
	v_mul_f32_e32 v37, 0xbfb8aa3b, v89
	v_exp_f32_e32 v91, v37
	s_nop 0
	v_pk_add_f32 v[90:91], v[90:91], 1.0 op_sel_hi:[1,0]
	s_nop 0
	v_rcp_f32_e32 v49, v91
	s_nop 0
	v_mul_f32_e32 v87, v89, v49
	v_mov_b32_e32 v37, v87
	v_rcp_f32_e32 v52, v90
	v_mov_b32_e32 v37, v37
	v_mul_f32_e32 v89, v88, v52
	v_mov_b32_e32 v49, v89
	v_pk_mov_b32 v[88:89], v[74:75], v[70:71] op_sel:[1,0]
	v_pk_fma_f32 v[74:75], v[40:41], v[74:75], v[76:77] op_sel_hi:[0,1,1]
	v_pk_fma_f32 v[76:77], v[42:43], v[88:89], v[74:75] op_sel_hi:[0,1,1]
	v_mul_f32_e32 v52, 0xbfb8aa3b, v76
	v_exp_f32_e32 v74, v52
	v_mul_f32_e32 v52, 0xbfb8aa3b, v77
	v_exp_f32_e32 v75, v52
	v_pk_fma_f32 v[72:73], v[38:39], v[88:89], v[72:73] op_sel_hi:[0,1,1]
	v_pk_add_f32 v[90:91], v[74:75], 1.0 op_sel_hi:[1,0]
	s_nop 0
	v_rcp_f32_e32 v74, v91
	s_nop 0
	v_mul_f32_e32 v87, v77, v74
	v_mov_b32_e32 v74, v87
	v_rcp_f32_e32 v75, v90
	s_nop 0
	v_mul_f32_e32 v87, v76, v75
	v_mov_b32_e32 v75, v87
	v_pk_mov_b32 v[76:77], v[70:71], v[66:67] op_sel:[1,0]
	v_pk_fma_f32 v[70:71], v[40:41], v[70:71], v[72:73] op_sel_hi:[0,1,1]
	v_pk_fma_f32 v[72:73], v[42:43], v[76:77], v[70:71] op_sel_hi:[0,1,1]
	v_mul_f32_e32 v52, 0xbfb8aa3b, v72
	v_exp_f32_e32 v70, v52
	v_mul_f32_e32 v52, 0xbfb8aa3b, v73
	v_exp_f32_e32 v71, v52
	v_pk_fma_f32 v[68:69], v[38:39], v[76:77], v[68:69] op_sel_hi:[0,1,1]
	v_pk_add_f32 v[88:89], v[70:71], 1.0 op_sel_hi:[1,0]
	s_nop 0
	v_rcp_f32_e32 v70, v89
	s_nop 0
	v_mul_f32_e32 v87, v73, v70
	v_mov_b32_e32 v70, v87
	v_rcp_f32_e32 v71, v88
	s_nop 0
	v_mul_f32_e32 v87, v72, v71
	v_mov_b32_e32 v71, v87
	v_pk_mov_b32 v[72:73], v[66:67], v[62:63] op_sel:[1,0]
	v_pk_fma_f32 v[66:67], v[40:41], v[66:67], v[68:69] op_sel_hi:[0,1,1]
	v_pk_fma_f32 v[68:69], v[42:43], v[72:73], v[66:67] op_sel_hi:[0,1,1]
	v_mul_f32_e32 v52, 0xbfb8aa3b, v68
	v_exp_f32_e32 v66, v52
	v_mul_f32_e32 v52, 0xbfb8aa3b, v69
	v_exp_f32_e32 v67, v52
	v_pk_fma_f32 v[64:65], v[38:39], v[72:73], v[64:65] op_sel_hi:[0,1,1]
	v_pk_add_f32 v[76:77], v[66:67], 1.0 op_sel_hi:[1,0]
	s_nop 0
	v_rcp_f32_e32 v66, v77
	s_nop 0
	v_mul_f32_e32 v87, v69, v66
	v_mov_b32_e32 v66, v87
	v_rcp_f32_e32 v67, v76
	s_nop 0
	v_mul_f32_e32 v77, v68, v67
	v_mov_b32_e32 v67, v77
	v_pk_mov_b32 v[68:69], v[62:63], v[58:59] op_sel:[1,0]
	v_pk_fma_f32 v[62:63], v[40:41], v[62:63], v[64:65] op_sel_hi:[0,1,1]
	v_pk_fma_f32 v[64:65], v[42:43], v[68:69], v[62:63] op_sel_hi:[0,1,1]
	v_mul_f32_e32 v52, 0xbfb8aa3b, v64
	v_exp_f32_e32 v62, v52
	v_mul_f32_e32 v52, 0xbfb8aa3b, v65
	v_exp_f32_e32 v63, v52
	v_pk_fma_f32 v[60:61], v[38:39], v[68:69], v[60:61] op_sel_hi:[0,1,1]
	v_pk_add_f32 v[72:73], v[62:63], 1.0 op_sel_hi:[1,0]
	s_nop 0
	v_rcp_f32_e32 v62, v73
	s_nop 0
	v_mul_f32_e32 v76, v65, v62
	v_mov_b32_e32 v62, v76
	v_rcp_f32_e32 v63, v72
	s_nop 0
	v_mul_f32_e32 v73, v64, v63
	v_mov_b32_e32 v63, v73
	v_pk_mov_b32 v[64:65], v[58:59], v[46:47] op_sel:[1,0]
	v_pk_fma_f32 v[58:59], v[40:41], v[58:59], v[60:61] op_sel_hi:[0,1,1]
	v_pk_fma_f32 v[60:61], v[42:43], v[64:65], v[58:59] op_sel_hi:[0,1,1]
	v_mul_f32_e32 v52, 0xbfb8aa3b, v60
	v_exp_f32_e32 v58, v52
	v_mul_f32_e32 v52, 0xbfb8aa3b, v61
	v_exp_f32_e32 v59, v52
	v_pk_fma_f32 v[56:57], v[38:39], v[64:65], v[56:57] op_sel_hi:[0,1,1]
	v_pk_fma_f32 v[56:57], v[40:41], v[46:47], v[56:57] op_sel_hi:[0,1,1]
	v_pk_fma_f32 v[46:47], v[36:37], v[46:47], v[44:45] op_sel_hi:[0,1,0]
	v_pk_add_f32 v[68:69], v[58:59], 1.0 op_sel_hi:[1,0]
	v_pk_fma_f32 v[46:47], v[38:39], v[50:51], v[46:47] op_sel_hi:[0,1,1]
	v_rcp_f32_e32 v58, v69
	v_pk_fma_f32 v[46:47], v[40:41], v[54:55], v[46:47] op_sel_hi:[0,1,1]
	v_mul_f32_e32 v72, v61, v58
	v_mov_b32_e32 v58, v72
	v_rcp_f32_e32 v59, v68
	s_nop 0
	v_mul_f32_e32 v69, v60, v59
	v_mov_b32_e32 v59, v69
	v_pk_fma_f32 v[60:61], v[42:43], v[50:51], v[56:57] op_sel_hi:[0,1,1]
	v_mul_f32_e32 v52, 0xbfb8aa3b, v60
	v_exp_f32_e32 v56, v52
	v_mul_f32_e32 v52, 0xbfb8aa3b, v61
	v_exp_f32_e32 v57, v52
	s_nop 0
	v_pk_add_f32 v[64:65], v[56:57], 1.0 op_sel_hi:[1,0]
	s_nop 0
	v_rcp_f32_e32 v56, v65
	s_nop 0
	v_mul_f32_e32 v68, v61, v56
	v_mov_b32_e32 v56, v68
	v_rcp_f32_e32 v57, v64
	s_nop 0
	v_mul_f32_e32 v65, v60, v57
	v_mov_b32_e32 v57, v65
	v_mov_b32_e32 v52, v55
	v_pk_fma_f32 v[46:47], v[42:43], v[52:53], v[46:47] op_sel_hi:[0,1,1]
	v_mul_f32_e32 v36, 0xbfb8aa3b, v46
	v_exp_f32_e32 v50, v36
	v_mul_f32_e32 v36, 0xbfb8aa3b, v47
	v_exp_f32_e32 v51, v36
	s_nop 0
	v_pk_add_f32 v[50:51], v[50:51], 1.0 op_sel_hi:[1,0]
	s_nop 0
	v_rcp_f32_e32 v38, v51
	s_nop 0
	v_mul_f32_e32 v42, v47, v38
	v_mov_b32_e32 v36, v42
	v_rcp_f32_e32 v40, v50
	v_mov_b32_e32 v36, v36
	v_mul_f32_e32 v44, v46, v40
	v_mov_b32_e32 v38, v44
	s_cbranch_scc1 .LBB0_567
	v_cvt_pk_bf16_f32 v50, v49, v37
	v_cvt_pk_bf16_f32 v51, v75, v74
	v_cvt_pk_bf16_f32 v52, v71, v70
	v_cvt_pk_bf16_f32 v53, v67, v66
	v_add_u32_e32 v40, v45, v78
	v_cvt_pk_bf16_f32 v88, v63, v62
	v_cvt_pk_bf16_f32 v89, v59, v58
	v_cvt_pk_bf16_f32 v90, v57, v56
	v_cvt_pk_bf16_f32 v91, v38, v36
	ds_write_b128 v40, v[50:53] offset:49920
	ds_write_b128 v40, v[88:91] offset:49936

; DI_ float silu_f(float v) { return v / (1.f + __expf(-v)); }
; DI_ void ssm_conv_tile(int tile, const unsigned char* buf, unsigned char* obuf, const float* cw, const float* cbias, bf16_t* xsT, bf16_t* Btok, bf16_t* BT, bf16_t* Ctok, int tid) {
;     const int ct = tile & 63, tt = tile >> 6, ch0 = ct * 64, tb = tt * 128;
;     const int ch = tid & 63, run = tid >> 6, tl0 = run * 16, chg = ch0 + ch;
;     const float w0 = cw[chg], w1 = cw[4096 + chg], w2 = cw[2 * 4096 + chg], w3 = cw[3 * 4096 + chg], bb = cbias[chg];
;     const bf16_t* col = (const bf16_t*)buf + ch;
;     float x0 = __uint_as_float((unsigned)col[(tl0 + 0) * 64] << 16), x1 = __uint_as_float((unsigned)col[(tl0 + 1) * 64] << 16), x2 = __uint_as_float((unsigned)col[(tl0 + 2) * 64] << 16);
;     float y[16];
; #pragma unroll
;     for (int i = 0; i < 16; ++i) { const float x3 = __uint_as_float((unsigned)col[(tl0 + 3 + i) * 64] << 16); const float v = bb + w0 * x0 + w1 * x1 + w2 * x2 + w3 * x3; y[i] = silu_f(v); x0 = x1; x1 = x2; x2 = x3; }
.LBB0_588:
	v_readlane_b32 s4, v254, 11
	s_add_i32 s4, s4, s26
	s_and_b32 s8, s4, 0xfc0
	v_or_b32_e32 v36, s8, v25
	v_lshlrev_b32_e32 v46, 2, v36
	v_mov_b32_e32 v47, v48
	v_lshl_add_u64 v[50:51], s[68:69], 0, v[46:47]
	v_add_co_u32_e32 v52, vcc, 0x4000, v50
	global_load_dword v36, v46, s[68:69]
	s_nop 0
	v_addc_co_u32_e32 v53, vcc, 0, v51, vcc
	global_load_dword v38, v[52:53], off
	v_add_co_u32_e32 v52, vcc, 0x8000, v50
	s_cmpk_lt_u32 s8, 0xc00
	s_nop 0
	v_addc_co_u32_e32 v53, vcc, 0, v51, vcc
	v_add_co_u32_e32 v50, vcc, 0xc000, v50
	global_load_dword v40, v[52:53], off
	s_nop 0
	v_addc_co_u32_e32 v51, vcc, 0, v51, vcc
	global_load_dword v42, v[50:51], off
	global_load_dword v44, v46, s[70:71]
	ds_read_u16 v37, v39 offset:18560
	ds_read_u16 v46, v43 offset:16768
	s_cselect_b64 s[10:11], -1, 0
	s_cmpk_gt_u32 s8, 0xbff
	s_waitcnt lgkmcnt(0)
	v_lshlrev_b32_e32 v47, 16, v46
	v_lshlrev_b32_e32 v46, 16, v37
	ds_read_u16 v37, v39 offset:18816
	v_mov_b32_e32 v50, v47
	s_waitcnt lgkmcnt(0)
	v_lshlrev_b32_e32 v51, 16, v37
	ds_read_u16 v37, v39 offset:18944
	ds_read_u16 v49, v39 offset:19072
	v_mov_b32_e32 v54, v51
	s_waitcnt lgkmcnt(1)
	v_lshlrev_b32_e32 v55, 16, v37
	s_waitcnt lgkmcnt(0)
	v_lshlrev_b32_e32 v53, 16, v49
	ds_read_u16 v37, v39 offset:18304
	ds_read_u16 v49, v39 offset:18432
	s_waitcnt lgkmcnt(1)
	v_lshlrev_b32_e32 v58, 16, v37
	s_waitcnt lgkmcnt(0)
	v_lshlrev_b32_e32 v59, 16, v49
	s_waitcnt vmcnt(0)
	v_pk_fma_f32 v[56:57], v[36:37], v[58:59], v[44:45] op_sel_hi:[0,1,0]
	ds_read_u16 v37, v39 offset:18048
	ds_read_u16 v49, v39 offset:18176
	s_waitcnt lgkmcnt(1)
	v_lshlrev_b32_e32 v62, 16, v37
	s_waitcnt lgkmcnt(0)
	v_lshlrev_b32_e32 v63, 16, v49
	v_pk_fma_f32 v[60:61], v[36:37], v[62:63], v[44:45] op_sel_hi:[0,1,0]
	ds_read_u16 v37, v39 offset:17792
	ds_read_u16 v49, v39 offset:17920
	s_waitcnt lgkmcnt(1)
	v_lshlrev_b32_e32 v66, 16, v37
	s_waitcnt lgkmcnt(0)
	v_lshlrev_b32_e32 v67, 16, v49
	v_pk_fma_f32 v[64:65], v[36:37], v[66:67], v[44:45] op_sel_hi:[0,1,0]
	ds_read_u16 v37, v39 offset:17536
	ds_read_u16 v49, v39 offset:17664
	s_waitcnt lgkmcnt(1)
	v_lshlrev_b32_e32 v70, 16, v37
	s_waitcnt lgkmcnt(0)
	v_lshlrev_b32_e32 v71, 16, v49
	v_pk_fma_f32 v[68:69], v[36:37], v[70:71], v[44:45] op_sel_hi:[0,1,0]
	ds_read_u16 v37, v39 offset:17280
	ds_read_u16 v49, v39 offset:17408
	s_waitcnt lgkmcnt(1)
	v_lshlrev_b32_e32 v74, 16, v37
	s_waitcnt lgkmcnt(0)
	v_lshlrev_b32_e32 v75, 16, v49
	v_pk_fma_f32 v[72:73], v[36:37], v[74:75], v[44:45] op_sel_hi:[0,1,0]
	ds_read_u16 v37, v39 offset:17024
	ds_read_u16 v49, v39 offset:17152
	s_waitcnt lgkmcnt(1)
	v_lshlrev_b32_e32 v88, 16, v37
	s_waitcnt lgkmcnt(0)
	v_lshlrev_b32_e32 v89, 16, v49
	v_pk_fma_f32 v[76:77], v[36:37], v[88:89], v[44:45] op_sel_hi:[0,1,0]
	ds_read_u16 v37, v39 offset:16768
	ds_read_u16 v49, v39 offset:16896
	v_pk_mov_b32 v[94:95], v[88:89], v[74:75] op_sel:[1,0]
	s_waitcnt lgkmcnt(1)
	v_lshlrev_b32_e32 v90, 16, v37
	s_waitcnt lgkmcnt(0)
; DI_ unsigned pk2(float lo, float hi) { typedef float f2 __attribute__((ext_vector_type(2))); typedef __bf16 b2 __attribute__((ext_vector_type(2))); f2 v = {lo, hi}; b2 b = __builtin_convertvector(v, b2); return __builtin_bit_cast(unsigned, b); }
; DI_ float silu_f(float v) { return v / (1.f + __expf(-v)); }
; DI_ void ssm_conv_tile(int tile, const unsigned char* buf, unsigned char* obuf, const float* cw, const float* cbias, bf16_t* xsT, bf16_t* Btok, bf16_t* BT, bf16_t* Ctok, int tid) {
;     ...
;     for (int i = 0; i < 16; ++i) { const float x3 = __uint_as_float((unsigned)col[(tl0 + 3 + i) * 64] << 16); const float v = bb + w0 * x0 + w1 * x1 + w2 * x2 + w3 * x3; y[i] = silu_f(v); x0 = x1; x1 = x2; x2 = x3; }
;     u32x4 o0, o1; o0.x = pk2(y[0], y[1]); o0.y = pk2(y[2], y[3]); o0.z = pk2(y[4], y[5]); o0.w = pk2(y[6], y[7]); o1.x = pk2(y[8], y[9]); o1.y = pk2(y[10], y[11]); o1.z = pk2(y[12], y[13]); o1.w = pk2(y[14], y[15]);
;     const int tg0 = tb + tl0;
;     unsigned char* obuf2 = obuf + 16384;
;     const bool chmaj = ch0 < 3072, tokmaj = ch0 >= 2048;
;     if (chmaj) { *(u32x4*)(obuf2 + ch * 272 + tl0 * 2) = o0; *(u32x4*)(obuf2 + ch * 272 + tl0 * 2 + 16) = o1; }
	v_lshlrev_b32_e32 v91, 16, v49
	v_pk_fma_f32 v[92:93], v[36:37], v[90:91], v[44:45] op_sel_hi:[0,1,0]
	v_pk_mov_b32 v[90:91], v[90:91], v[88:89] op_sel:[1,0]
	v_pk_fma_f32 v[76:77], v[38:39], v[94:95], v[76:77] op_sel_hi:[0,1,1]
	v_pk_fma_f32 v[90:91], v[38:39], v[90:91], v[92:93] op_sel_hi:[0,1,1]
	v_pk_fma_f32 v[88:89], v[40:41], v[88:89], v[90:91] op_sel_hi:[0,1,1]
	v_pk_fma_f32 v[88:89], v[42:43], v[94:95], v[88:89] op_sel_hi:[0,1,1]
	v_mul_f32_e32 v37, 0xbfb8aa3b, v88
	v_exp_f32_e32 v90, v37
	v_mul_f32_e32 v37, 0xbfb8aa3b, v89
	v_exp_f32_e32 v91, v37
	s_nop 0
	v_pk_add_f32 v[90:91], v[90:91], 1.0 op_sel_hi:[1,0]
	s_nop 0
	v_rcp_f32_e32 v49, v91
	s_nop 0
	v_mul_f32_e32 v87, v89, v49
	v_mov_b32_e32 v37, v87
	v_rcp_f32_e32 v52, v90
	v_mov_b32_e32 v37, v37
	v_mul_f32_e32 v89, v88, v52
	v_mov_b32_e32 v49, v89
	v_pk_mov_b32 v[88:89], v[74:75], v[70:71] op_sel:[1,0]
	v_pk_fma_f32 v[74:75], v[40:41], v[74:75], v[76:77] op_sel_hi:[0,1,1]
	v_pk_fma_f32 v[76:77], v[42:43], v[88:89], v[74:75] op_sel_hi:[0,1,1]
	v_mul_f32_e32 v52, 0xbfb8aa3b, v76
	v_exp_f32_e32 v74, v52
	v_mul_f32_e32 v52, 0xbfb8aa3b, v77
	v_exp_f32_e32 v75, v52
	v_pk_fma_f32 v[72:73], v[38:39], v[88:89], v[72:73] op_sel_hi:[0,1,1]
	v_pk_add_f32 v[90:91], v[74:75], 1.0 op_sel_hi:[1,0]
	s_nop 0
	v_rcp_f32_e32 v74, v91
	s_nop 0
	v_mul_f32_e32 v87, v77, v74
	v_mov_b32_e32 v74, v87
	v_rcp_f32_e32 v75, v90
	s_nop 0
	v_mul_f32_e32 v87, v76, v75
	v_mov_b32_e32 v75, v87
	v_pk_mov_b32 v[76:77], v[70:71], v[66:67] op_sel:[1,0]
	v_pk_fma_f32 v[70:71], v[40:41], v[70:71], v[72:73] op_sel_hi:[0,1,1]
	v_pk_fma_f32 v[72:73], v[42:43], v[76:77], v[70:71] op_sel_hi:[0,1,1]
	v_mul_f32_e32 v52, 0xbfb8aa3b, v72
	v_exp_f32_e32 v70, v52
	v_mul_f32_e32 v52, 0xbfb8aa3b, v73
	v_exp_f32_e32 v71, v52
	v_pk_fma_f32 v[68:69], v[38:39], v[76:77], v[68:69] op_sel_hi:[0,1,1]
	v_pk_add_f32 v[88:89], v[70:71], 1.0 op_sel_hi:[1,0]
	s_nop 0
	v_rcp_f32_e32 v70, v89
	s_nop 0
	v_mul_f32_e32 v87, v73, v70
	v_mov_b32_e32 v70, v87
	v_rcp_f32_e32 v71, v88
	s_nop 0
	v_mul_f32_e32 v87, v72, v71
	v_mov_b32_e32 v71, v87
	v_pk_mov_b32 v[72:73], v[66:67], v[62:63] op_sel:[1,0]
	v_pk_fma_f32 v[66:67], v[40:41], v[66:67], v[68:69] op_sel_hi:[0,1,1]
	v_pk_fma_f32 v[68:69], v[42:43], v[72:73], v[66:67] op_sel_hi:[0,1,1]
	v_mul_f32_e32 v52, 0xbfb8aa3b, v68
	v_exp_f32_e32 v66, v52
	v_mul_f32_e32 v52, 0xbfb8aa3b, v69
	v_exp_f32_e32 v67, v52
	v_pk_fma_f32 v[64:65], v[38:39], v[72:73], v[64:65] op_sel_hi:[0,1,1]
	v_pk_add_f32 v[76:77], v[66:67], 1.0 op_sel_hi:[1,0]
	s_nop 0
	v_rcp_f32_e32 v66, v77
	s_nop 0
	v_mul_f32_e32 v87, v69, v66
	v_mov_b32_e32 v66, v87
	v_rcp_f32_e32 v67, v76
	s_nop 0
	v_mul_f32_e32 v77, v68, v67
	v_mov_b32_e32 v67, v77
	v_pk_mov_b32 v[68:69], v[62:63], v[58:59] op_sel:[1,0]
	v_pk_fma_f32 v[62:63], v[40:41], v[62:63], v[64:65] op_sel_hi:[0,1,1]
	v_pk_fma_f32 v[64:65], v[42:43], v[68:69], v[62:63] op_sel_hi:[0,1,1]
	v_mul_f32_e32 v52, 0xbfb8aa3b, v64
	v_exp_f32_e32 v62, v52
	v_mul_f32_e32 v52, 0xbfb8aa3b, v65
	v_exp_f32_e32 v63, v52
	v_pk_fma_f32 v[60:61], v[38:39], v[68:69], v[60:61] op_sel_hi:[0,1,1]
	v_pk_add_f32 v[72:73], v[62:63], 1.0 op_sel_hi:[1,0]
	s_nop 0
	v_rcp_f32_e32 v62, v73
	s_nop 0
	v_mul_f32_e32 v76, v65, v62
	v_mov_b32_e32 v62, v76
	v_rcp_f32_e32 v63, v72
	s_nop 0
	v_mul_f32_e32 v73, v64, v63
	v_mov_b32_e32 v63, v73
	v_pk_mov_b32 v[64:65], v[58:59], v[46:47] op_sel:[1,0]
	v_pk_fma_f32 v[58:59], v[40:41], v[58:59], v[60:61] op_sel_hi:[0,1,1]
	v_pk_fma_f32 v[60:61], v[42:43], v[64:65], v[58:59] op_sel_hi:[0,1,1]
	v_mul_f32_e32 v52, 0xbfb8aa3b, v60
	v_exp_f32_e32 v58, v52
	v_mul_f32_e32 v52, 0xbfb8aa3b, v61
	v_exp_f32_e32 v59, v52
	v_pk_fma_f32 v[56:57], v[38:39], v[64:65], v[56:57] op_sel_hi:[0,1,1]
	v_pk_fma_f32 v[56:57], v[40:41], v[46:47], v[56:57] op_sel_hi:[0,1,1]
	v_pk_fma_f32 v[46:47], v[36:37], v[46:47], v[44:45] op_sel_hi:[0,1,0]
	v_pk_add_f32 v[68:69], v[58:59], 1.0 op_sel_hi:[1,0]
	v_pk_fma_f32 v[46:47], v[38:39], v[50:51], v[46:47] op_sel_hi:[0,1,1]
	v_rcp_f32_e32 v58, v69
	v_pk_fma_f32 v[46:47], v[40:41], v[54:55], v[46:47] op_sel_hi:[0,1,1]
	v_mul_f32_e32 v72, v61, v58
	v_mov_b32_e32 v58, v72
	v_rcp_f32_e32 v59, v68
	s_nop 0
	v_mul_f32_e32 v69, v60, v59
	v_mov_b32_e32 v59, v69
	v_pk_fma_f32 v[60:61], v[42:43], v[50:51], v[56:57] op_sel_hi:[0,1,1]
	v_mul_f32_e32 v52, 0xbfb8aa3b, v60
	v_exp_f32_e32 v56, v52
	v_mul_f32_e32 v52, 0xbfb8aa3b, v61
	v_exp_f32_e32 v57, v52
	s_nop 0
	v_pk_add_f32 v[64:65], v[56:57], 1.0 op_sel_hi:[1,0]
	s_nop 0
	v_rcp_f32_e32 v56, v65
	s_nop 0
	v_mul_f32_e32 v68, v61, v56
	v_mov_b32_e32 v56, v68
	v_rcp_f32_e32 v57, v64
	s_nop 0
	v_mul_f32_e32 v65, v60, v57
	v_mov_b32_e32 v57, v65
	v_mov_b32_e32 v52, v55
	v_pk_fma_f32 v[46:47], v[42:43], v[52:53], v[46:47] op_sel_hi:[0,1,1]
	v_mul_f32_e32 v36, 0xbfb8aa3b, v46
	v_exp_f32_e32 v50, v36
	v_mul_f32_e32 v36, 0xbfb8aa3b, v47
	v_exp_f32_e32 v51, v36
	s_nop 0
	v_pk_add_f32 v[50:51], v[50:51], 1.0 op_sel_hi:[1,0]
	s_nop 0
	v_rcp_f32_e32 v38, v51
	s_nop 0
	v_mul_f32_e32 v42, v47, v38
	v_mov_b32_e32 v36, v42
	v_rcp_f32_e32 v40, v50
	v_mov_b32_e32 v36, v36
	v_mul_f32_e32 v44, v46, v40
	v_mov_b32_e32 v38, v44
	s_cbranch_scc1 .LBB0_590
	v_cvt_pk_bf16_f32 v50, v49, v37
	v_cvt_pk_bf16_f32 v51, v75, v74
	v_cvt_pk_bf16_f32 v52, v71, v70
	v_cvt_pk_bf16_f32 v53, v67, v66
	v_add_u32_e32 v40, v45, v78
	v_cvt_pk_bf16_f32 v88, v63, v62
	v_cvt_pk_bf16_f32 v89, v59, v58
	v_cvt_pk_bf16_f32 v90, v57, v56
	v_cvt_pk_bf16_f32 v91, v38, v36
	ds_write_b128 v40, v[50:53] offset:49920
	ds_write_b128 v40, v[88:91] offset:49936

; DI_ unsigned pk2(float lo, float hi) { typedef float f2 __attribute__((ext_vector_type(2))); typedef __bf16 b2 __attribute__((ext_vector_type(2))); f2 v = {lo, hi}; b2 b = __builtin_convertvector(v, b2); return __builtin_bit_cast(unsigned, b); }
; DI_ void ssd_passC(const bf16_t* xsT, const bf16_t* Btok, const bf16_t* Ctok, const bf16_t* Sc, const float* dt, const float* acum, const float* Dskip, const float* norm_w, bf16_t* Z, unsigned char* lds, int tid, int lane, int wid) {
;     ...
; #pragma unroll
;         for (int it = 0; it < 2; ++it) {
;             const int tb = it ? 3 - (wid & 3) : (wid & 3), hl = 2 * (wid >> 2) + it, hh = g * 4 + hl, tl = 32 * tb + r32, tg = t0 + tl;
;             const float tot = (ex[tl] + ex[128 + tl]) + (ex[256 + tl] + ex[384 + tl]);
;             const float rstd = 1.f / sqrtf(tot * (1.f / 256.f) + RMS_EPS);
; #pragma unroll
;             for (int pb = 0; pb < 2; ++pb)
; #pragma unroll
;                 for (int q4 = 0; q4 < 4; ++q4) {
;                     const int chn = hh * 64 + 32 * pb + 8 * q4 + 4 * hi;
;                     const f32x4 nw = *(const f32x4*)(norm_w + chn);
;                     u32x2 w; w.x = pk2(yv[it][pb][4 * q4] * rstd * nw[0], yv[it][pb][4 * q4 + 1] * rstd * nw[1]); w.y = pk2(yv[it][pb][4 * q4 + 2] * rstd * nw[2], yv[it][pb][4 * q4 + 3] * rstd * nw[3]);
;                     *(u32x2*)(Z + (size_t)tg * DI + chn) = w;
;                 }
;         }
.LBB0_763:
	s_or_b64 exec, exec, s[0:1]
	s_waitcnt lgkmcnt(0)
	s_barrier
	ds_read2st64_b32 v[34:35], v144 offset1:2
	ds_read2st64_b32 v[36:37], v144 offset0:4 offset1:6
	s_add_i32 s20, s20, s92
	s_cmpk_lt_i32 s20, 0x400
	s_waitcnt lgkmcnt(1)
	v_mov_b32_e32 v38, v34
	s_waitcnt lgkmcnt(0)
	v_mov_b32_e32 v39, v36
	v_mov_b32_e32 v36, v35
	v_pk_add_f32 v[34:35], v[38:39], v[36:37]
	s_nop 0
	v_add_f32_e32 v34, v34, v35
	v_fmamk_f32 v34, v34, 0x3b800000, v203
	v_cmp_gt_f32_e32 vcc, s17, v34
	v_mul_f32_e32 v35, 0x4f800000, v34
	s_nop 0
	v_cndmask_b32_e32 v34, v34, v35, vcc
	v_sqrt_f32_e32 v35, v34
	s_nop 0
	v_add_u32_e32 v36, -1, v35
	v_fma_f32 v37, -v36, v35, v34
	v_cmp_ge_f32_e64 s[0:1], 0, v37
	v_add_u32_e32 v37, 1, v35
	s_nop 0
	v_cndmask_b32_e64 v36, v35, v36, s[0:1]
	v_fma_f32 v35, -v37, v35, v34
	v_cmp_lt_f32_e64 s[0:1], 0, v35
	s_nop 1
	v_cndmask_b32_e64 v35, v36, v37, s[0:1]
	v_mul_f32_e32 v36, 0x37800000, v35
	v_cndmask_b32_e32 v35, v35, v36, vcc
	v_cmp_class_f32_e32 vcc, v34, v204
	s_nop 1
	v_cndmask_b32_e32 v34, v35, v34, vcc
	v_div_scale_f32 v35, s[0:1], v34, v34, 1.0
	v_rcp_f32_e32 v36, v35
	s_nop 0
	v_fma_f32 v37, -v35, v36, 1.0
	v_fmac_f32_e32 v36, v37, v36
	v_div_scale_f32 v37, vcc, 1.0, v34, 1.0
	v_mul_f32_e32 v38, v37, v36
	v_fma_f32 v39, -v35, v38, v37
	v_fmac_f32_e32 v38, v39, v36
	v_fma_f32 v35, -v35, v38, v37
	v_div_fmas_f32 v35, v35, v36, v38
	v_div_fixup_f32 v38, v35, v34, 1.0
	v_lshlrev_b64 v[34:35], 12, v[102:103]
	v_lshl_add_u64 v[40:41], s[56:57], 0, v[34:35]
	v_lshl_add_u64 v[34:35], v[96:97], 2, s[78:79]
	global_load_dwordx4 v[206:209], v[34:35], off
	global_load_dwordx4 v[210:213], v[34:35], off offset:32
	global_load_dwordx4 v[214:217], v[34:35], off offset:64
	global_load_dwordx4 v[218:221], v[34:35], off offset:96
	global_load_dwordx4 v[222:225], v[34:35], off offset:128
	global_load_dwordx4 v[226:229], v[34:35], off offset:160
	global_load_dwordx4 v[230:233], v[34:35], off offset:192
	global_load_dwordx4 v[234:237], v[34:35], off offset:224
	v_pk_mul_f32 v[36:37], v[98:99], v[38:39] op_sel_hi:[1,0]
	v_pk_mul_f32 v[46:47], v[104:105], v[38:39] op_sel_hi:[1,0]
	s_waitcnt vmcnt(7)
	v_mov_b32_e32 v42, v206
	v_mov_b32_e32 v43, v207
	v_mov_b32_e32 v44, v208
	v_mov_b32_e32 v45, v209
	v_pk_mul_f32 v[36:37], v[42:43], v[36:37]
	s_nop 0
	v_cvt_pk_bf16_f32 v42, v36, v37
	v_pk_mul_f32 v[36:37], v[100:101], v[38:39] op_sel_hi:[1,0]
	s_nop 0
	v_pk_mul_f32 v[36:37], v[44:45], v[36:37]
	s_nop 0
	v_cvt_pk_bf16_f32 v43, v36, v37
	v_lshlrev_b64 v[36:37], 1, v[96:97]
	v_lshl_add_u64 v[40:41], v[40:41], 0, v[36:37]
	global_store_dwordx2 v[40:41], v[42:43], off
	v_lshl_add_u64 v[32:33], v[32:33], 0, v[36:37]
	s_waitcnt vmcnt(7)
	v_mov_b32_e32 v42, v210
	v_mov_b32_e32 v43, v211
	v_mov_b32_e32 v44, v212
	v_mov_b32_e32 v45, v213
	v_pk_mul_f32 v[42:43], v[42:43], v[46:47]
	v_pk_mul_f32 v[46:47], v[106:107], v[38:39] op_sel_hi:[1,0]
	v_cvt_pk_bf16_f32 v42, v42, v43
	v_pk_mul_f32 v[44:45], v[44:45], v[46:47]
	v_pk_mul_f32 v[46:47], v[108:109], v[38:39] op_sel_hi:[1,0]
	v_cvt_pk_bf16_f32 v43, v44, v45
	global_store_dwordx2 v[40:41], v[42:43], off offset:16
	s_waitcnt vmcnt(7)
	v_mov_b32_e32 v42, v214
	v_mov_b32_e32 v43, v215
	v_mov_b32_e32 v44, v216
	v_mov_b32_e32 v45, v217
	v_pk_mul_f32 v[42:43], v[42:43], v[46:47]
	v_pk_mul_f32 v[46:47], v[110:111], v[38:39] op_sel_hi:[1,0]
	v_cvt_pk_bf16_f32 v42, v42, v43
	v_pk_mul_f32 v[44:45], v[44:45], v[46:47]
	v_pk_mul_f32 v[46:47], v[112:113], v[38:39] op_sel_hi:[1,0]
	v_cvt_pk_bf16_f32 v43, v44, v45
	global_store_dwordx2 v[40:41], v[42:43], off offset:32
	s_waitcnt vmcnt(7)
	v_mov_b32_e32 v42, v218
	v_mov_b32_e32 v43, v219
	v_mov_b32_e32 v44, v220
	v_mov_b32_e32 v45, v221
	v_pk_mul_f32 v[42:43], v[46:47], v[42:43]
	v_pk_mul_f32 v[46:47], v[114:115], v[38:39] op_sel_hi:[1,0]
	v_cvt_pk_bf16_f32 v42, v42, v43
	v_pk_mul_f32 v[44:45], v[46:47], v[44:45]
	v_pk_mul_f32 v[46:47], v[116:117], v[38:39] op_sel_hi:[1,0]
	v_cvt_pk_bf16_f32 v43, v44, v45
	global_store_dwordx2 v[40:41], v[42:43], off offset:48
	s_waitcnt vmcnt(7)
	v_mov_b32_e32 v42, v222
	v_mov_b32_e32 v43, v223
	v_mov_b32_e32 v44, v224
	v_mov_b32_e32 v45, v225
	v_pk_mul_f32 v[42:43], v[46:47], v[42:43]
	v_pk_mul_f32 v[46:47], v[118:119], v[38:39] op_sel_hi:[1,0]
	v_cvt_pk_bf16_f32 v42, v42, v43
	v_pk_mul_f32 v[44:45], v[46:47], v[44:45]
	v_pk_mul_f32 v[46:47], v[120:121], v[38:39] op_sel_hi:[1,0]
	v_cvt_pk_bf16_f32 v43, v44, v45
	global_store_dwordx2 v[40:41], v[42:43], off offset:64
	s_waitcnt vmcnt(7)
	v_mov_b32_e32 v42, v226
	v_mov_b32_e32 v43, v227
	v_mov_b32_e32 v44, v228
	v_mov_b32_e32 v45, v229
	v_pk_mul_f32 v[42:43], v[46:47], v[42:43]
	v_pk_mul_f32 v[46:47], v[122:123], v[38:39] op_sel_hi:[1,0]
	v_cvt_pk_bf16_f32 v42, v42, v43
	v_pk_mul_f32 v[44:45], v[46:47], v[44:45]
	v_pk_mul_f32 v[46:47], v[124:125], v[38:39] op_sel_hi:[1,0]
	v_cvt_pk_bf16_f32 v43, v44, v45
	global_store_dwordx2 v[40:41], v[42:43], off offset:80
	s_waitcnt vmcnt(7)
	v_mov_b32_e32 v42, v230
	v_mov_b32_e32 v43, v231
	v_mov_b32_e32 v44, v232
	v_mov_b32_e32 v45, v233
	v_pk_mul_f32 v[42:43], v[46:47], v[42:43]
	v_pk_mul_f32 v[46:47], v[126:127], v[38:39] op_sel_hi:[1,0]
	v_cvt_pk_bf16_f32 v42, v42, v43
	v_pk_mul_f32 v[44:45], v[46:47], v[44:45]
	v_pk_mul_f32 v[46:47], v[128:129], v[38:39] op_sel_hi:[1,0]
	v_cvt_pk_bf16_f32 v43, v44, v45
	global_store_dwordx2 v[40:41], v[42:43], off offset:96
	v_pk_mul_f32 v[38:39], v[130:131], v[38:39] op_sel_hi:[1,0]
	s_waitcnt vmcnt(7)
; DI_ unsigned pk2(float lo, float hi) { typedef float f2 __attribute__((ext_vector_type(2))); typedef __bf16 b2 __attribute__((ext_vector_type(2))); f2 v = {lo, hi}; b2 b = __builtin_convertvector(v, b2); return __builtin_bit_cast(unsigned, b); }
; DI_ void ssd_passC(const bf16_t* xsT, const bf16_t* Btok, const bf16_t* Ctok, const bf16_t* Sc, const float* dt, const float* acum, const float* Dskip, const float* norm_w, bf16_t* Z, unsigned char* lds, int tid, int lane, int wid) {
;     ...
; #pragma unroll
;         for (int it = 0; it < 2; ++it) {
;             const int tb = it ? 3 - (wid & 3) : (wid & 3), hl = 2 * (wid >> 2) + it, hh = g * 4 + hl, tl = 32 * tb + r32, tg = t0 + tl;
;             const float tot = (ex[tl] + ex[128 + tl]) + (ex[256 + tl] + ex[384 + tl]);
;             const float rstd = 1.f / sqrtf(tot * (1.f / 256.f) + RMS_EPS);
; #pragma unroll
;             for (int pb = 0; pb < 2; ++pb)
; #pragma unroll
;                 for (int q4 = 0; q4 < 4; ++q4) {
;                     const int chn = hh * 64 + 32 * pb + 8 * q4 + 4 * hi;
;                     const f32x4 nw = *(const f32x4*)(norm_w + chn);
;                     u32x2 w; w.x = pk2(yv[it][pb][4 * q4] * rstd * nw[0], yv[it][pb][4 * q4 + 1] * rstd * nw[1]); w.y = pk2(yv[it][pb][4 * q4 + 2] * rstd * nw[2], yv[it][pb][4 * q4 + 3] * rstd * nw[3]);
;                     *(u32x2*)(Z + (size_t)tg * DI + chn) = w;
;                 }
;         }
	v_mov_b32_e32 v42, v234
	v_mov_b32_e32 v43, v235
	v_mov_b32_e32 v44, v236
	v_mov_b32_e32 v45, v237
	v_pk_mul_f32 v[42:43], v[46:47], v[42:43]
	v_pk_mul_f32 v[38:39], v[38:39], v[44:45]
	v_cvt_pk_bf16_f32 v42, v42, v43
	v_cvt_pk_bf16_f32 v43, v38, v39
	global_store_dwordx2 v[40:41], v[42:43], off offset:112
	global_load_dwordx4 v[206:209], v[34:35], off offset:256
	global_load_dwordx4 v[210:213], v[34:35], off offset:288
	global_load_dwordx4 v[214:217], v[34:35], off offset:320
	global_load_dwordx4 v[218:221], v[34:35], off offset:352
	global_load_dwordx4 v[222:225], v[34:35], off offset:384
	global_load_dwordx4 v[226:229], v[34:35], off offset:416
	global_load_dwordx4 v[230:233], v[34:35], off offset:448
	global_load_dwordx4 v[234:237], v[34:35], off offset:480
	ds_read2st64_b32 v[38:39], v145 offset1:2
	ds_read2st64_b32 v[40:41], v145 offset0:4 offset1:6
	s_waitcnt lgkmcnt(1)
	v_mov_b32_e32 v42, v38
	s_waitcnt lgkmcnt(0)
	v_mov_b32_e32 v43, v40
	v_mov_b32_e32 v40, v39
	v_pk_add_f32 v[38:39], v[42:43], v[40:41]
	s_nop 0
	v_add_f32_e32 v38, v38, v39
	v_fmamk_f32 v38, v38, 0x3b800000, v203
	v_cmp_gt_f32_e32 vcc, s17, v38
	v_mul_f32_e32 v39, 0x4f800000, v38
	s_nop 0
	v_cndmask_b32_e32 v38, v38, v39, vcc
	v_sqrt_f32_e32 v39, v38
	s_nop 0
	v_add_u32_e32 v40, -1, v39
	v_fma_f32 v41, -v40, v39, v38
	v_cmp_ge_f32_e64 s[0:1], 0, v41
	v_add_u32_e32 v41, 1, v39
	s_nop 0
	v_cndmask_b32_e64 v40, v39, v40, s[0:1]
	v_fma_f32 v39, -v41, v39, v38
	v_cmp_lt_f32_e64 s[0:1], 0, v39
	s_nop 1
	v_cndmask_b32_e64 v39, v40, v41, s[0:1]
	v_mul_f32_e32 v40, 0x37800000, v39
	v_cndmask_b32_e32 v39, v39, v40, vcc
	v_cmp_class_f32_e32 vcc, v38, v204
	s_nop 1
	v_cndmask_b32_e32 v38, v39, v38, vcc
	v_div_scale_f32 v39, s[0:1], v38, v38, 1.0
	v_rcp_f32_e32 v40, v39
	s_nop 0
	v_fma_f32 v41, -v39, v40, 1.0
	v_fmac_f32_e32 v40, v41, v40
	v_div_scale_f32 v41, vcc, 1.0, v38, 1.0
	v_mul_f32_e32 v42, v41, v40
	v_fma_f32 v43, -v39, v42, v41
	v_fmac_f32_e32 v42, v43, v40
	v_fma_f32 v39, -v39, v42, v41
	v_div_fmas_f32 v39, v39, v40, v42
	v_div_fixup_f32 v38, v39, v38, 1.0
	v_pk_mul_f32 v[16:17], v[16:17], v[38:39] op_sel_hi:[1,0]
	v_pk_mul_f32 v[18:19], v[18:19], v[38:39] op_sel_hi:[1,0]
	v_pk_mul_f32 v[20:21], v[20:21], v[38:39] op_sel_hi:[1,0]
	v_pk_mul_f32 v[0:1], v[0:1], v[38:39] op_sel_hi:[1,0]
	v_pk_mul_f32 v[2:3], v[2:3], v[38:39] op_sel_hi:[1,0]
	v_pk_mul_f32 v[4:5], v[4:5], v[38:39] op_sel_hi:[1,0]
	s_waitcnt vmcnt(7)
	v_mov_b32_e32 v40, v206
	v_mov_b32_e32 v41, v207
	v_mov_b32_e32 v42, v208
	v_mov_b32_e32 v43, v209
	v_pk_mul_f32 v[16:17], v[40:41], v[16:17]
	v_pk_mul_f32 v[18:19], v[42:43], v[18:19]
	v_cvt_pk_bf16_f32 v16, v16, v17
	v_cvt_pk_bf16_f32 v17, v18, v19
	global_store_dwordx2 v[32:33], v[16:17], off offset:128
	s_waitcnt vmcnt(7)
	v_mov_b32_e32 v16, v210
	v_mov_b32_e32 v17, v211
	v_mov_b32_e32 v18, v212
	v_mov_b32_e32 v19, v213
	v_pk_mul_f32 v[16:17], v[16:17], v[20:21]
	v_pk_mul_f32 v[20:21], v[22:23], v[38:39] op_sel_hi:[1,0]
	v_cvt_pk_bf16_f32 v16, v16, v17
	v_pk_mul_f32 v[18:19], v[18:19], v[20:21]
	v_pk_mul_f32 v[20:21], v[24:25], v[38:39] op_sel_hi:[1,0]
	v_cvt_pk_bf16_f32 v17, v18, v19
	global_store_dwordx2 v[32:33], v[16:17], off offset:144
	s_waitcnt vmcnt(7)
	v_mov_b32_e32 v16, v214
	v_mov_b32_e32 v17, v215
	v_mov_b32_e32 v18, v216
	v_mov_b32_e32 v19, v217
	v_pk_mul_f32 v[16:17], v[16:17], v[20:21]
	v_pk_mul_f32 v[20:21], v[26:27], v[38:39] op_sel_hi:[1,0]
	v_cvt_pk_bf16_f32 v16, v16, v17
	v_pk_mul_f32 v[18:19], v[18:19], v[20:21]
	v_pk_mul_f32 v[20:21], v[28:29], v[38:39] op_sel_hi:[1,0]
	v_cvt_pk_bf16_f32 v17, v18, v19
	global_store_dwordx2 v[32:33], v[16:17], off offset:160
	s_waitcnt vmcnt(7)
	v_mov_b32_e32 v16, v218
	v_mov_b32_e32 v17, v219
	v_mov_b32_e32 v18, v220
	v_mov_b32_e32 v19, v221
	v_pk_mul_f32 v[16:17], v[20:21], v[16:17]
	v_pk_mul_f32 v[20:21], v[30:31], v[38:39] op_sel_hi:[1,0]
	v_cvt_pk_bf16_f32 v16, v16, v17
	v_pk_mul_f32 v[18:19], v[20:21], v[18:19]
	s_nop 0
	v_cvt_pk_bf16_f32 v17, v18, v19
	global_store_dwordx2 v[32:33], v[16:17], off offset:176
	s_waitcnt vmcnt(7)
	v_mov_b32_e32 v16, v222
	v_mov_b32_e32 v17, v223
	v_mov_b32_e32 v18, v224
	v_mov_b32_e32 v19, v225
	v_pk_mul_f32 v[0:1], v[0:1], v[16:17]
	v_pk_mul_f32 v[2:3], v[2:3], v[18:19]
	v_cvt_pk_bf16_f32 v0, v0, v1
	v_cvt_pk_bf16_f32 v1, v2, v3
	global_store_dwordx2 v[32:33], v[0:1], off offset:192
	s_waitcnt vmcnt(7)
	v_mov_b32_e32 v0, v226
	v_mov_b32_e32 v1, v227
	v_mov_b32_e32 v2, v228
	v_mov_b32_e32 v3, v229
	v_pk_mul_f32 v[0:1], v[4:5], v[0:1]
	v_pk_mul_f32 v[4:5], v[6:7], v[38:39] op_sel_hi:[1,0]
	v_cvt_pk_bf16_f32 v0, v0, v1
	v_pk_mul_f32 v[2:3], v[4:5], v[2:3]
	v_pk_mul_f32 v[4:5], v[8:9], v[38:39] op_sel_hi:[1,0]
	v_cvt_pk_bf16_f32 v1, v2, v3
	global_store_dwordx2 v[32:33], v[0:1], off offset:208
	s_waitcnt vmcnt(7)
	v_mov_b32_e32 v0, v230
	v_mov_b32_e32 v1, v231
	v_mov_b32_e32 v2, v232
	v_mov_b32_e32 v3, v233
	v_pk_mul_f32 v[0:1], v[4:5], v[0:1]
	v_pk_mul_f32 v[4:5], v[10:11], v[38:39] op_sel_hi:[1,0]
	v_cvt_pk_bf16_f32 v0, v0, v1
	v_pk_mul_f32 v[2:3], v[4:5], v[2:3]
	v_pk_mul_f32 v[4:5], v[12:13], v[38:39] op_sel_hi:[1,0]
	v_cvt_pk_bf16_f32 v1, v2, v3
	global_store_dwordx2 v[32:33], v[0:1], off offset:224
	s_waitcnt vmcnt(7)
	v_mov_b32_e32 v0, v234
	v_mov_b32_e32 v1, v235
	v_mov_b32_e32 v2, v236
	v_mov_b32_e32 v3, v237
	v_pk_mul_f32 v[0:1], v[4:5], v[0:1]
	v_pk_mul_f32 v[4:5], v[14:15], v[38:39] op_sel_hi:[1,0]
	v_cvt_pk_bf16_f32 v0, v0, v1
	v_pk_mul_f32 v[2:3], v[4:5], v[2:3]
	s_nop 0
	v_cvt_pk_bf16_f32 v1, v2, v3
	global_store_dwordx2 v[32:33], v[0:1], off offset:240
	s_barrier
	s_cbranch_scc0 .LBB0_772

; DI_ bf16x8 pack8(float a0, float a1, float a2, float a3, float a4, float a5, float a6, float a7) { u32x4 p; p.x = pk2(a0, a1); p.y = pk2(a2, a3); p.z = pk2(a4, a5); p.w = pk2(a6, a7); return __builtin_bit_cast(bf16x8, p); }
; #define MFMA32(a, b, c) __builtin_amdgcn_mfma_f32_32x32x16_bf16((a), (b), (c), 0, 0, 0)
; DI_ int kvmap(int rho) { return (rho & 0x13) | ((rho & 4) << 1) | ((rho & 8) >> 1); }
; DI_ void ssd_passC(const bf16_t* xsT, const bf16_t* Btok, const bf16_t* Ctok, const bf16_t* Sc, const float* dt, const float* acum, const float* Dskip, const float* norm_w, bf16_t* Z, unsigned char* lds, int tid, int lane, int wid) {
;     ...
;             for (int sb = 0; sb <= tb; ++sb) {
;                 f32x16 cb;
; #pragma unroll
;                 for (int i = 0; i < 16; ++i) cb[i] = 0.f;
;                 const unsigned char* bp = lds + PC_B + (32 * sb + kvmap(r32)) * PC_RS + hi * 16;
; #pragma unroll
;                 for (int ks = 0; ks < 8; ++ks) cb = MFMA32(*(const bf16x8*)(bp + 32 * ks), *(const bf16x8*)(cfp + 32 * ks), cb);
;                 float m[16];
; #pragma unroll
;                 for (int q4 = 0; q4 < 4; ++q4) {
;                     const int sl0 = 32 * sb + 16 * (q4 >> 1) + 8 * hi + 4 * (q4 & 1);
;                     const f32x4 as4 = *(const f32x4*)(sa + hl * 128 + sl0), ds4 = *(const f32x4*)(sd + hl * 128 + sl0);
; #pragma unroll
;                     for (int e = 0; e < 4; ++e) { const int sl = sl0 + e; float v = cb[4 * q4 + e] * __expf(fminf(at - as4[e], 0.f)) * ds4[e]; v = (sl <= tl) ? v : 0.f; if (sl == tl) v += Dh; m[4 * q4 + e] = v; }
;                 }
;                 const bf16x8 pf0 = pack8(m[0], m[1], m[2], m[3], m[4], m[5], m[6], m[7]), pf1 = pack8(m[8], m[9], m[10], m[11], m[12], m[13], m[14], m[15]);
; #pragma unroll
;                 for (int pb = 0; pb < 2; ++pb) {
;                     const unsigned char* xp = lds + PC_X + (hl * 64 + 32 * pb + r32) * PC_RS + (32 * sb + 8 * hi) * 2;
;                     yv[it][pb] = MFMA32(*(const bf16x8*)xp, pf0, yv[it][pb]); yv[it][pb] = MFMA32(*(const bf16x8*)(xp + 32), pf1, yv[it][pb]);
;                 }
;             }
.LBB0_765:
	v_add_u32_e32 v106, 0, v99
	ds_read_b128 v[32:35], v106
	ds_read_b128 v[102:105], v106 offset:32
	v_add_u32_e32 v111, 0, v100
	v_add_u32_e32 v110, s7, v137
	v_cmp_gt_u32_e32 vcc, v90, v110
	s_waitcnt lgkmcnt(1)
	v_mfma_f32_32x32x16_bf16 v[32:47], v[32:35], v[50:53], 0
	v_cmp_le_u32_e64 s[0:1], v110, v90
	v_add_u32_e32 v112, 4, v110
	s_add_i32 s7, s7, 32
	v_add_u32_e32 v100, 0x80, v100
	v_add_u32_e32 v99, 0x2200, v99
	s_cmp_lg_u32 s18, s7
	s_waitcnt lgkmcnt(0)
	v_mfma_f32_32x32x16_bf16 v[32:47], v[102:105], v[54:57], v[32:47]
	ds_read_b128 v[102:105], v106 offset:64
	s_waitcnt lgkmcnt(0)
	v_mfma_f32_32x32x16_bf16 v[32:47], v[102:105], v[58:61], v[32:47]
	ds_read_b128 v[102:105], v106 offset:96
	s_waitcnt lgkmcnt(0)
	v_mfma_f32_32x32x16_bf16 v[32:47], v[102:105], v[62:65], v[32:47]
	ds_read_b128 v[102:105], v106 offset:128
	s_waitcnt lgkmcnt(0)
	v_mfma_f32_32x32x16_bf16 v[32:47], v[102:105], v[66:69], v[32:47]
	ds_read_b128 v[102:105], v106 offset:160
	s_waitcnt lgkmcnt(0)
	v_mfma_f32_32x32x16_bf16 v[32:47], v[102:105], v[70:73], v[32:47]
	ds_read_b128 v[102:105], v106 offset:192
	s_waitcnt lgkmcnt(0)
	v_mfma_f32_32x32x16_bf16 v[32:47], v[102:105], v[74:77], v[32:47]
	ds_read_b128 v[102:105], v106 offset:224
	v_add_u32_e32 v106, 0x22800, v111
	ds_read_b128 v[106:109], v106
	s_waitcnt lgkmcnt(1)
	v_mfma_f32_32x32x16_bf16 v[32:47], v[102:105], v[78:81], v[32:47]
	v_add_u32_e32 v102, 0x22000, v111
	ds_read_b128 v[102:105], v102
	s_waitcnt lgkmcnt(0)
	v_sub_f32_e32 v102, v98, v102
	v_sub_f32_e32 v103, v98, v103
	v_min_f32_e32 v102, 0, v102
	v_min_f32_e32 v103, 0, v103
	v_mul_f32_e32 v102, 0x3fb8aa3b, v102
	v_mul_f32_e32 v103, 0x3fb8aa3b, v103
	v_exp_f32_e32 v102, v102
	v_exp_f32_e32 v103, v103
	s_nop 0
	v_mul_f32_e32 v32, v32, v102
	v_mul_f32_e32 v33, v33, v103
	v_mul_f32_e32 v32, v106, v32
	v_mul_f32_e32 v103, v107, v33
	v_add_u32_e32 v102, 1, v110
	v_cndmask_b32_e64 v33, 0, v32, s[0:1]
	v_cndmask_b32_e32 v32, 0, v103, vcc
	v_cmp_eq_u32_e32 vcc, v110, v90
	v_cmp_eq_u32_e64 s[0:1], v102, v49
	v_pk_add_f32 v[102:103], v[96:97], v[32:33]
	s_nop 0
	v_cndmask_b32_e64 v106, v32, v102, s[0:1]
	v_cndmask_b32_e32 v107, v33, v103, vcc
	v_sub_f32_e32 v32, v98, v104
	v_sub_f32_e32 v33, v98, v105
	v_min_f32_e32 v32, 0, v32
	v_min_f32_e32 v33, 0, v33
	v_mul_f32_e32 v32, 0x3fb8aa3b, v32
	v_mul_f32_e32 v33, 0x3fb8aa3b, v33
	v_exp_f32_e32 v32, v32
	v_exp_f32_e32 v33, v33
	v_or_b32_e32 v102, 3, v110
	v_or_b32_e32 v103, 2, v110
	v_cmp_le_u32_e32 vcc, v102, v49
	v_pk_mul_f32 v[32:33], v[34:35], v[32:33]
	v_cmp_eq_u32_e64 s[0:1], v102, v49
	v_pk_mul_f32 v[32:33], v[108:109], v[32:33]
	v_add_u32_e32 v102, 0x22810, v111
	v_cndmask_b32_e32 v33, 0, v33, vcc
	v_cmp_le_u32_e32 vcc, v103, v90
	s_nop 1
	v_cndmask_b32_e32 v32, 0, v32, vcc
	v_cmp_eq_u32_e32 vcc, v103, v90
	v_pk_add_f32 v[34:35], v[96:97], v[32:33]
	ds_read_b128 v[102:105], v102
	v_cndmask_b32_e32 v109, v32, v34, vcc
	v_add_u32_e32 v32, 0x22010, v111
	v_cndmask_b32_e64 v108, v33, v35, s[0:1]
	ds_read_b128 v[32:35], v32
	v_cmp_gt_u32_e32 vcc, v90, v112
	v_cmp_le_u32_e64 s[0:1], v112, v90
	s_waitcnt lgkmcnt(0)
	v_sub_f32_e32 v32, v98, v32
	v_sub_f32_e32 v33, v98, v33
	v_min_f32_e32 v32, 0, v32
	v_min_f32_e32 v33, 0, v33
	v_mul_f32_e32 v32, 0x3fb8aa3b, v32
	v_mul_f32_e32 v33, 0x3fb8aa3b, v33
	v_exp_f32_e32 v32, v32
	v_exp_f32_e32 v33, v33
	v_mul_f32_e32 v32, v36, v32
	v_mul_f32_e32 v33, v37, v33
	v_mul_f32_e32 v32, v102, v32
	v_mul_f32_e32 v37, v103, v33
	v_add_u32_e32 v36, 5, v110
	v_cndmask_b32_e64 v33, 0, v32, s[0:1]
	v_cndmask_b32_e32 v32, 0, v37, vcc
	v_cmp_eq_u32_e32 vcc, v112, v90
	v_cmp_eq_u32_e64 s[0:1], v36, v49
	v_pk_add_f32 v[36:37], v[96:97], v[32:33]
	s_nop 0
	v_cndmask_b32_e64 v102, v32, v36, s[0:1]
	v_cndmask_b32_e32 v103, v33, v37, vcc
	v_sub_f32_e32 v32, v98, v34
	v_sub_f32_e32 v33, v98, v35
	v_min_f32_e32 v32, 0, v32
	v_min_f32_e32 v33, 0, v33
	v_mul_f32_e32 v32, 0x3fb8aa3b, v32
	v_mul_f32_e32 v33, 0x3fb8aa3b, v33
	v_exp_f32_e32 v32, v32
	v_exp_f32_e32 v33, v33
	v_or_b32_e32 v34, 3, v112
	v_or_b32_e32 v35, 2, v112
	v_cmp_le_u32_e32 vcc, v34, v49
	v_pk_mul_f32 v[32:33], v[38:39], v[32:33]
	v_cmp_eq_u32_e64 s[0:1], v34, v49
	v_pk_mul_f32 v[32:33], v[104:105], v[32:33]
	v_add_u32_e32 v36, 0x22840, v111
	v_cndmask_b32_e32 v33, 0, v33, vcc
	v_cmp_le_u32_e32 vcc, v35, v90
	ds_read_b128 v[36:39], v36
	v_add_u32_e32 v112, 16, v110
	v_cndmask_b32_e32 v32, 0, v32, vcc
	v_cmp_eq_u32_e32 vcc, v35, v90
	v_pk_add_f32 v[34:35], v[96:97], v[32:33]
	s_nop 0
	v_cndmask_b32_e32 v105, v32, v34, vcc
	v_add_u32_e32 v32, 0x22040, v111
	v_cndmask_b32_e64 v104, v33, v35, s[0:1]
	ds_read_b128 v[32:35], v32
	v_cmp_gt_u32_e32 vcc, v90, v112
	v_cmp_le_u32_e64 s[0:1], v112, v90
	s_waitcnt lgkmcnt(0)
	v_sub_f32_e32 v32, v98, v32
	v_sub_f32_e32 v33, v98, v33
	v_min_f32_e32 v32, 0, v32
	v_min_f32_e32 v33, 0, v33
	v_mul_f32_e32 v32, 0x3fb8aa3b, v32
	v_mul_f32_e32 v33, 0x3fb8aa3b, v33
	v_exp_f32_e32 v32, v32
	v_exp_f32_e32 v33, v33
	v_mul_f32_e32 v32, v40, v32
	v_mul_f32_e32 v33, v41, v33
	v_mul_f32_e32 v32, v36, v32
	v_mul_f32_e32 v37, v37, v33
	v_add_u32_e32 v36, 17, v110
	v_cndmask_b32_e64 v33, 0, v32, s[0:1]
	v_cndmask_b32_e32 v32, 0, v37, vcc
	v_cmp_eq_u32_e32 vcc, v112, v90
	v_cmp_eq_u32_e64 s[0:1], v36, v49
	v_pk_add_f32 v[36:37], v[96:97], v[32:33]
	s_nop 0
	v_cndmask_b32_e64 v40, v32, v36, s[0:1]
	v_cndmask_b32_e32 v41, v33, v37, vcc
	v_sub_f32_e32 v32, v98, v34
	v_sub_f32_e32 v33, v98, v35
	v_min_f32_e32 v32, 0, v32
	v_min_f32_e32 v33, 0, v33
	v_mul_f32_e32 v32, 0x3fb8aa3b, v32
	v_mul_f32_e32 v33, 0x3fb8aa3b, v33
	v_exp_f32_e32 v32, v32
	v_exp_f32_e32 v33, v33
	v_or_b32_e32 v34, 3, v112
	v_or_b32_e32 v35, 2, v112
	v_cmp_le_u32_e32 vcc, v34, v49
	v_pk_mul_f32 v[32:33], v[42:43], v[32:33]
	v_cmp_eq_u32_e64 s[0:1], v34, v49
	v_pk_mul_f32 v[32:33], v[38:39], v[32:33]
	v_add_u32_e32 v36, 0x22850, v111
	v_cndmask_b32_e32 v33, 0, v33, vcc
	v_cmp_le_u32_e32 vcc, v35, v90
	ds_read_b128 v[36:39], v36
	v_add_u32_e32 v112, 20, v110
	v_cndmask_b32_e32 v32, 0, v32, vcc
	v_cmp_eq_u32_e32 vcc, v35, v90
	v_pk_add_f32 v[34:35], v[96:97], v[32:33]
	s_nop 0
	v_cndmask_b32_e32 v43, v32, v34, vcc
	v_add_u32_e32 v32, 0x22050, v111
	v_cndmask_b32_e64 v42, v33, v35, s[0:1]
	ds_read_b128 v[32:35], v32
	v_cmp_gt_u32_e32 vcc, v90, v112
	v_cmp_le_u32_e64 s[0:1], v112, v90
	s_waitcnt lgkmcnt(0)
; DI_ float bf_lo(unsigned w) { return __uint_as_float(w << 16); }
; DI_ float bf_hi(unsigned w) { return __uint_as_float(w & 0xffff0000u); }
; DI_ bf16x8 pack8(float a0, float a1, float a2, float a3, float a4, float a5, float a6, float a7) { u32x4 p; p.x = pk2(a0, a1); p.y = pk2(a2, a3); p.z = pk2(a4, a5); p.w = pk2(a6, a7); return __builtin_bit_cast(bf16x8, p); }
; #define MFMA32(a, b, c) __builtin_amdgcn_mfma_f32_32x32x16_bf16((a), (b), (c), 0, 0, 0)
; DI_ float silu_f(float v) { return v / (1.f + __expf(-v)); }
; DI_ void ssd_passC(const bf16_t* xsT, const bf16_t* Btok, const bf16_t* Ctok, const bf16_t* Sc, const float* dt, const float* acum, const float* Dskip, const float* norm_w, bf16_t* Z, unsigned char* lds, int tid, int lane, int wid) {
;     ...
;                     for (int e = 0; e < 4; ++e) { const int sl = sl0 + e; float v = cb[4 * q4 + e] * __expf(fminf(at - as4[e], 0.f)) * ds4[e]; v = (sl <= tl) ? v : 0.f; if (sl == tl) v += Dh; m[4 * q4 + e] = v; }
;                 }
;                 const bf16x8 pf0 = pack8(m[0], m[1], m[2], m[3], m[4], m[5], m[6], m[7]), pf1 = pack8(m[8], m[9], m[10], m[11], m[12], m[13], m[14], m[15]);
; #pragma unroll
;                 for (int pb = 0; pb < 2; ++pb) {
;                     const unsigned char* xp = lds + PC_X + (hl * 64 + 32 * pb + r32) * PC_RS + (32 * sb + 8 * hi) * 2;
;                     yv[it][pb] = MFMA32(*(const bf16x8*)xp, pf0, yv[it][pb]); yv[it][pb] = MFMA32(*(const bf16x8*)(xp + 32), pf1, yv[it][pb]);
;                 }
;             }
;             const int tg = t0 + tl; float sq = 0.f;
; #pragma unroll
;             for (int pb = 0; pb < 2; ++pb)
; #pragma unroll
;                 for (int q4 = 0; q4 < 4; ++q4) {
;                     const int chn = hh * 64 + 32 * pb + 8 * q4 + 4 * hi;
;                     const u32x2 zw = *(const u32x2*)(Z + (size_t)tg * DI + chn);
;                     const float a0 = yv[it][pb][4 * q4] * silu_f(bf_lo(zw.x)), a1 = yv[it][pb][4 * q4 + 1] * silu_f(bf_hi(zw.x)), a2 = yv[it][pb][4 * q4 + 2] * silu_f(bf_lo(zw.y)), a3 = yv[it][pb][4 * q4 + 3] * silu_f(bf_hi(zw.y));
;                     sq += (a0 * a0 + a1 * a1) + (a2 * a2 + a3 * a3);
;                     yv[it][pb][4 * q4] = a0; yv[it][pb][4 * q4 + 1] = a1; yv[it][pb][4 * q4 + 2] = a2; yv[it][pb][4 * q4 + 3] = a3;
;                 }
	v_sub_f32_e32 v32, v98, v32
	v_sub_f32_e32 v33, v98, v33
	v_min_f32_e32 v32, 0, v32
	v_min_f32_e32 v33, 0, v33
	v_mul_f32_e32 v32, 0x3fb8aa3b, v32
	v_mul_f32_e32 v33, 0x3fb8aa3b, v33
	v_exp_f32_e32 v32, v32
	v_exp_f32_e32 v33, v33
	v_mul_f32_e32 v32, v44, v32
	v_mul_f32_e32 v33, v45, v33
	v_mul_f32_e32 v32, v36, v32
	v_mul_f32_e32 v37, v37, v33
	v_add_u32_e32 v36, 21, v110
	v_cndmask_b32_e64 v33, 0, v32, s[0:1]
	v_cndmask_b32_e32 v32, 0, v37, vcc
	v_cmp_eq_u32_e32 vcc, v112, v90
	v_cmp_eq_u32_e64 s[0:1], v36, v49
	v_pk_add_f32 v[36:37], v[96:97], v[32:33]
	s_nop 0
	v_cndmask_b32_e64 v44, v32, v36, s[0:1]
	v_cndmask_b32_e32 v45, v33, v37, vcc
	v_sub_f32_e32 v32, v98, v34
	v_sub_f32_e32 v33, v98, v35
	v_min_f32_e32 v32, 0, v32
	v_min_f32_e32 v33, 0, v33
	v_mul_f32_e32 v32, 0x3fb8aa3b, v32
	v_mul_f32_e32 v33, 0x3fb8aa3b, v33
	v_exp_f32_e32 v32, v32
	v_exp_f32_e32 v33, v33
	v_or_b32_e32 v34, 3, v112
	v_or_b32_e32 v35, 2, v112
	v_cmp_le_u32_e32 vcc, v34, v49
	v_pk_mul_f32 v[32:33], v[46:47], v[32:33]
	v_cmp_eq_u32_e64 s[0:1], v34, v49
	v_pk_mul_f32 v[32:33], v[38:39], v[32:33]
	v_cvt_pk_bf16_f32 v36, v107, v106
	v_cndmask_b32_e32 v33, 0, v33, vcc
	v_cmp_le_u32_e32 vcc, v35, v90
	v_cvt_pk_bf16_f32 v37, v109, v108
	v_cvt_pk_bf16_f32 v38, v103, v102
	v_cndmask_b32_e32 v32, 0, v32, vcc
	v_cmp_eq_u32_e32 vcc, v35, v90
	v_pk_add_f32 v[34:35], v[96:97], v[32:33]
	v_cvt_pk_bf16_f32 v39, v105, v104
	v_cndmask_b32_e32 v46, v32, v34, vcc
	v_cvt_pk_bf16_f32 v34, v45, v44
	v_add_u32_e32 v44, 0, v101
	v_cvt_pk_bf16_f32 v32, v41, v40
	v_add_u32_e32 v40, 0x11000, v44
	v_cndmask_b32_e64 v35, v33, v35, s[0:1]
	v_cvt_pk_bf16_f32 v33, v43, v42
	ds_read_b128 v[40:43], v40
	s_waitcnt lgkmcnt(0)
	v_mfma_f32_32x32x16_bf16 v[16:31], v[40:43], v[36:39], v[16:31]
	v_add_u32_e32 v40, 0x11020, v44
	ds_read_b128 v[40:43], v40
	v_cvt_pk_bf16_f32 v35, v46, v35
	v_add_u32_e32 v101, 64, v101
	s_waitcnt lgkmcnt(0)
	v_mfma_f32_32x32x16_bf16 v[16:31], v[40:43], v[32:35], v[16:31]
	v_add_u32_e32 v40, 0x13200, v44
	ds_read_b128 v[40:43], v40
	s_waitcnt lgkmcnt(0)
	v_mfma_f32_32x32x16_bf16 v[0:15], v[40:43], v[36:39], v[0:15]
	v_add_u32_e32 v36, 0x13220, v44
	ds_read_b128 v[36:39], v36
	s_waitcnt lgkmcnt(0)
	v_mfma_f32_32x32x16_bf16 v[0:15], v[36:39], v[32:35], v[0:15]
	s_cbranch_scc1 .LBB0_765
	v_or_b32_e32 v102, s42, v90
	v_ashrrev_i32_e32 v103, 31, v102
	v_lshl_or_b32 v96, s6, 6, v138
	v_lshlrev_b64 v[32:33], 12, v[102:103]
	v_lshl_add_u64 v[32:33], s[56:57], 0, v[32:33]
	v_ashrrev_i32_e32 v97, 31, v96
	v_lshl_add_u64 v[32:33], v[96:97], 1, v[32:33]
	global_load_dwordx2 v[206:207], v[32:33], off
	global_load_dwordx2 v[208:209], v[32:33], off offset:16
	global_load_dwordx2 v[210:211], v[32:33], off offset:32
	global_load_dwordx2 v[212:213], v[32:33], off offset:48
	global_load_dwordx2 v[214:215], v[32:33], off offset:64
	global_load_dwordx2 v[216:217], v[32:33], off offset:80
	global_load_dwordx2 v[218:219], v[32:33], off offset:96
	global_load_dwordx2 v[220:221], v[32:33], off offset:112
	s_waitcnt vmcnt(7)
	v_mov_b32_e32 v34, v206
	v_mov_b32_e32 v35, v207
	v_lshlrev_b32_e32 v38, 16, v34
	v_and_b32_e32 v34, 0xffff0000, v34
	v_mul_f32_e32 v36, 0xbfb8aa3b, v38
	v_mul_f32_e32 v37, 0xbfb8aa3b, v34
	v_exp_f32_e32 v36, v36
	v_exp_f32_e32 v37, v37
	s_nop 0
	v_pk_add_f32 v[36:37], v[36:37], 1.0 op_sel_hi:[1,0]
	s_nop 0
	v_rcp_f32_e32 v40, v37
	s_nop 0
	v_mul_f32_e32 v42, v34, v40
	v_mov_b32_e32 v37, v42
	v_rcp_f32_e32 v39, v36
	s_nop 0
	v_mul_f32_e32 v41, v38, v39
	v_mov_b32_e32 v36, v41
	v_lshlrev_b32_e32 v34, 16, v35
	v_and_b32_e32 v35, 0xffff0000, v35
	v_pk_mul_f32 v[98:99], v[16:17], v[36:37]
	v_mul_f32_e32 v16, 0xbfb8aa3b, v34
	v_mul_f32_e32 v17, 0xbfb8aa3b, v35
	v_exp_f32_e32 v16, v16
	v_exp_f32_e32 v17, v17
	s_nop 0
	v_pk_add_f32 v[16:17], v[16:17], 1.0 op_sel_hi:[1,0]
	s_nop 0
	v_rcp_f32_e32 v37, v17
	s_nop 0
	v_mul_f32_e32 v39, v35, v37
	v_mov_b32_e32 v17, v39
	v_rcp_f32_e32 v36, v16
	s_nop 0
	v_mul_f32_e32 v38, v34, v36
	v_mov_b32_e32 v16, v38
	v_pk_mul_f32 v[100:101], v[18:19], v[16:17]
	v_pk_mul_f32 v[16:17], v[98:99], v[98:99]
	v_pk_mul_f32 v[18:19], v[100:101], v[100:101]
	v_add_f32_e32 v16, v16, v17
	v_add_f32_e32 v18, v18, v19
	v_add_f32_e32 v16, v16, v18
	s_waitcnt vmcnt(6)
	v_mov_b32_e32 v34, v208
	v_mov_b32_e32 v35, v209
	v_lshlrev_b32_e32 v38, 16, v34
	v_and_b32_e32 v34, 0xffff0000, v34
	v_mul_f32_e32 v36, 0xbfb8aa3b, v38
	v_mul_f32_e32 v37, 0xbfb8aa3b, v34
	v_exp_f32_e32 v36, v36
	v_exp_f32_e32 v37, v37
	s_nop 0
	v_pk_add_f32 v[36:37], v[36:37], 1.0 op_sel_hi:[1,0]
	s_nop 0
	v_rcp_f32_e32 v40, v37
	s_nop 0
	v_mul_f32_e32 v42, v34, v40
	v_mov_b32_e32 v37, v42
	v_rcp_f32_e32 v39, v36
	s_nop 0
	v_mul_f32_e32 v41, v38, v39
	v_mov_b32_e32 v36, v41
	v_lshlrev_b32_e32 v34, 16, v35
	v_and_b32_e32 v35, 0xffff0000, v35
	v_pk_mul_f32 v[104:105], v[20:21], v[36:37]
	v_mul_f32_e32 v20, 0xbfb8aa3b, v34
	v_mul_f32_e32 v21, 0xbfb8aa3b, v35
	v_exp_f32_e32 v20, v20
	v_exp_f32_e32 v21, v21
	s_nop 0
	v_pk_add_f32 v[20:21], v[20:21], 1.0 op_sel_hi:[1,0]
	s_nop 0
	v_rcp_f32_e32 v37, v21
	s_nop 0
	v_mul_f32_e32 v39, v35, v37
	v_mov_b32_e32 v21, v39
	v_rcp_f32_e32 v36, v20
	s_nop 0
	v_mul_f32_e32 v38, v34, v36
	v_mov_b32_e32 v20, v38
	v_pk_mul_f32 v[106:107], v[22:23], v[20:21]
	v_pk_mul_f32 v[20:21], v[104:105], v[104:105]
	v_pk_mul_f32 v[22:23], v[106:107], v[106:107]
	v_add_f32_e32 v20, v20, v21
	v_add_f32_e32 v22, v22, v23
	v_add_f32_e32 v20, v20, v22
	v_add_f32_e32 v16, v16, v20
	s_waitcnt vmcnt(5)
; DI_ float bf_lo(unsigned w) { return __uint_as_float(w << 16); }
; DI_ float bf_hi(unsigned w) { return __uint_as_float(w & 0xffff0000u); }
; DI_ float silu_f(float v) { return v / (1.f + __expf(-v)); }
; DI_ void ssd_passC(const bf16_t* xsT, const bf16_t* Btok, const bf16_t* Ctok, const bf16_t* Sc, const float* dt, const float* acum, const float* Dskip, const float* norm_w, bf16_t* Z, unsigned char* lds, int tid, int lane, int wid) {
;     ...
;                 for (int q4 = 0; q4 < 4; ++q4) {
;                     const int chn = hh * 64 + 32 * pb + 8 * q4 + 4 * hi;
;                     const u32x2 zw = *(const u32x2*)(Z + (size_t)tg * DI + chn);
;                     const float a0 = yv[it][pb][4 * q4] * silu_f(bf_lo(zw.x)), a1 = yv[it][pb][4 * q4 + 1] * silu_f(bf_hi(zw.x)), a2 = yv[it][pb][4 * q4 + 2] * silu_f(bf_lo(zw.y)), a3 = yv[it][pb][4 * q4 + 3] * silu_f(bf_hi(zw.y));
;                     sq += (a0 * a0 + a1 * a1) + (a2 * a2 + a3 * a3);
;                     yv[it][pb][4 * q4] = a0; yv[it][pb][4 * q4 + 1] = a1; yv[it][pb][4 * q4 + 2] = a2; yv[it][pb][4 * q4 + 3] = a3;
;                 }
	v_mov_b32_e32 v34, v210
	v_mov_b32_e32 v35, v211
	v_lshlrev_b32_e32 v38, 16, v34
	v_and_b32_e32 v34, 0xffff0000, v34
	v_mul_f32_e32 v36, 0xbfb8aa3b, v38
	v_mul_f32_e32 v37, 0xbfb8aa3b, v34
	v_exp_f32_e32 v36, v36
	v_exp_f32_e32 v37, v37
	s_nop 0
	v_pk_add_f32 v[36:37], v[36:37], 1.0 op_sel_hi:[1,0]
	s_nop 0
	v_rcp_f32_e32 v40, v37
	s_nop 0
	v_mul_f32_e32 v42, v34, v40
	v_mov_b32_e32 v37, v42
	v_rcp_f32_e32 v39, v36
	s_nop 0
	v_mul_f32_e32 v41, v38, v39
	v_mov_b32_e32 v36, v41
	v_lshlrev_b32_e32 v34, 16, v35
	v_and_b32_e32 v35, 0xffff0000, v35
	v_pk_mul_f32 v[108:109], v[24:25], v[36:37]
	v_mul_f32_e32 v24, 0xbfb8aa3b, v34
	v_mul_f32_e32 v25, 0xbfb8aa3b, v35
	v_exp_f32_e32 v24, v24
	v_exp_f32_e32 v25, v25
	s_nop 0
	v_pk_add_f32 v[24:25], v[24:25], 1.0 op_sel_hi:[1,0]
	s_nop 0
	v_rcp_f32_e32 v37, v25
	s_nop 0
	v_mul_f32_e32 v39, v35, v37
	v_mov_b32_e32 v25, v39
	v_rcp_f32_e32 v36, v24
	s_nop 0
	v_mul_f32_e32 v38, v34, v36
	v_mov_b32_e32 v24, v38
	v_pk_mul_f32 v[110:111], v[26:27], v[24:25]
	v_pk_mul_f32 v[24:25], v[108:109], v[108:109]
	v_pk_mul_f32 v[26:27], v[110:111], v[110:111]
	v_add_f32_e32 v18, v24, v25
	v_add_f32_e32 v17, v26, v27
	v_add_f32_e32 v17, v18, v17
	v_add_f32_e32 v16, v16, v17
	s_waitcnt vmcnt(4)
	v_mov_b32_e32 v34, v212
	v_mov_b32_e32 v35, v213
	v_lshlrev_b32_e32 v38, 16, v34
	v_and_b32_e32 v34, 0xffff0000, v34
	v_mul_f32_e32 v36, 0xbfb8aa3b, v38
	v_mul_f32_e32 v37, 0xbfb8aa3b, v34
	v_exp_f32_e32 v36, v36
	v_exp_f32_e32 v37, v37
	s_nop 0
	v_pk_add_f32 v[36:37], v[36:37], 1.0 op_sel_hi:[1,0]
	s_nop 0
	v_rcp_f32_e32 v40, v37
	s_nop 0
	v_mul_f32_e32 v42, v34, v40
	v_mov_b32_e32 v37, v42
	v_rcp_f32_e32 v39, v36
	s_nop 0
	v_mul_f32_e32 v41, v38, v39
	v_mov_b32_e32 v36, v41
	v_lshlrev_b32_e32 v34, 16, v35
	v_and_b32_e32 v35, 0xffff0000, v35
	v_pk_mul_f32 v[112:113], v[28:29], v[36:37]
	v_mul_f32_e32 v28, 0xbfb8aa3b, v34
	v_mul_f32_e32 v29, 0xbfb8aa3b, v35
	v_exp_f32_e32 v28, v28
	v_exp_f32_e32 v29, v29
	s_nop 0
	v_pk_add_f32 v[28:29], v[28:29], 1.0 op_sel_hi:[1,0]
	s_nop 0
	v_rcp_f32_e32 v37, v29
	s_nop 0
	v_mul_f32_e32 v39, v35, v37
	v_mov_b32_e32 v29, v39
	v_rcp_f32_e32 v36, v28
	s_nop 0
	v_mul_f32_e32 v38, v34, v36
	v_mov_b32_e32 v28, v38
	v_pk_mul_f32 v[114:115], v[30:31], v[28:29]
	v_pk_mul_f32 v[28:29], v[112:113], v[112:113]
	v_pk_mul_f32 v[30:31], v[114:115], v[114:115]
	v_add_f32_e32 v18, v28, v29
	v_add_f32_e32 v17, v30, v31
	v_add_f32_e32 v17, v18, v17
	v_add_f32_e32 v16, v16, v17
	s_waitcnt vmcnt(3)
	v_mov_b32_e32 v34, v214
	v_mov_b32_e32 v35, v215
	v_lshlrev_b32_e32 v38, 16, v34
	v_and_b32_e32 v34, 0xffff0000, v34
	v_mul_f32_e32 v36, 0xbfb8aa3b, v38
	v_mul_f32_e32 v37, 0xbfb8aa3b, v34
	v_exp_f32_e32 v36, v36
	v_exp_f32_e32 v37, v37
	s_nop 0
	v_pk_add_f32 v[36:37], v[36:37], 1.0 op_sel_hi:[1,0]
	s_nop 0
	v_rcp_f32_e32 v40, v37
	s_nop 0
	v_mul_f32_e32 v42, v34, v40
	v_mov_b32_e32 v37, v42
	v_rcp_f32_e32 v39, v36
	s_nop 0
	v_mul_f32_e32 v41, v38, v39
	v_mov_b32_e32 v36, v41
	v_lshlrev_b32_e32 v34, 16, v35
	v_and_b32_e32 v35, 0xffff0000, v35
	v_pk_mul_f32 v[116:117], v[0:1], v[36:37]
	v_mul_f32_e32 v0, 0xbfb8aa3b, v34
	v_mul_f32_e32 v1, 0xbfb8aa3b, v35
	v_exp_f32_e32 v0, v0
	v_exp_f32_e32 v1, v1
	s_nop 0
	v_pk_add_f32 v[0:1], v[0:1], 1.0 op_sel_hi:[1,0]
	s_nop 0
	v_rcp_f32_e32 v37, v1
	s_nop 0
	v_mul_f32_e32 v39, v35, v37
	v_mov_b32_e32 v1, v39
	v_rcp_f32_e32 v36, v0
	s_nop 0
	v_mul_f32_e32 v38, v34, v36
	v_mov_b32_e32 v0, v38
	v_pk_mul_f32 v[118:119], v[2:3], v[0:1]
	v_pk_mul_f32 v[0:1], v[116:117], v[116:117]
	v_pk_mul_f32 v[2:3], v[118:119], v[118:119]
	v_add_f32_e32 v0, v0, v1
	v_add_f32_e32 v2, v2, v3
	v_add_f32_e32 v0, v0, v2
	v_add_f32_e32 v0, v16, v0
	s_waitcnt vmcnt(2)
; DI_ float bf_lo(unsigned w) { return __uint_as_float(w << 16); }
; DI_ float bf_hi(unsigned w) { return __uint_as_float(w & 0xffff0000u); }
; DI_ float silu_f(float v) { return v / (1.f + __expf(-v)); }
; DI_ void ssd_passC(const bf16_t* xsT, const bf16_t* Btok, const bf16_t* Ctok, const bf16_t* Sc, const float* dt, const float* acum, const float* Dskip, const float* norm_w, bf16_t* Z, unsigned char* lds, int tid, int lane, int wid) {
;     ...
;                 for (int q4 = 0; q4 < 4; ++q4) {
;                     const int chn = hh * 64 + 32 * pb + 8 * q4 + 4 * hi;
;                     const u32x2 zw = *(const u32x2*)(Z + (size_t)tg * DI + chn);
;                     const float a0 = yv[it][pb][4 * q4] * silu_f(bf_lo(zw.x)), a1 = yv[it][pb][4 * q4 + 1] * silu_f(bf_hi(zw.x)), a2 = yv[it][pb][4 * q4 + 2] * silu_f(bf_lo(zw.y)), a3 = yv[it][pb][4 * q4 + 3] * silu_f(bf_hi(zw.y));
;                     sq += (a0 * a0 + a1 * a1) + (a2 * a2 + a3 * a3);
;                     yv[it][pb][4 * q4] = a0; yv[it][pb][4 * q4 + 1] = a1; yv[it][pb][4 * q4 + 2] = a2; yv[it][pb][4 * q4 + 3] = a3;
;                 }
;             sq += __shfl_xor(sq, 32);
;             if (hi == 0) ex[hl * 128 + tl] = sq;
	v_mov_b32_e32 v34, v216
	v_mov_b32_e32 v35, v217
	v_lshlrev_b32_e32 v38, 16, v34
	v_and_b32_e32 v34, 0xffff0000, v34
	v_mul_f32_e32 v36, 0xbfb8aa3b, v38
	v_mul_f32_e32 v37, 0xbfb8aa3b, v34
	v_exp_f32_e32 v36, v36
	v_exp_f32_e32 v37, v37
	s_nop 0
	v_pk_add_f32 v[36:37], v[36:37], 1.0 op_sel_hi:[1,0]
	s_nop 0
	v_rcp_f32_e32 v40, v37
	s_nop 0
	v_mul_f32_e32 v42, v34, v40
	v_mov_b32_e32 v37, v42
	v_rcp_f32_e32 v39, v36
	s_nop 0
	v_mul_f32_e32 v41, v38, v39
	v_mov_b32_e32 v36, v41
	v_lshlrev_b32_e32 v34, 16, v35
	v_and_b32_e32 v35, 0xffff0000, v35
	v_pk_mul_f32 v[120:121], v[4:5], v[36:37]
	v_mul_f32_e32 v4, 0xbfb8aa3b, v34
	v_mul_f32_e32 v5, 0xbfb8aa3b, v35
	v_exp_f32_e32 v4, v4
	v_exp_f32_e32 v5, v5
	s_nop 0
	v_pk_add_f32 v[4:5], v[4:5], 1.0 op_sel_hi:[1,0]
	s_nop 0
	v_rcp_f32_e32 v37, v5
	s_nop 0
	v_mul_f32_e32 v39, v35, v37
	v_mov_b32_e32 v5, v39
	v_rcp_f32_e32 v36, v4
	s_nop 0
	v_mul_f32_e32 v38, v34, v36
	v_mov_b32_e32 v4, v38
	v_pk_mul_f32 v[122:123], v[6:7], v[4:5]
	v_pk_mul_f32 v[4:5], v[120:121], v[120:121]
	v_pk_mul_f32 v[6:7], v[122:123], v[122:123]
	v_add_f32_e32 v2, v4, v5
	v_add_f32_e32 v1, v6, v7
	v_add_f32_e32 v1, v2, v1
	v_add_f32_e32 v0, v0, v1
	s_waitcnt vmcnt(1)
	v_mov_b32_e32 v34, v218
	v_mov_b32_e32 v35, v219
	v_lshlrev_b32_e32 v38, 16, v34
	v_and_b32_e32 v34, 0xffff0000, v34
	v_mul_f32_e32 v36, 0xbfb8aa3b, v38
	v_mul_f32_e32 v37, 0xbfb8aa3b, v34
	v_exp_f32_e32 v36, v36
	v_exp_f32_e32 v37, v37
	s_nop 0
	v_pk_add_f32 v[36:37], v[36:37], 1.0 op_sel_hi:[1,0]
	s_nop 0
	v_rcp_f32_e32 v40, v37
	s_nop 0
	v_mul_f32_e32 v42, v34, v40
	v_mov_b32_e32 v37, v42
	v_rcp_f32_e32 v39, v36
	s_nop 0
	v_mul_f32_e32 v41, v38, v39
	v_mov_b32_e32 v36, v41
	v_lshlrev_b32_e32 v34, 16, v35
	v_and_b32_e32 v35, 0xffff0000, v35
	v_pk_mul_f32 v[124:125], v[8:9], v[36:37]
	v_mul_f32_e32 v8, 0xbfb8aa3b, v34
	v_mul_f32_e32 v9, 0xbfb8aa3b, v35
	v_exp_f32_e32 v8, v8
	v_exp_f32_e32 v9, v9
	s_nop 0
	v_pk_add_f32 v[8:9], v[8:9], 1.0 op_sel_hi:[1,0]
	s_nop 0
	v_rcp_f32_e32 v37, v9
	s_nop 0
	v_mul_f32_e32 v39, v35, v37
	v_mov_b32_e32 v9, v39
	v_rcp_f32_e32 v36, v8
	s_nop 0
	v_mul_f32_e32 v38, v34, v36
	v_mov_b32_e32 v35, v38
	s_waitcnt vmcnt(0)
	v_mov_b32_e32 v32, v220
	v_mov_b32_e32 v33, v221
	v_lshlrev_b32_e32 v36, 16, v32
	v_and_b32_e32 v32, 0xffff0000, v32
	v_mov_b32_e32 v8, v35
	v_mul_f32_e32 v34, 0xbfb8aa3b, v36
	v_mul_f32_e32 v35, 0xbfb8aa3b, v32
	v_exp_f32_e32 v34, v34
	v_exp_f32_e32 v35, v35
	v_pk_mul_f32 v[126:127], v[10:11], v[8:9]
	v_pk_mul_f32 v[8:9], v[124:125], v[124:125]
	v_pk_mul_f32 v[10:11], v[126:127], v[126:127]
	v_pk_add_f32 v[34:35], v[34:35], 1.0 op_sel_hi:[1,0]
	v_add_f32_e32 v1, v10, v11
	v_rcp_f32_e32 v38, v35
	v_add_f32_e32 v2, v8, v9
	v_add_f32_e32 v1, v2, v1
	v_add_f32_e32 v0, v0, v1
	v_mul_f32_e32 v40, v32, v38
	v_mov_b32_e32 v35, v40
	v_rcp_f32_e32 v37, v34
	s_nop 0
	v_mul_f32_e32 v39, v36, v37
	v_mov_b32_e32 v34, v39
	v_lshlrev_b32_e32 v32, 16, v33
	v_and_b32_e32 v33, 0xffff0000, v33
	v_pk_mul_f32 v[128:129], v[12:13], v[34:35]
	v_mul_f32_e32 v12, 0xbfb8aa3b, v32
	v_mul_f32_e32 v13, 0xbfb8aa3b, v33
	v_exp_f32_e32 v12, v12
	v_exp_f32_e32 v13, v13
	s_nop 0
	v_pk_add_f32 v[12:13], v[12:13], 1.0 op_sel_hi:[1,0]
	s_nop 0
	v_rcp_f32_e32 v35, v13
	s_nop 0
	v_mul_f32_e32 v37, v33, v35
	v_mov_b32_e32 v13, v37
	v_rcp_f32_e32 v34, v12
	s_nop 0
	v_mul_f32_e32 v36, v32, v34
	v_mov_b32_e32 v12, v36
	v_pk_mul_f32 v[130:131], v[14:15], v[12:13]
	v_pk_mul_f32 v[12:13], v[128:129], v[128:129]
	v_pk_mul_f32 v[14:15], v[130:131], v[130:131]
	v_add_f32_e32 v2, v12, v13
	v_add_f32_e32 v1, v14, v15
	v_add_f32_e32 v1, v2, v1
	v_add_f32_e32 v0, v0, v1
	ds_bpermute_b32 v1, v139, v0
	s_and_saveexec_b64 s[0:1], s[40:41]
	s_cbranch_execz .LBB0_768
	s_waitcnt lgkmcnt(0)
	v_add_f32_e32 v0, v0, v1
	ds_write_b32 v141, v0

; DI_ bf16x8 pack8(float a0, float a1, float a2, float a3, float a4, float a5, float a6, float a7) { u32x4 p; p.x = pk2(a0, a1); p.y = pk2(a2, a3); p.z = pk2(a4, a5); p.w = pk2(a6, a7); return __builtin_bit_cast(bf16x8, p); }
; #define MFMA32(a, b, c) __builtin_amdgcn_mfma_f32_32x32x16_bf16((a), (b), (c), 0, 0, 0)
; DI_ int kvmap(int rho) { return (rho & 0x13) | ((rho & 4) << 1) | ((rho & 8) >> 1); }
; DI_ void ssd_passC(const bf16_t* xsT, const bf16_t* Btok, const bf16_t* Ctok, const bf16_t* Sc, const float* dt, const float* acum, const float* Dskip, const float* norm_w, bf16_t* Z, unsigned char* lds, int tid, int lane, int wid) {
;     ...
;             for (int sb = 0; sb <= tb; ++sb) {
;                 f32x16 cb;
; #pragma unroll
;                 for (int i = 0; i < 16; ++i) cb[i] = 0.f;
;                 const unsigned char* bp = lds + PC_B + (32 * sb + kvmap(r32)) * PC_RS + hi * 16;
; #pragma unroll
;                 for (int ks = 0; ks < 8; ++ks) cb = MFMA32(*(const bf16x8*)(bp + 32 * ks), *(const bf16x8*)(cfp + 32 * ks), cb);
;                 float m[16];
; #pragma unroll
;                 for (int q4 = 0; q4 < 4; ++q4) {
;                     const int sl0 = 32 * sb + 16 * (q4 >> 1) + 8 * hi + 4 * (q4 & 1);
;                     const f32x4 as4 = *(const f32x4*)(sa + hl * 128 + sl0), ds4 = *(const f32x4*)(sd + hl * 128 + sl0);
; #pragma unroll
;                     for (int e = 0; e < 4; ++e) { const int sl = sl0 + e; float v = cb[4 * q4 + e] * __expf(fminf(at - as4[e], 0.f)) * ds4[e]; v = (sl <= tl) ? v : 0.f; if (sl == tl) v += Dh; m[4 * q4 + e] = v; }
;                 }
;                 const bf16x8 pf0 = pack8(m[0], m[1], m[2], m[3], m[4], m[5], m[6], m[7]), pf1 = pack8(m[8], m[9], m[10], m[11], m[12], m[13], m[14], m[15]);
; #pragma unroll
;                 for (int pb = 0; pb < 2; ++pb) {
;                     const unsigned char* xp = lds + PC_X + (hl * 64 + 32 * pb + r32) * PC_RS + (32 * sb + 8 * hi) * 2;
;                     yv[it][pb] = MFMA32(*(const bf16x8*)xp, pf0, yv[it][pb]); yv[it][pb] = MFMA32(*(const bf16x8*)(xp + 32), pf1, yv[it][pb]);
;                 }
;             }
.LBB0_769:
	v_add_u32_e32 v159, 0, v156
	ds_read_b128 v[32:35], v159
	ds_read_b128 v[160:163], v159 offset:32
	v_add_u32_e32 v177, 0, v157
	v_add_u32_e32 v164, 0x22800, v177
	v_add_u32_e32 v157, 0x80, v157
	s_waitcnt lgkmcnt(1)
	v_mfma_f32_32x32x16_bf16 v[32:47], v[32:35], v[50:53], 0
	v_add_u32_e32 v156, 0x2200, v156
	ds_read_b128 v[164:167], v164
	s_waitcnt lgkmcnt(1)
	v_mfma_f32_32x32x16_bf16 v[32:47], v[160:163], v[54:57], v[32:47]
	ds_read_b128 v[160:163], v159 offset:64
	s_waitcnt lgkmcnt(0)
	v_mfma_f32_32x32x16_bf16 v[32:47], v[160:163], v[58:61], v[32:47]
	ds_read_b128 v[160:163], v159 offset:96
	s_waitcnt lgkmcnt(0)
	v_mfma_f32_32x32x16_bf16 v[32:47], v[160:163], v[62:65], v[32:47]
	ds_read_b128 v[160:163], v159 offset:128
	s_waitcnt lgkmcnt(0)
	v_mfma_f32_32x32x16_bf16 v[32:47], v[160:163], v[66:69], v[32:47]
	ds_read_b128 v[160:163], v159 offset:160
	s_waitcnt lgkmcnt(0)
	v_mfma_f32_32x32x16_bf16 v[32:47], v[160:163], v[70:73], v[32:47]
	ds_read_b128 v[160:163], v159 offset:192
	s_waitcnt lgkmcnt(0)
	v_mfma_f32_32x32x16_bf16 v[32:47], v[160:163], v[74:77], v[32:47]
	ds_read_b128 v[160:163], v159 offset:224
	v_add_u32_e32 v159, s7, v137
	v_cmp_gt_u32_e32 vcc, v92, v159
	v_cmp_le_u32_e64 s[0:1], v159, v92
	v_add_u32_e32 v178, 4, v159
	s_add_i32 s7, s7, 32
	s_waitcnt lgkmcnt(0)
	v_mfma_f32_32x32x16_bf16 v[32:47], v[160:163], v[78:81], v[32:47]
	v_add_u32_e32 v160, 0x22000, v177
	ds_read_b128 v[160:163], v160
	s_waitcnt lgkmcnt(0)
	v_sub_f32_e32 v160, v155, v160
	v_sub_f32_e32 v161, v155, v161
	v_min_f32_e32 v160, 0, v160
	v_min_f32_e32 v161, 0, v161
	v_mul_f32_e32 v160, 0x3fb8aa3b, v160
	v_mul_f32_e32 v161, 0x3fb8aa3b, v161
	v_exp_f32_e32 v160, v160
	v_exp_f32_e32 v161, v161
	s_nop 0
	v_mul_f32_e32 v32, v32, v160
	v_mul_f32_e32 v33, v33, v161
	v_mul_f32_e32 v32, v164, v32
	v_mul_f32_e32 v161, v165, v33
	v_add_u32_e32 v160, 1, v159
	v_cndmask_b32_e64 v33, 0, v32, s[0:1]
	v_cndmask_b32_e32 v32, 0, v161, vcc
	v_cmp_eq_u32_e32 vcc, v159, v92
	v_cmp_eq_u32_e64 s[0:1], v160, v91
	v_pk_add_f32 v[160:161], v[132:133], v[32:33]
	s_nop 0
	v_cndmask_b32_e64 v164, v32, v160, s[0:1]
	v_cndmask_b32_e32 v165, v33, v161, vcc
	v_sub_f32_e32 v32, v155, v162
	v_sub_f32_e32 v33, v155, v163
	v_min_f32_e32 v32, 0, v32
	v_min_f32_e32 v33, 0, v33
	v_mul_f32_e32 v32, 0x3fb8aa3b, v32
	v_mul_f32_e32 v33, 0x3fb8aa3b, v33
	v_exp_f32_e32 v32, v32
	v_exp_f32_e32 v33, v33
	v_or_b32_e32 v160, 3, v159
	v_or_b32_e32 v161, 2, v159
	v_cmp_le_u32_e32 vcc, v160, v91
	v_pk_mul_f32 v[32:33], v[34:35], v[32:33]
	v_cmp_eq_u32_e64 s[0:1], v160, v91
	v_pk_mul_f32 v[32:33], v[166:167], v[32:33]
	v_add_u32_e32 v160, 0x22810, v177
	v_cndmask_b32_e32 v33, 0, v33, vcc
	v_cmp_le_u32_e32 vcc, v161, v92
	s_nop 1
	v_cndmask_b32_e32 v32, 0, v32, vcc
	v_cmp_eq_u32_e32 vcc, v161, v92
	v_pk_add_f32 v[34:35], v[132:133], v[32:33]
	ds_read_b128 v[160:163], v160
	v_cndmask_b32_e32 v167, v32, v34, vcc
	v_add_u32_e32 v32, 0x22010, v177
	v_cndmask_b32_e64 v166, v33, v35, s[0:1]
	ds_read_b128 v[32:35], v32
	v_cmp_gt_u32_e32 vcc, v92, v178
	v_cmp_le_u32_e64 s[0:1], v178, v92
	s_waitcnt lgkmcnt(0)
	v_sub_f32_e32 v32, v155, v32
	v_sub_f32_e32 v33, v155, v33
	v_min_f32_e32 v32, 0, v32
	v_min_f32_e32 v33, 0, v33
	v_mul_f32_e32 v32, 0x3fb8aa3b, v32
	v_mul_f32_e32 v33, 0x3fb8aa3b, v33
	v_exp_f32_e32 v32, v32
	v_exp_f32_e32 v33, v33
	v_mul_f32_e32 v32, v36, v32
	v_mul_f32_e32 v33, v37, v33
	v_mul_f32_e32 v32, v160, v32
	v_mul_f32_e32 v37, v161, v33
	v_add_u32_e32 v36, 5, v159
	v_cndmask_b32_e64 v33, 0, v32, s[0:1]
	v_cndmask_b32_e32 v32, 0, v37, vcc
	v_cmp_eq_u32_e32 vcc, v178, v92
	v_cmp_eq_u32_e64 s[0:1], v36, v91
	v_pk_add_f32 v[36:37], v[132:133], v[32:33]
	s_nop 0
	v_cndmask_b32_e64 v160, v32, v36, s[0:1]
	v_cndmask_b32_e32 v161, v33, v37, vcc
	v_sub_f32_e32 v32, v155, v34
	v_sub_f32_e32 v33, v155, v35
	v_min_f32_e32 v32, 0, v32
	v_min_f32_e32 v33, 0, v33
	v_mul_f32_e32 v32, 0x3fb8aa3b, v32
	v_mul_f32_e32 v33, 0x3fb8aa3b, v33
	v_exp_f32_e32 v32, v32
	v_exp_f32_e32 v33, v33
	v_or_b32_e32 v34, 3, v178
	v_or_b32_e32 v35, 2, v178
	v_cmp_le_u32_e32 vcc, v34, v91
	v_pk_mul_f32 v[32:33], v[38:39], v[32:33]
	v_cmp_eq_u32_e64 s[0:1], v34, v91
	v_pk_mul_f32 v[32:33], v[162:163], v[32:33]
	v_add_u32_e32 v36, 0x22840, v177
	v_cndmask_b32_e32 v33, 0, v33, vcc
	v_cmp_le_u32_e32 vcc, v35, v92
	ds_read_b128 v[36:39], v36
	v_add_u32_e32 v178, 16, v159
	v_cndmask_b32_e32 v32, 0, v32, vcc
	v_cmp_eq_u32_e32 vcc, v35, v92
	v_pk_add_f32 v[34:35], v[132:133], v[32:33]
	s_nop 0
	v_cndmask_b32_e32 v163, v32, v34, vcc
	v_add_u32_e32 v32, 0x22040, v177
	v_cndmask_b32_e64 v162, v33, v35, s[0:1]
	ds_read_b128 v[32:35], v32
	v_cmp_gt_u32_e32 vcc, v92, v178
	v_cmp_le_u32_e64 s[0:1], v178, v92
	s_waitcnt lgkmcnt(0)
	v_sub_f32_e32 v32, v155, v32
	v_sub_f32_e32 v33, v155, v33
	v_min_f32_e32 v32, 0, v32
	v_min_f32_e32 v33, 0, v33
	v_mul_f32_e32 v32, 0x3fb8aa3b, v32
	v_mul_f32_e32 v33, 0x3fb8aa3b, v33
	v_exp_f32_e32 v32, v32
	v_exp_f32_e32 v33, v33
	v_mul_f32_e32 v32, v40, v32
	v_mul_f32_e32 v33, v41, v33
	v_mul_f32_e32 v32, v36, v32
	v_mul_f32_e32 v37, v37, v33
	v_add_u32_e32 v36, 17, v159
	v_cndmask_b32_e64 v33, 0, v32, s[0:1]
	v_cndmask_b32_e32 v32, 0, v37, vcc
	v_cmp_eq_u32_e32 vcc, v178, v92
	v_cmp_eq_u32_e64 s[0:1], v36, v91
	v_pk_add_f32 v[36:37], v[132:133], v[32:33]
	s_nop 0
	v_cndmask_b32_e64 v40, v32, v36, s[0:1]
	v_cndmask_b32_e32 v41, v33, v37, vcc
	v_sub_f32_e32 v32, v155, v34
	v_sub_f32_e32 v33, v155, v35
	v_min_f32_e32 v32, 0, v32
	v_min_f32_e32 v33, 0, v33
	v_mul_f32_e32 v32, 0x3fb8aa3b, v32
	v_mul_f32_e32 v33, 0x3fb8aa3b, v33
	v_exp_f32_e32 v32, v32
	v_exp_f32_e32 v33, v33
	v_or_b32_e32 v34, 3, v178
	v_or_b32_e32 v35, 2, v178
	v_cmp_le_u32_e32 vcc, v34, v91
	v_pk_mul_f32 v[32:33], v[42:43], v[32:33]
	v_cmp_eq_u32_e64 s[0:1], v34, v91
	v_pk_mul_f32 v[32:33], v[38:39], v[32:33]
	v_add_u32_e32 v36, 0x22850, v177
	v_cndmask_b32_e32 v33, 0, v33, vcc
	v_cmp_le_u32_e32 vcc, v35, v92
	ds_read_b128 v[36:39], v36
	v_add_u32_e32 v178, 20, v159
	v_cndmask_b32_e32 v32, 0, v32, vcc
	v_cmp_eq_u32_e32 vcc, v35, v92
	v_pk_add_f32 v[34:35], v[132:133], v[32:33]
	s_nop 0
	v_cndmask_b32_e32 v43, v32, v34, vcc
	v_add_u32_e32 v32, 0x22050, v177
	v_cndmask_b32_e64 v42, v33, v35, s[0:1]
	ds_read_b128 v[32:35], v32
	v_cmp_gt_u32_e32 vcc, v92, v178
	v_cmp_le_u32_e64 s[0:1], v178, v92
	s_waitcnt lgkmcnt(0)
; DI_ float bf_lo(unsigned w) { return __uint_as_float(w << 16); }
; DI_ float bf_hi(unsigned w) { return __uint_as_float(w & 0xffff0000u); }
; DI_ bf16x8 pack8(float a0, float a1, float a2, float a3, float a4, float a5, float a6, float a7) { u32x4 p; p.x = pk2(a0, a1); p.y = pk2(a2, a3); p.z = pk2(a4, a5); p.w = pk2(a6, a7); return __builtin_bit_cast(bf16x8, p); }
; #define MFMA32(a, b, c) __builtin_amdgcn_mfma_f32_32x32x16_bf16((a), (b), (c), 0, 0, 0)
; DI_ float silu_f(float v) { return v / (1.f + __expf(-v)); }
; DI_ void ssd_passC(const bf16_t* xsT, const bf16_t* Btok, const bf16_t* Ctok, const bf16_t* Sc, const float* dt, const float* acum, const float* Dskip, const float* norm_w, bf16_t* Z, unsigned char* lds, int tid, int lane, int wid) {
;     ...
;                     for (int e = 0; e < 4; ++e) { const int sl = sl0 + e; float v = cb[4 * q4 + e] * __expf(fminf(at - as4[e], 0.f)) * ds4[e]; v = (sl <= tl) ? v : 0.f; if (sl == tl) v += Dh; m[4 * q4 + e] = v; }
;                 }
;                 const bf16x8 pf0 = pack8(m[0], m[1], m[2], m[3], m[4], m[5], m[6], m[7]), pf1 = pack8(m[8], m[9], m[10], m[11], m[12], m[13], m[14], m[15]);
; #pragma unroll
;                 for (int pb = 0; pb < 2; ++pb) {
;                     const unsigned char* xp = lds + PC_X + (hl * 64 + 32 * pb + r32) * PC_RS + (32 * sb + 8 * hi) * 2;
;                     yv[it][pb] = MFMA32(*(const bf16x8*)xp, pf0, yv[it][pb]); yv[it][pb] = MFMA32(*(const bf16x8*)(xp + 32), pf1, yv[it][pb]);
;                 }
;             }
;             const int tg = t0 + tl; float sq = 0.f;
; #pragma unroll
;             for (int pb = 0; pb < 2; ++pb)
; #pragma unroll
;                 for (int q4 = 0; q4 < 4; ++q4) {
;                     const int chn = hh * 64 + 32 * pb + 8 * q4 + 4 * hi;
;                     const u32x2 zw = *(const u32x2*)(Z + (size_t)tg * DI + chn);
;                     const float a0 = yv[it][pb][4 * q4] * silu_f(bf_lo(zw.x)), a1 = yv[it][pb][4 * q4 + 1] * silu_f(bf_hi(zw.x)), a2 = yv[it][pb][4 * q4 + 2] * silu_f(bf_lo(zw.y)), a3 = yv[it][pb][4 * q4 + 3] * silu_f(bf_hi(zw.y));
;                     sq += (a0 * a0 + a1 * a1) + (a2 * a2 + a3 * a3);
;                     yv[it][pb][4 * q4] = a0; yv[it][pb][4 * q4 + 1] = a1; yv[it][pb][4 * q4 + 2] = a2; yv[it][pb][4 * q4 + 3] = a3;
;                 }
	v_sub_f32_e32 v32, v155, v32
	v_sub_f32_e32 v33, v155, v33
	v_min_f32_e32 v32, 0, v32
	v_min_f32_e32 v33, 0, v33
	v_mul_f32_e32 v32, 0x3fb8aa3b, v32
	v_mul_f32_e32 v33, 0x3fb8aa3b, v33
	v_exp_f32_e32 v32, v32
	v_exp_f32_e32 v33, v33
	v_mul_f32_e32 v32, v44, v32
	v_mul_f32_e32 v33, v45, v33
	v_mul_f32_e32 v32, v36, v32
	v_mul_f32_e32 v37, v37, v33
	v_add_u32_e32 v36, 21, v159
	v_cndmask_b32_e64 v33, 0, v32, s[0:1]
	v_cndmask_b32_e32 v32, 0, v37, vcc
	v_cmp_eq_u32_e32 vcc, v178, v92
	v_cmp_eq_u32_e64 s[0:1], v36, v91
	v_pk_add_f32 v[36:37], v[132:133], v[32:33]
	s_nop 0
	v_cndmask_b32_e64 v44, v32, v36, s[0:1]
	v_cndmask_b32_e32 v45, v33, v37, vcc
	v_sub_f32_e32 v32, v155, v34
	v_sub_f32_e32 v33, v155, v35
	v_min_f32_e32 v32, 0, v32
	v_min_f32_e32 v33, 0, v33
	v_mul_f32_e32 v32, 0x3fb8aa3b, v32
	v_mul_f32_e32 v33, 0x3fb8aa3b, v33
	v_exp_f32_e32 v32, v32
	v_exp_f32_e32 v33, v33
	v_or_b32_e32 v34, 3, v178
	v_or_b32_e32 v35, 2, v178
	v_cmp_le_u32_e32 vcc, v34, v91
	v_pk_mul_f32 v[32:33], v[46:47], v[32:33]
	v_cmp_eq_u32_e64 s[0:1], v34, v91
	v_pk_mul_f32 v[32:33], v[38:39], v[32:33]
	v_cvt_pk_bf16_f32 v36, v165, v164
	v_cndmask_b32_e32 v33, 0, v33, vcc
	v_cmp_le_u32_e32 vcc, v35, v92
	v_cvt_pk_bf16_f32 v37, v167, v166
	v_cvt_pk_bf16_f32 v38, v161, v160
	v_cndmask_b32_e32 v32, 0, v32, vcc
	v_cmp_eq_u32_e32 vcc, v35, v92
	v_pk_add_f32 v[34:35], v[132:133], v[32:33]
	v_cvt_pk_bf16_f32 v39, v163, v162
	v_cndmask_b32_e32 v46, v32, v34, vcc
	v_cvt_pk_bf16_f32 v34, v45, v44
	v_add_u32_e32 v44, 0, v158
	v_cvt_pk_bf16_f32 v32, v41, v40
	v_add_u32_e32 v40, 0x11000, v44
	v_cndmask_b32_e64 v35, v33, v35, s[0:1]
	v_cvt_pk_bf16_f32 v33, v43, v42
	ds_read_b128 v[40:43], v40
	s_waitcnt lgkmcnt(0)
	v_mfma_f32_32x32x16_bf16 v[16:31], v[40:43], v[36:39], v[16:31]
	v_add_u32_e32 v40, 0x11020, v44
	ds_read_b128 v[40:43], v40
	v_cvt_pk_bf16_f32 v35, v46, v35
	s_add_i32 s0, s19, s7
	v_add_u32_e32 v158, 64, v158
	s_cmp_lg_u32 s0, 0
	s_waitcnt lgkmcnt(0)
	v_mfma_f32_32x32x16_bf16 v[16:31], v[40:43], v[32:35], v[16:31]
	v_add_u32_e32 v40, 0x13200, v44
	ds_read_b128 v[40:43], v40
	s_waitcnt lgkmcnt(0)
	v_mfma_f32_32x32x16_bf16 v[0:15], v[40:43], v[36:39], v[0:15]
	v_add_u32_e32 v36, 0x13220, v44
	ds_read_b128 v[36:39], v36
	s_waitcnt lgkmcnt(0)
	v_mfma_f32_32x32x16_bf16 v[0:15], v[36:39], v[32:35], v[0:15]
	s_cbranch_scc1 .LBB0_769
	v_or_b32_e32 v32, s42, v92
	v_ashrrev_i32_e32 v33, 31, v32
	v_lshl_or_b32 v34, s6, 6, v138
	v_lshlrev_b64 v[32:33], 12, v[32:33]
	v_lshl_add_u64 v[32:33], s[56:57], 0, v[32:33]
	v_ashrrev_i32_e32 v35, 31, v34
	v_lshl_add_u64 v[46:47], v[34:35], 1, v[32:33]
	global_load_dwordx2 v[206:207], v[46:47], off
	global_load_dwordx2 v[208:209], v[46:47], off offset:16
	global_load_dwordx2 v[210:211], v[46:47], off offset:32
	global_load_dwordx2 v[212:213], v[46:47], off offset:48
	global_load_dwordx2 v[214:215], v[46:47], off offset:64
	global_load_dwordx2 v[216:217], v[46:47], off offset:80
	global_load_dwordx2 v[218:219], v[46:47], off offset:96
	global_load_dwordx2 v[220:221], v[46:47], off offset:112
	s_waitcnt vmcnt(7)
	v_mov_b32_e32 v34, v206
	v_mov_b32_e32 v35, v207
	v_lshlrev_b32_e32 v38, 16, v34
	v_and_b32_e32 v34, 0xffff0000, v34
	v_mul_f32_e32 v36, 0xbfb8aa3b, v38
	v_mul_f32_e32 v37, 0xbfb8aa3b, v34
	v_exp_f32_e32 v36, v36
	v_exp_f32_e32 v37, v37
	s_nop 0
	v_pk_add_f32 v[36:37], v[36:37], 1.0 op_sel_hi:[1,0]
	s_nop 0
	v_rcp_f32_e32 v40, v37
	s_nop 0
	v_mul_f32_e32 v42, v34, v40
	v_mov_b32_e32 v37, v42
	v_rcp_f32_e32 v39, v36
	s_nop 0
	v_mul_f32_e32 v41, v38, v39
	v_mov_b32_e32 v36, v41
	v_pk_mul_f32 v[16:17], v[16:17], v[36:37]
	v_lshlrev_b32_e32 v36, 16, v35
	v_and_b32_e32 v37, 0xffff0000, v35
	v_mul_f32_e32 v34, 0xbfb8aa3b, v36
	v_mul_f32_e32 v35, 0xbfb8aa3b, v37
	v_exp_f32_e32 v34, v34
	v_exp_f32_e32 v35, v35
	s_nop 0
	v_pk_add_f32 v[34:35], v[34:35], 1.0 op_sel_hi:[1,0]
	s_nop 0
	v_rcp_f32_e32 v39, v35
	s_nop 0
	v_mul_f32_e32 v41, v37, v39
	v_mov_b32_e32 v35, v41
	v_rcp_f32_e32 v38, v34
	s_nop 0
	v_mul_f32_e32 v40, v36, v38
	v_mov_b32_e32 v34, v40
	v_pk_mul_f32 v[18:19], v[18:19], v[34:35]
	v_pk_mul_f32 v[34:35], v[16:17], v[16:17]
	v_pk_mul_f32 v[36:37], v[18:19], v[18:19]
	v_add_f32_e32 v34, v34, v35
	v_add_f32_e32 v36, v36, v37
	v_add_f32_e32 v34, v34, v36
	s_waitcnt vmcnt(6)
	v_mov_b32_e32 v38, v208
	v_mov_b32_e32 v39, v209
	v_lshlrev_b32_e32 v42, 16, v38
	v_and_b32_e32 v38, 0xffff0000, v38
	v_mul_f32_e32 v40, 0xbfb8aa3b, v42
	v_mul_f32_e32 v41, 0xbfb8aa3b, v38
	v_exp_f32_e32 v40, v40
	v_exp_f32_e32 v41, v41
	s_nop 0
	v_pk_add_f32 v[40:41], v[40:41], 1.0 op_sel_hi:[1,0]
	s_nop 0
	v_rcp_f32_e32 v44, v41
	s_nop 0
	v_mul_f32_e32 v50, v38, v44
	v_mov_b32_e32 v41, v50
	v_rcp_f32_e32 v43, v40
	s_nop 0
	v_mul_f32_e32 v45, v42, v43
	v_mov_b32_e32 v40, v45
	v_pk_mul_f32 v[20:21], v[20:21], v[40:41]
	v_lshlrev_b32_e32 v40, 16, v39
	v_and_b32_e32 v41, 0xffff0000, v39
	v_mul_f32_e32 v38, 0xbfb8aa3b, v40
	v_mul_f32_e32 v39, 0xbfb8aa3b, v41
	v_exp_f32_e32 v38, v38
	v_exp_f32_e32 v39, v39
	s_nop 0
	v_pk_add_f32 v[38:39], v[38:39], 1.0 op_sel_hi:[1,0]
	s_nop 0
	v_rcp_f32_e32 v43, v39
	s_nop 0
	v_mul_f32_e32 v45, v41, v43
	v_mov_b32_e32 v39, v45
	v_rcp_f32_e32 v42, v38
	s_nop 0
	v_mul_f32_e32 v44, v40, v42
	v_mov_b32_e32 v38, v44
	v_pk_mul_f32 v[22:23], v[22:23], v[38:39]
	v_pk_mul_f32 v[38:39], v[20:21], v[20:21]
	v_pk_mul_f32 v[40:41], v[22:23], v[22:23]
	v_add_f32_e32 v38, v38, v39
	v_add_f32_e32 v40, v40, v41
	v_add_f32_e32 v38, v38, v40
	v_add_f32_e32 v34, v34, v38
	s_waitcnt vmcnt(5)
; DI_ float bf_lo(unsigned w) { return __uint_as_float(w << 16); }
; DI_ float bf_hi(unsigned w) { return __uint_as_float(w & 0xffff0000u); }
; DI_ float silu_f(float v) { return v / (1.f + __expf(-v)); }
; DI_ void ssd_passC(const bf16_t* xsT, const bf16_t* Btok, const bf16_t* Ctok, const bf16_t* Sc, const float* dt, const float* acum, const float* Dskip, const float* norm_w, bf16_t* Z, unsigned char* lds, int tid, int lane, int wid) {
;     ...
; #pragma unroll
;             for (int pb = 0; pb < 2; ++pb)
; #pragma unroll
;                 for (int q4 = 0; q4 < 4; ++q4) {
;                     const int chn = hh * 64 + 32 * pb + 8 * q4 + 4 * hi;
;                     const u32x2 zw = *(const u32x2*)(Z + (size_t)tg * DI + chn);
;                     const float a0 = yv[it][pb][4 * q4] * silu_f(bf_lo(zw.x)), a1 = yv[it][pb][4 * q4 + 1] * silu_f(bf_hi(zw.x)), a2 = yv[it][pb][4 * q4 + 2] * silu_f(bf_lo(zw.y)), a3 = yv[it][pb][4 * q4 + 3] * silu_f(bf_hi(zw.y));
;                     sq += (a0 * a0 + a1 * a1) + (a2 * a2 + a3 * a3);
;                     yv[it][pb][4 * q4] = a0; yv[it][pb][4 * q4 + 1] = a1; yv[it][pb][4 * q4 + 2] = a2; yv[it][pb][4 * q4 + 3] = a3;
;                 }
;             sq += __shfl_xor(sq, 32);
;             if (hi == 0) ex[hl * 128 + tl] = sq;
	v_mov_b32_e32 v42, v210
	v_mov_b32_e32 v43, v211
	v_lshlrev_b32_e32 v50, 16, v42
	v_and_b32_e32 v42, 0xffff0000, v42
	v_mul_f32_e32 v44, 0xbfb8aa3b, v50
	v_mul_f32_e32 v45, 0xbfb8aa3b, v42
	v_exp_f32_e32 v44, v44
	v_exp_f32_e32 v45, v45
	s_nop 0
	v_pk_add_f32 v[44:45], v[44:45], 1.0 op_sel_hi:[1,0]
	s_nop 0
	v_rcp_f32_e32 v52, v45
	s_nop 0
	v_mul_f32_e32 v54, v42, v52
	v_mov_b32_e32 v45, v54
	v_rcp_f32_e32 v51, v44
	s_nop 0
	v_mul_f32_e32 v53, v50, v51
	v_mov_b32_e32 v44, v53
	v_pk_mul_f32 v[24:25], v[24:25], v[44:45]
	v_lshlrev_b32_e32 v44, 16, v43
	v_and_b32_e32 v45, 0xffff0000, v43
	v_mul_f32_e32 v42, 0xbfb8aa3b, v44
	v_mul_f32_e32 v43, 0xbfb8aa3b, v45
	v_exp_f32_e32 v42, v42
	v_exp_f32_e32 v43, v43
	s_nop 0
	v_pk_add_f32 v[42:43], v[42:43], 1.0 op_sel_hi:[1,0]
	s_nop 0
	v_rcp_f32_e32 v51, v43
	s_nop 0
	v_mul_f32_e32 v53, v45, v51
	v_mov_b32_e32 v43, v53
	v_rcp_f32_e32 v50, v42
	s_nop 0
	v_mul_f32_e32 v52, v44, v50
	v_mov_b32_e32 v42, v52
	v_pk_mul_f32 v[26:27], v[26:27], v[42:43]
	v_pk_mul_f32 v[42:43], v[24:25], v[24:25]
	v_pk_mul_f32 v[44:45], v[26:27], v[26:27]
	v_add_f32_e32 v36, v42, v43
	v_add_f32_e32 v35, v44, v45
	v_add_f32_e32 v35, v36, v35
	v_add_f32_e32 v34, v34, v35
	s_waitcnt vmcnt(4)
	v_mov_b32_e32 v50, v212
	v_mov_b32_e32 v51, v213
	v_lshlrev_b32_e32 v54, 16, v50
	v_and_b32_e32 v50, 0xffff0000, v50
	v_mul_f32_e32 v52, 0xbfb8aa3b, v54
	v_mul_f32_e32 v53, 0xbfb8aa3b, v50
	v_exp_f32_e32 v52, v52
	v_exp_f32_e32 v53, v53
	s_nop 0
	v_pk_add_f32 v[52:53], v[52:53], 1.0 op_sel_hi:[1,0]
	s_nop 0
	v_rcp_f32_e32 v56, v53
	s_nop 0
	v_mul_f32_e32 v58, v50, v56
	v_mov_b32_e32 v53, v58
	v_rcp_f32_e32 v55, v52
	s_nop 0
	v_mul_f32_e32 v57, v54, v55
	v_mov_b32_e32 v52, v57
	v_pk_mul_f32 v[28:29], v[28:29], v[52:53]
	v_lshlrev_b32_e32 v52, 16, v51
	v_and_b32_e32 v53, 0xffff0000, v51
	v_mul_f32_e32 v50, 0xbfb8aa3b, v52
	v_mul_f32_e32 v51, 0xbfb8aa3b, v53
	v_exp_f32_e32 v50, v50
	v_exp_f32_e32 v51, v51
	s_nop 0
	v_pk_add_f32 v[50:51], v[50:51], 1.0 op_sel_hi:[1,0]
	s_nop 0
	v_rcp_f32_e32 v55, v51
	s_nop 0
	v_mul_f32_e32 v57, v53, v55
	v_mov_b32_e32 v51, v57
	v_rcp_f32_e32 v54, v50
	s_nop 0
	v_mul_f32_e32 v56, v52, v54
	v_mov_b32_e32 v50, v56
	v_pk_mul_f32 v[30:31], v[30:31], v[50:51]
	v_pk_mul_f32 v[50:51], v[28:29], v[28:29]
	v_pk_mul_f32 v[52:53], v[30:31], v[30:31]
	v_add_f32_e32 v36, v50, v51
	v_add_f32_e32 v35, v52, v53
	v_add_f32_e32 v35, v36, v35
	v_add_f32_e32 v34, v34, v35
	s_waitcnt vmcnt(3)
	v_mov_b32_e32 v54, v214
	v_mov_b32_e32 v55, v215
	v_lshlrev_b32_e32 v58, 16, v54
	v_and_b32_e32 v54, 0xffff0000, v54
	v_mul_f32_e32 v56, 0xbfb8aa3b, v58
	v_mul_f32_e32 v57, 0xbfb8aa3b, v54
	v_exp_f32_e32 v56, v56
	v_exp_f32_e32 v57, v57
	s_nop 0
	v_pk_add_f32 v[56:57], v[56:57], 1.0 op_sel_hi:[1,0]
	s_nop 0
	v_rcp_f32_e32 v60, v57
	s_nop 0
	v_mul_f32_e32 v62, v54, v60
	v_mov_b32_e32 v57, v62
	v_rcp_f32_e32 v59, v56
	s_nop 0
	v_mul_f32_e32 v61, v58, v59
	v_mov_b32_e32 v56, v61
	v_pk_mul_f32 v[0:1], v[0:1], v[56:57]
	v_lshlrev_b32_e32 v56, 16, v55
	v_and_b32_e32 v57, 0xffff0000, v55
	v_mul_f32_e32 v54, 0xbfb8aa3b, v56
	v_mul_f32_e32 v55, 0xbfb8aa3b, v57
	v_exp_f32_e32 v54, v54
	v_exp_f32_e32 v55, v55
	s_nop 0
	v_pk_add_f32 v[54:55], v[54:55], 1.0 op_sel_hi:[1,0]
	s_nop 0
	v_rcp_f32_e32 v59, v55
	s_nop 0
	v_mul_f32_e32 v61, v57, v59
	v_mov_b32_e32 v55, v61
	v_rcp_f32_e32 v58, v54
	s_nop 0
	v_mul_f32_e32 v60, v56, v58
	v_mov_b32_e32 v54, v60
	v_pk_mul_f32 v[2:3], v[2:3], v[54:55]
	v_pk_mul_f32 v[54:55], v[0:1], v[0:1]
	v_pk_mul_f32 v[56:57], v[2:3], v[2:3]
	v_add_f32_e32 v36, v54, v55
	v_add_f32_e32 v35, v56, v57
	v_add_f32_e32 v35, v36, v35
	v_add_f32_e32 v34, v34, v35
	s_waitcnt vmcnt(2)
; DI_ float bf_lo(unsigned w) { return __uint_as_float(w << 16); }
; DI_ float bf_hi(unsigned w) { return __uint_as_float(w & 0xffff0000u); }
; DI_ float silu_f(float v) { return v / (1.f + __expf(-v)); }
; DI_ void ssd_passC(const bf16_t* xsT, const bf16_t* Btok, const bf16_t* Ctok, const bf16_t* Sc, const float* dt, const float* acum, const float* Dskip, const float* norm_w, bf16_t* Z, unsigned char* lds, int tid, int lane, int wid) {
;     ...
; #pragma unroll
;             for (int pb = 0; pb < 2; ++pb)
; #pragma unroll
;                 for (int q4 = 0; q4 < 4; ++q4) {
;                     const int chn = hh * 64 + 32 * pb + 8 * q4 + 4 * hi;
;                     const u32x2 zw = *(const u32x2*)(Z + (size_t)tg * DI + chn);
;                     const float a0 = yv[it][pb][4 * q4] * silu_f(bf_lo(zw.x)), a1 = yv[it][pb][4 * q4 + 1] * silu_f(bf_hi(zw.x)), a2 = yv[it][pb][4 * q4 + 2] * silu_f(bf_lo(zw.y)), a3 = yv[it][pb][4 * q4 + 3] * silu_f(bf_hi(zw.y));
;                     sq += (a0 * a0 + a1 * a1) + (a2 * a2 + a3 * a3);
;                     yv[it][pb][4 * q4] = a0; yv[it][pb][4 * q4 + 1] = a1; yv[it][pb][4 * q4 + 2] = a2; yv[it][pb][4 * q4 + 3] = a3;
;                 }
;             sq += __shfl_xor(sq, 32);
;             if (hi == 0) ex[hl * 128 + tl] = sq;
	v_mov_b32_e32 v58, v216
	v_mov_b32_e32 v59, v217
	v_lshlrev_b32_e32 v62, 16, v58
	v_and_b32_e32 v58, 0xffff0000, v58
	v_mul_f32_e32 v60, 0xbfb8aa3b, v62
	v_mul_f32_e32 v61, 0xbfb8aa3b, v58
	v_exp_f32_e32 v60, v60
	v_exp_f32_e32 v61, v61
	s_nop 0
	v_pk_add_f32 v[60:61], v[60:61], 1.0 op_sel_hi:[1,0]
	s_nop 0
	v_rcp_f32_e32 v64, v61
	s_nop 0
	v_mul_f32_e32 v66, v58, v64
	v_mov_b32_e32 v61, v66
	v_rcp_f32_e32 v63, v60
	s_nop 0
	v_mul_f32_e32 v65, v62, v63
	v_mov_b32_e32 v60, v65
	v_pk_mul_f32 v[4:5], v[4:5], v[60:61]
	v_lshlrev_b32_e32 v60, 16, v59
	v_and_b32_e32 v61, 0xffff0000, v59
	v_mul_f32_e32 v58, 0xbfb8aa3b, v60
	v_mul_f32_e32 v59, 0xbfb8aa3b, v61
	v_exp_f32_e32 v58, v58
	v_exp_f32_e32 v59, v59
	s_nop 0
	v_pk_add_f32 v[58:59], v[58:59], 1.0 op_sel_hi:[1,0]
	s_nop 0
	v_rcp_f32_e32 v63, v59
	s_nop 0
	v_mul_f32_e32 v65, v61, v63
	v_mov_b32_e32 v59, v65
	v_rcp_f32_e32 v62, v58
	s_nop 0
	v_mul_f32_e32 v64, v60, v62
	v_mov_b32_e32 v58, v64
	v_pk_mul_f32 v[6:7], v[6:7], v[58:59]
	v_pk_mul_f32 v[58:59], v[4:5], v[4:5]
	v_pk_mul_f32 v[60:61], v[6:7], v[6:7]
	v_add_f32_e32 v36, v58, v59
	v_add_f32_e32 v35, v60, v61
	v_add_f32_e32 v35, v36, v35
	v_add_f32_e32 v34, v34, v35
	s_waitcnt vmcnt(1)
	v_mov_b32_e32 v62, v218
	v_mov_b32_e32 v63, v219
	v_lshlrev_b32_e32 v66, 16, v62
	v_and_b32_e32 v62, 0xffff0000, v62
	v_mul_f32_e32 v64, 0xbfb8aa3b, v66
	v_mul_f32_e32 v65, 0xbfb8aa3b, v62
	v_exp_f32_e32 v64, v64
	v_exp_f32_e32 v65, v65
	s_nop 0
	v_pk_add_f32 v[64:65], v[64:65], 1.0 op_sel_hi:[1,0]
	s_nop 0
	v_rcp_f32_e32 v68, v65
	s_nop 0
	v_mul_f32_e32 v70, v62, v68
	v_mov_b32_e32 v65, v70
	v_rcp_f32_e32 v67, v64
	s_nop 0
	v_mul_f32_e32 v69, v66, v67
	v_mov_b32_e32 v64, v69
	v_pk_mul_f32 v[8:9], v[8:9], v[64:65]
	v_lshlrev_b32_e32 v64, 16, v63
	v_and_b32_e32 v65, 0xffff0000, v63
	v_mul_f32_e32 v62, 0xbfb8aa3b, v64
	v_mul_f32_e32 v63, 0xbfb8aa3b, v65
	v_exp_f32_e32 v62, v62
	v_exp_f32_e32 v63, v63
	s_nop 0
	v_pk_add_f32 v[62:63], v[62:63], 1.0 op_sel_hi:[1,0]
	s_nop 0
	v_rcp_f32_e32 v67, v63
	s_nop 0
	v_mul_f32_e32 v69, v65, v67
	v_mov_b32_e32 v63, v69
	v_rcp_f32_e32 v66, v62
	s_nop 0
	v_mul_f32_e32 v68, v64, v66
	v_mov_b32_e32 v65, v68
	s_waitcnt vmcnt(0)
	v_mov_b32_e32 v46, v220
	v_mov_b32_e32 v47, v221
	v_lshlrev_b32_e32 v68, 16, v46
	v_and_b32_e32 v46, 0xffff0000, v46
	v_mul_f32_e32 v66, 0xbfb8aa3b, v68
	v_mul_f32_e32 v67, 0xbfb8aa3b, v46
	v_exp_f32_e32 v66, v66
	v_exp_f32_e32 v67, v67
	v_mov_b32_e32 v62, v65
	v_pk_mul_f32 v[10:11], v[10:11], v[62:63]
	v_pk_mul_f32 v[62:63], v[8:9], v[8:9]
	v_pk_add_f32 v[66:67], v[66:67], 1.0 op_sel_hi:[1,0]
	v_pk_mul_f32 v[64:65], v[10:11], v[10:11]
	v_rcp_f32_e32 v70, v67
	v_add_f32_e32 v35, v64, v65
	v_add_f32_e32 v36, v62, v63
	v_add_f32_e32 v35, v36, v35
	v_mul_f32_e32 v72, v46, v70
	v_mov_b32_e32 v67, v72
	v_rcp_f32_e32 v69, v66
	v_add_f32_e32 v34, v34, v35
	v_mul_f32_e32 v71, v68, v69
	v_mov_b32_e32 v66, v71
	v_pk_mul_f32 v[12:13], v[12:13], v[66:67]
	v_lshlrev_b32_e32 v66, 16, v47
	v_and_b32_e32 v67, 0xffff0000, v47
	v_mul_f32_e32 v46, 0xbfb8aa3b, v66
	v_mul_f32_e32 v47, 0xbfb8aa3b, v67
	v_exp_f32_e32 v46, v46
	v_exp_f32_e32 v47, v47
	s_nop 0
	v_pk_add_f32 v[46:47], v[46:47], 1.0 op_sel_hi:[1,0]
	s_nop 0
	v_rcp_f32_e32 v69, v47
	s_nop 0
	v_mul_f32_e32 v71, v67, v69
	v_mov_b32_e32 v47, v71
	v_rcp_f32_e32 v68, v46
	s_nop 0
	v_mul_f32_e32 v70, v66, v68
	v_mov_b32_e32 v46, v70
	v_pk_mul_f32 v[14:15], v[14:15], v[46:47]
	v_pk_mul_f32 v[46:47], v[12:13], v[12:13]
	v_pk_mul_f32 v[66:67], v[14:15], v[14:15]
	v_add_f32_e32 v36, v46, v47
	v_add_f32_e32 v35, v66, v67
	v_add_f32_e32 v35, v36, v35
	v_add_f32_e32 v34, v34, v35
	ds_bpermute_b32 v35, v139, v34
	s_and_saveexec_b64 s[0:1], s[40:41]
	s_cbranch_execz .LBB0_763
	s_waitcnt lgkmcnt(0)
	v_add_f32_e32 v34, v34, v35
	ds_write_b32 v143, v34
	s_branch .LBB0_763

; __device__ __forceinline__ unsigned cvt_pk_bf16(float lo, float hi) { unsigned r; asm volatile("v_cvt_pk_bf16_f32 %0, %1, %2" : "=v"(r) : "v"(lo), "v"(hi)); return r; }
;     __device__ __forceinline__ void operator()(const f32x4 (&acc)[2][2][4][2], const Unit& u, int wr, int wc, int fr, int fq) const {
;     ...
;         for (int bj = 0; bj < 2; ++bj) { const f32x4 b0 = *(const f32x4*)(bg + col0 + bj * HALF), b1 = *(const f32x4*)(bg + col0 + bj * HALF + 4);
; #pragma unroll
;             for (int ai = 0; ai < 2; ++ai)
; #pragma unroll
;                 for (int m = 0; m < 4; ++m) { const size_t off = (size_t)(u.pm * BM + ai * HALF + wr * 64 + m * 16 + fr) * ldc + col0 + bj * HALF;
;                     const u32x4 xr = *(const u32x4*)(XB + off), pr = *(const u32x4*)(Pp + off); const f32x4 a0 = acc[ai][bj][m][0] + b0, a1 = acc[ai][bj][m][1] + b1;
;                     float x[8], p[8], o[8];
; #pragma unroll
;                     for (int e = 0; e < 4; ++e) { x[2 * e] = __uint_as_float(xr[e] << 16); x[2 * e + 1] = __uint_as_float(xr[e] & 0xffff0000u); p[2 * e] = __uint_as_float(pr[e] << 16); p[2 * e + 1] = __uint_as_float(pr[e] & 0xffff0000u); }
; #pragma unroll
;                     for (int e = 0; e < 4; ++e) { o[e] = x[e] + p[e] / (1.0f + __expf(-a0[e])); o[4 + e] = x[4 + e] + p[4 + e] / (1.0f + __expf(-a1[e])); }
;                     if (OutF) { *(f32x4*)(OutF + off) = (f32x4){o[0], o[1], o[2], o[3]}; *(f32x4*)(OutF + off + 4) = (f32x4){o[4], o[5], o[6], o[7]}; }
;                     else { u32x4 w; w.x = cvt_pk_bf16(o[0], o[1]); w.y = cvt_pk_bf16(o[2], o[3]); w.z = cvt_pk_bf16(o[4], o[5]); w.w = cvt_pk_bf16(o[6], o[7]); *(u32x4*)(XBout + off) = w; } } }
.LBB0_1246:
	v_lshl_or_b32 v158, s26, 8, v178
	v_ashrrev_i32_e32 v159, 31, v158
	v_lshl_add_u64 v[160:161], v[158:159], 2, s[86:87]
	v_lshl_add_u32 v164, s27, 8, v49
	global_load_dwordx4 v[74:77], v[160:161], off offset:16
	global_load_dwordx4 v[82:85], v[160:161], off
	v_ashrrev_i32_e32 v165, 31, v164
	v_lshlrev_b64 v[162:163], 10, v[164:165]
	v_lshl_add_u64 v[166:167], v[162:163], 0, v[158:159]
	v_lshlrev_b64 v[138:139], 1, v[166:167]
	v_lshl_add_u64 v[140:141], s[36:37], 0, v[138:139]
	v_lshl_add_u64 v[138:139], s[60:61], 0, v[138:139]
	global_load_dwordx4 v[142:145], v[140:141], off
	v_readlane_b32 s28, v254, 32
	global_load_dwordx4 v[138:141], v[138:139], off
	v_readlane_b32 s29, v254, 33
	v_readlane_b32 s30, v254, 42
	v_readlane_b32 s31, v254, 43
	s_waitcnt vmcnt(0)
	v_add_f32_e32 v130, v130, v74
	v_add_f32_e32 v134, v134, v82
	v_add_f32_e32 v135, v135, v83
	v_mul_f32_e32 v134, 0xbfb8aa3b, v134
	v_mul_f32_e32 v135, 0xbfb8aa3b, v135
	v_exp_f32_e32 v134, v134
	v_exp_f32_e32 v135, v135
	v_add_f32_e32 v131, v131, v75
	v_lshlrev_b32_e32 v180, 16, v142
	v_and_b32_e32 v181, 0xffff0000, v142
	v_lshlrev_b32_e32 v142, 16, v138
	v_and_b32_e32 v138, 0xffff0000, v138
	v_pk_add_f32 v[134:135], v[134:135], 1.0 op_sel_hi:[1,0]
	v_mul_f32_e32 v130, 0xbfb8aa3b, v130
	v_rcp_f32_e32 v182, v135
	v_mul_f32_e32 v131, 0xbfb8aa3b, v131
	v_exp_f32_e32 v130, v130
	v_exp_f32_e32 v131, v131
	v_mul_f32_e32 v184, v138, v182
	v_mov_b32_e32 v135, v184
	v_rcp_f32_e32 v165, v134
	v_pk_add_f32 v[130:131], v[130:131], 1.0 op_sel_hi:[1,0]
	v_add_f32_e32 v136, v136, v84
	v_mul_f32_e32 v136, 0xbfb8aa3b, v136
	v_mul_f32_e32 v183, v142, v165
	v_mov_b32_e32 v134, v183
	v_lshlrev_b32_e32 v138, 16, v140
	v_and_b32_e32 v140, 0xffff0000, v140
	v_pk_add_f32 v[134:135], v[134:135], v[180:181]
	v_lshlrev_b32_e32 v180, 16, v144
	v_and_b32_e32 v181, 0xffff0000, v144
	v_rcp_f32_e32 v144, v131
	v_add_f32_e32 v132, v132, v76
	v_add_f32_e32 v133, v133, v77
	v_mul_f32_e32 v132, 0xbfb8aa3b, v132
	v_mul_f32_e32 v182, v140, v144
	v_mov_b32_e32 v131, v182
	v_rcp_f32_e32 v142, v130
	v_mul_f32_e32 v133, 0xbfb8aa3b, v133
	v_exp_f32_e32 v132, v132
	v_exp_f32_e32 v133, v133
	v_mul_f32_e32 v165, v138, v142
	v_mov_b32_e32 v130, v165
	v_pk_add_f32 v[130:131], v[130:131], v[180:181]
	v_exp_f32_e32 v180, v136
	v_add_f32_e32 v136, v137, v85
	v_mul_f32_e32 v136, 0xbfb8aa3b, v136
	v_exp_f32_e32 v181, v136
	v_lshlrev_b32_e32 v140, 16, v139
	v_and_b32_e32 v142, 0xffff0000, v139
	v_lshlrev_b32_e32 v136, 16, v143
	v_pk_add_f32 v[138:139], v[180:181], 1.0 op_sel_hi:[1,0]
	v_and_b32_e32 v137, 0xffff0000, v143
	v_rcp_f32_e32 v144, v139
	v_pk_add_f32 v[132:133], v[132:133], 1.0 op_sel_hi:[1,0]
	v_mul_f32_e32 v180, v142, v144
	v_mov_b32_e32 v139, v180
	v_rcp_f32_e32 v143, v138
	s_nop 0
	v_mul_f32_e32 v165, v140, v143
	v_mov_b32_e32 v138, v165
	v_lshlrev_b32_e32 v140, 16, v141
	v_and_b32_e32 v141, 0xffff0000, v141
	v_rcp_f32_e32 v143, v133
	v_pk_add_f32 v[136:137], v[138:139], v[136:137]
	v_lshlrev_b32_e32 v138, 16, v145
	v_and_b32_e32 v139, 0xffff0000, v145
	v_mul_f32_e32 v145, v141, v143
	v_mov_b32_e32 v133, v145
	v_rcp_f32_e32 v142, v132
	s_nop 0
	v_mul_f32_e32 v144, v140, v142
	v_mov_b32_e32 v132, v144
	v_pk_add_f32 v[132:133], v[132:133], v[138:139]
	v_cndmask_b32_e64 v138, 0, 1, s[50:51]
	v_cmp_ne_u32_e64 s[40:41], 1, v138
	s_andn2_b64 vcc, exec, s[50:51]
	v_lshl_add_u64 v[138:139], v[166:167], 2, s[44:45]
	s_cbranch_vccnz .LBB0_1293
	global_store_dwordx4 v[138:139], v[134:137], off
	global_store_dwordx4 v[138:139], v[130:133], off offset:16
	s_cbranch_execnz .LBB0_1249

; __device__ __forceinline__ unsigned cvt_pk_bf16(float lo, float hi) { unsigned r; asm volatile("v_cvt_pk_bf16_f32 %0, %1, %2" : "=v"(r) : "v"(lo), "v"(hi)); return r; }
;     __device__ __forceinline__ void operator()(const f32x4 (&acc)[2][2][4][2], const Unit& u, int wr, int wc, int fr, int fq) const {
;     ...
;                 for (int m = 0; m < 4; ++m) { const size_t off = (size_t)(u.pm * BM + ai * HALF + wr * 64 + m * 16 + fr) * ldc + col0 + bj * HALF;
;                     const u32x4 xr = *(const u32x4*)(XB + off), pr = *(const u32x4*)(Pp + off); const f32x4 a0 = acc[ai][bj][m][0] + b0, a1 = acc[ai][bj][m][1] + b1;
;                     float x[8], p[8], o[8];
; #pragma unroll
;                     for (int e = 0; e < 4; ++e) { x[2 * e] = __uint_as_float(xr[e] << 16); x[2 * e + 1] = __uint_as_float(xr[e] & 0xffff0000u); p[2 * e] = __uint_as_float(pr[e] << 16); p[2 * e + 1] = __uint_as_float(pr[e] & 0xffff0000u); }
; #pragma unroll
;                     for (int e = 0; e < 4; ++e) { o[e] = x[e] + p[e] / (1.0f + __expf(-a0[e])); o[4 + e] = x[4 + e] + p[4 + e] / (1.0f + __expf(-a1[e])); }
;                     if (OutF) { *(f32x4*)(OutF + off) = (f32x4){o[0], o[1], o[2], o[3]}; *(f32x4*)(OutF + off + 4) = (f32x4){o[4], o[5], o[6], o[7]}; }
;                     else { u32x4 w; w.x = cvt_pk_bf16(o[0], o[1]); w.y = cvt_pk_bf16(o[2], o[3]); w.z = cvt_pk_bf16(o[4], o[5]); w.w = cvt_pk_bf16(o[6], o[7]); *(u32x4*)(XBout + off) = w; } } }
.LBB0_1249:
	s_nop 0
	v_or_b32_e32 v130, 16, v164
	v_ashrrev_i32_e32 v131, 31, v130
	v_lshlrev_b64 v[140:141], 10, v[130:131]
	v_lshl_add_u64 v[142:143], v[140:141], 0, v[158:159]
	v_lshlrev_b64 v[130:131], 1, v[142:143]
	v_lshl_add_u64 v[132:133], s[36:37], 0, v[130:131]
	v_lshl_add_u64 v[130:131], s[60:61], 0, v[130:131]
	global_load_dwordx4 v[134:137], v[132:133], off
	v_add_f32_e32 v126, v126, v82
	global_load_dwordx4 v[130:133], v[130:131], off
	v_add_f32_e32 v127, v127, v83
	v_mul_f32_e32 v126, 0xbfb8aa3b, v126
	v_mul_f32_e32 v127, 0xbfb8aa3b, v127
	v_exp_f32_e32 v126, v126
	v_exp_f32_e32 v127, v127
	v_add_f32_e32 v122, v122, v74
	v_add_f32_e32 v123, v123, v75
	v_mul_f32_e32 v122, 0xbfb8aa3b, v122
	v_pk_add_f32 v[126:127], v[126:127], 1.0 op_sel_hi:[1,0]
	v_mul_f32_e32 v123, 0xbfb8aa3b, v123
	v_exp_f32_e32 v122, v122
	v_exp_f32_e32 v123, v123
	v_add_f32_e32 v128, v128, v84
	v_mul_f32_e32 v128, 0xbfb8aa3b, v128
	v_add_f32_e32 v124, v124, v76
	v_pk_add_f32 v[122:123], v[122:123], 1.0 op_sel_hi:[1,0]
	v_add_f32_e32 v125, v125, v77
	v_mul_f32_e32 v124, 0xbfb8aa3b, v124
	v_mul_f32_e32 v125, 0xbfb8aa3b, v125
	v_exp_f32_e32 v124, v124
	v_exp_f32_e32 v125, v125
	s_waitcnt vmcnt(1)
	v_lshlrev_b32_e32 v144, 16, v134
	v_and_b32_e32 v145, 0xffff0000, v134
	s_waitcnt vmcnt(0)
	v_lshlrev_b32_e32 v134, 16, v130
	v_and_b32_e32 v130, 0xffff0000, v130
	v_rcp_f32_e32 v166, v127
	v_pk_add_f32 v[124:125], v[124:125], 1.0 op_sel_hi:[1,0]
	v_mul_f32_e32 v180, v130, v166
	v_mov_b32_e32 v127, v180
	v_rcp_f32_e32 v165, v126
	s_nop 0
	v_mul_f32_e32 v167, v134, v165
	v_mov_b32_e32 v126, v167
	v_lshlrev_b32_e32 v130, 16, v132
	v_and_b32_e32 v132, 0xffff0000, v132
	v_pk_add_f32 v[126:127], v[126:127], v[144:145]
	v_lshlrev_b32_e32 v144, 16, v136
	v_and_b32_e32 v145, 0xffff0000, v136
	v_rcp_f32_e32 v136, v123
	s_nop 0
	v_mul_f32_e32 v166, v132, v136
	v_mov_b32_e32 v123, v166
	v_rcp_f32_e32 v134, v122
	s_nop 0
	v_mul_f32_e32 v165, v130, v134
	v_mov_b32_e32 v122, v165
	v_pk_add_f32 v[122:123], v[122:123], v[144:145]
	v_exp_f32_e32 v144, v128
	v_add_f32_e32 v128, v129, v85
	v_mul_f32_e32 v128, 0xbfb8aa3b, v128
	v_exp_f32_e32 v145, v128
	v_lshlrev_b32_e32 v132, 16, v131
	v_and_b32_e32 v134, 0xffff0000, v131
	v_lshlrev_b32_e32 v128, 16, v135
	v_pk_add_f32 v[130:131], v[144:145], 1.0 op_sel_hi:[1,0]
	v_and_b32_e32 v129, 0xffff0000, v135
	v_rcp_f32_e32 v136, v131
	s_nop 0
	v_mul_f32_e32 v145, v134, v136
	v_mov_b32_e32 v131, v145
	v_rcp_f32_e32 v135, v130
	s_nop 0
	v_mul_f32_e32 v144, v132, v135
	v_mov_b32_e32 v130, v144
	v_lshlrev_b32_e32 v132, 16, v133
	v_and_b32_e32 v133, 0xffff0000, v133
	v_rcp_f32_e32 v135, v125
	v_pk_add_f32 v[128:129], v[130:131], v[128:129]
	v_lshlrev_b32_e32 v130, 16, v137
	v_and_b32_e32 v131, 0xffff0000, v137
	v_mul_f32_e32 v137, v133, v135
	v_mov_b32_e32 v125, v137
	v_rcp_f32_e32 v134, v124
	s_nop 0
	v_mul_f32_e32 v136, v132, v134
	v_mov_b32_e32 v124, v136
	v_pk_add_f32 v[124:125], v[124:125], v[130:131]
	s_and_b64 vcc, exec, s[40:41]
	v_lshl_add_u64 v[130:131], v[142:143], 2, s[44:45]
	s_cbranch_vccnz .LBB0_1294
	global_store_dwordx4 v[130:131], v[126:129], off
	global_store_dwordx4 v[130:131], v[122:125], off offset:16
	s_cbranch_execnz .LBB0_1252

; __device__ __forceinline__ unsigned cvt_pk_bf16(float lo, float hi) { unsigned r; asm volatile("v_cvt_pk_bf16_f32 %0, %1, %2" : "=v"(r) : "v"(lo), "v"(hi)); return r; }
;     __device__ __forceinline__ void operator()(const f32x4 (&acc)[2][2][4][2], const Unit& u, int wr, int wc, int fr, int fq) const {
;     ...
;                 for (int m = 0; m < 4; ++m) { const size_t off = (size_t)(u.pm * BM + ai * HALF + wr * 64 + m * 16 + fr) * ldc + col0 + bj * HALF;
;                     const u32x4 xr = *(const u32x4*)(XB + off), pr = *(const u32x4*)(Pp + off); const f32x4 a0 = acc[ai][bj][m][0] + b0, a1 = acc[ai][bj][m][1] + b1;
;                     float x[8], p[8], o[8];
; #pragma unroll
;                     for (int e = 0; e < 4; ++e) { x[2 * e] = __uint_as_float(xr[e] << 16); x[2 * e + 1] = __uint_as_float(xr[e] & 0xffff0000u); p[2 * e] = __uint_as_float(pr[e] << 16); p[2 * e + 1] = __uint_as_float(pr[e] & 0xffff0000u); }
; #pragma unroll
;                     for (int e = 0; e < 4; ++e) { o[e] = x[e] + p[e] / (1.0f + __expf(-a0[e])); o[4 + e] = x[4 + e] + p[4 + e] / (1.0f + __expf(-a1[e])); }
;                     if (OutF) { *(f32x4*)(OutF + off) = (f32x4){o[0], o[1], o[2], o[3]}; *(f32x4*)(OutF + off + 4) = (f32x4){o[4], o[5], o[6], o[7]}; }
;                     else { u32x4 w; w.x = cvt_pk_bf16(o[0], o[1]); w.y = cvt_pk_bf16(o[2], o[3]); w.z = cvt_pk_bf16(o[4], o[5]); w.w = cvt_pk_bf16(o[6], o[7]); *(u32x4*)(XBout + off) = w; } } }
.LBB0_1252:
	s_nop 0
	v_or_b32_e32 v122, 32, v164
	v_ashrrev_i32_e32 v123, 31, v122
	v_lshlrev_b64 v[132:133], 10, v[122:123]
	v_lshl_add_u64 v[134:135], v[132:133], 0, v[158:159]
	v_lshlrev_b64 v[122:123], 1, v[134:135]
	v_lshl_add_u64 v[124:125], s[36:37], 0, v[122:123]
	v_lshl_add_u64 v[122:123], s[60:61], 0, v[122:123]
	global_load_dwordx4 v[126:129], v[124:125], off
	v_add_f32_e32 v118, v118, v82
	global_load_dwordx4 v[122:125], v[122:123], off
	v_add_f32_e32 v119, v119, v83
	v_mul_f32_e32 v118, 0xbfb8aa3b, v118
	v_mul_f32_e32 v119, 0xbfb8aa3b, v119
	v_exp_f32_e32 v118, v118
	v_exp_f32_e32 v119, v119
	v_add_f32_e32 v114, v114, v74
	v_add_f32_e32 v115, v115, v75
	v_mul_f32_e32 v114, 0xbfb8aa3b, v114
	v_pk_add_f32 v[118:119], v[118:119], 1.0 op_sel_hi:[1,0]
	v_mul_f32_e32 v115, 0xbfb8aa3b, v115
	v_exp_f32_e32 v114, v114
	v_exp_f32_e32 v115, v115
	v_add_f32_e32 v120, v120, v84
	v_mul_f32_e32 v120, 0xbfb8aa3b, v120
	v_add_f32_e32 v116, v116, v76
	v_pk_add_f32 v[114:115], v[114:115], 1.0 op_sel_hi:[1,0]
	v_add_f32_e32 v117, v117, v77
	v_mul_f32_e32 v116, 0xbfb8aa3b, v116
	v_mul_f32_e32 v117, 0xbfb8aa3b, v117
	v_exp_f32_e32 v116, v116
	v_exp_f32_e32 v117, v117
	s_waitcnt vmcnt(1)
	v_lshlrev_b32_e32 v136, 16, v126
	v_and_b32_e32 v137, 0xffff0000, v126
	s_waitcnt vmcnt(0)
	v_lshlrev_b32_e32 v126, 16, v122
	v_and_b32_e32 v122, 0xffff0000, v122
	v_rcp_f32_e32 v143, v119
	v_pk_add_f32 v[116:117], v[116:117], 1.0 op_sel_hi:[1,0]
	v_mul_f32_e32 v145, v122, v143
	v_mov_b32_e32 v119, v145
	v_rcp_f32_e32 v142, v118
	s_nop 0
	v_mul_f32_e32 v144, v126, v142
	v_mov_b32_e32 v118, v144
	v_lshlrev_b32_e32 v122, 16, v124
	v_and_b32_e32 v124, 0xffff0000, v124
	v_pk_add_f32 v[118:119], v[118:119], v[136:137]
	v_lshlrev_b32_e32 v136, 16, v128
	v_and_b32_e32 v137, 0xffff0000, v128
	v_rcp_f32_e32 v128, v115
	s_nop 0
	v_mul_f32_e32 v143, v124, v128
	v_mov_b32_e32 v115, v143
	v_rcp_f32_e32 v126, v114
	s_nop 0
	v_mul_f32_e32 v142, v122, v126
	v_mov_b32_e32 v114, v142
	v_pk_add_f32 v[114:115], v[114:115], v[136:137]
	v_exp_f32_e32 v136, v120
	v_add_f32_e32 v120, v121, v85
	v_mul_f32_e32 v120, 0xbfb8aa3b, v120
	v_exp_f32_e32 v137, v120
	v_lshlrev_b32_e32 v124, 16, v123
	v_and_b32_e32 v126, 0xffff0000, v123
	v_lshlrev_b32_e32 v120, 16, v127
	v_pk_add_f32 v[122:123], v[136:137], 1.0 op_sel_hi:[1,0]
	v_and_b32_e32 v121, 0xffff0000, v127
	v_rcp_f32_e32 v128, v123
	s_nop 0
	v_mul_f32_e32 v137, v126, v128
	v_mov_b32_e32 v123, v137
	v_rcp_f32_e32 v127, v122
	s_nop 0
	v_mul_f32_e32 v136, v124, v127
	v_mov_b32_e32 v122, v136
	v_lshlrev_b32_e32 v124, 16, v125
	v_and_b32_e32 v125, 0xffff0000, v125
	v_rcp_f32_e32 v127, v117
	v_pk_add_f32 v[120:121], v[122:123], v[120:121]
	v_lshlrev_b32_e32 v122, 16, v129
	v_and_b32_e32 v123, 0xffff0000, v129
	v_mul_f32_e32 v129, v125, v127
	v_mov_b32_e32 v117, v129
	v_rcp_f32_e32 v126, v116
	s_nop 0
	v_mul_f32_e32 v128, v124, v126
	v_mov_b32_e32 v116, v128
	v_pk_add_f32 v[116:117], v[116:117], v[122:123]
	s_and_b64 vcc, exec, s[40:41]
	v_lshl_add_u64 v[122:123], v[134:135], 2, s[44:45]
	s_cbranch_vccnz .LBB0_1295
	global_store_dwordx4 v[122:123], v[118:121], off
	global_store_dwordx4 v[122:123], v[114:117], off offset:16
	s_cbranch_execnz .LBB0_1255

; __device__ __forceinline__ unsigned cvt_pk_bf16(float lo, float hi) { unsigned r; asm volatile("v_cvt_pk_bf16_f32 %0, %1, %2" : "=v"(r) : "v"(lo), "v"(hi)); return r; }
;     __device__ __forceinline__ void operator()(const f32x4 (&acc)[2][2][4][2], const Unit& u, int wr, int wc, int fr, int fq) const {
;     ...
;                 for (int m = 0; m < 4; ++m) { const size_t off = (size_t)(u.pm * BM + ai * HALF + wr * 64 + m * 16 + fr) * ldc + col0 + bj * HALF;
;                     const u32x4 xr = *(const u32x4*)(XB + off), pr = *(const u32x4*)(Pp + off); const f32x4 a0 = acc[ai][bj][m][0] + b0, a1 = acc[ai][bj][m][1] + b1;
;                     float x[8], p[8], o[8];
; #pragma unroll
;                     for (int e = 0; e < 4; ++e) { x[2 * e] = __uint_as_float(xr[e] << 16); x[2 * e + 1] = __uint_as_float(xr[e] & 0xffff0000u); p[2 * e] = __uint_as_float(pr[e] << 16); p[2 * e + 1] = __uint_as_float(pr[e] & 0xffff0000u); }
; #pragma unroll
;                     for (int e = 0; e < 4; ++e) { o[e] = x[e] + p[e] / (1.0f + __expf(-a0[e])); o[4 + e] = x[4 + e] + p[4 + e] / (1.0f + __expf(-a1[e])); }
;                     if (OutF) { *(f32x4*)(OutF + off) = (f32x4){o[0], o[1], o[2], o[3]}; *(f32x4*)(OutF + off + 4) = (f32x4){o[4], o[5], o[6], o[7]}; }
;                     else { u32x4 w; w.x = cvt_pk_bf16(o[0], o[1]); w.y = cvt_pk_bf16(o[2], o[3]); w.z = cvt_pk_bf16(o[4], o[5]); w.w = cvt_pk_bf16(o[6], o[7]); *(u32x4*)(XBout + off) = w; } } }
.LBB0_1255:
	s_nop 0
	v_or_b32_e32 v114, 48, v164
	v_ashrrev_i32_e32 v115, 31, v114
	v_lshlrev_b64 v[124:125], 10, v[114:115]
	v_lshl_add_u64 v[126:127], v[124:125], 0, v[158:159]
	v_lshlrev_b64 v[114:115], 1, v[126:127]
	v_lshl_add_u64 v[116:117], s[36:37], 0, v[114:115]
	v_lshl_add_u64 v[114:115], s[60:61], 0, v[114:115]
	global_load_dwordx4 v[118:121], v[116:117], off
	v_add_f32_e32 v110, v110, v82
	global_load_dwordx4 v[114:117], v[114:115], off
	v_add_f32_e32 v111, v111, v83
	v_mul_f32_e32 v110, 0xbfb8aa3b, v110
	v_mul_f32_e32 v111, 0xbfb8aa3b, v111
	v_exp_f32_e32 v110, v110
	v_exp_f32_e32 v111, v111
	v_add_f32_e32 v106, v106, v74
	v_add_f32_e32 v107, v107, v75
	v_mul_f32_e32 v106, 0xbfb8aa3b, v106
	v_pk_add_f32 v[110:111], v[110:111], 1.0 op_sel_hi:[1,0]
	v_mul_f32_e32 v107, 0xbfb8aa3b, v107
	v_exp_f32_e32 v106, v106
	v_exp_f32_e32 v107, v107
	v_add_f32_e32 v112, v112, v84
	v_mul_f32_e32 v112, 0xbfb8aa3b, v112
	v_add_f32_e32 v108, v108, v76
	v_pk_add_f32 v[106:107], v[106:107], 1.0 op_sel_hi:[1,0]
	v_add_f32_e32 v109, v109, v77
	v_mul_f32_e32 v108, 0xbfb8aa3b, v108
	v_mul_f32_e32 v109, 0xbfb8aa3b, v109
	v_exp_f32_e32 v108, v108
	v_exp_f32_e32 v109, v109
	s_waitcnt vmcnt(1)
	v_lshlrev_b32_e32 v128, 16, v118
	v_and_b32_e32 v129, 0xffff0000, v118
	s_waitcnt vmcnt(0)
	v_lshlrev_b32_e32 v118, 16, v114
	v_and_b32_e32 v114, 0xffff0000, v114
	v_rcp_f32_e32 v135, v111
	v_pk_add_f32 v[108:109], v[108:109], 1.0 op_sel_hi:[1,0]
	v_mul_f32_e32 v137, v114, v135
	v_mov_b32_e32 v111, v137
	v_rcp_f32_e32 v134, v110
	s_nop 0
	v_mul_f32_e32 v136, v118, v134
	v_mov_b32_e32 v110, v136
	v_lshlrev_b32_e32 v114, 16, v116
	v_and_b32_e32 v116, 0xffff0000, v116
	v_pk_add_f32 v[110:111], v[110:111], v[128:129]
	v_lshlrev_b32_e32 v128, 16, v120
	v_and_b32_e32 v129, 0xffff0000, v120
	v_rcp_f32_e32 v120, v107
	s_nop 0
	v_mul_f32_e32 v135, v116, v120
	v_mov_b32_e32 v107, v135
	v_rcp_f32_e32 v118, v106
	s_nop 0
	v_mul_f32_e32 v134, v114, v118
	v_mov_b32_e32 v106, v134
	v_pk_add_f32 v[106:107], v[106:107], v[128:129]
	v_exp_f32_e32 v128, v112
	v_add_f32_e32 v112, v113, v85
	v_mul_f32_e32 v112, 0xbfb8aa3b, v112
	v_exp_f32_e32 v129, v112
	v_lshlrev_b32_e32 v116, 16, v115
	v_and_b32_e32 v118, 0xffff0000, v115
	v_lshlrev_b32_e32 v112, 16, v119
	v_pk_add_f32 v[114:115], v[128:129], 1.0 op_sel_hi:[1,0]
	v_and_b32_e32 v113, 0xffff0000, v119
	v_rcp_f32_e32 v120, v115
	s_nop 0
	v_mul_f32_e32 v129, v118, v120
	v_mov_b32_e32 v115, v129
	v_rcp_f32_e32 v119, v114
	s_nop 0
	v_mul_f32_e32 v128, v116, v119
	v_mov_b32_e32 v114, v128
	v_lshlrev_b32_e32 v116, 16, v117
	v_and_b32_e32 v117, 0xffff0000, v117
	v_rcp_f32_e32 v119, v109
	v_pk_add_f32 v[112:113], v[114:115], v[112:113]
	v_lshlrev_b32_e32 v114, 16, v121
	v_and_b32_e32 v115, 0xffff0000, v121
	v_mul_f32_e32 v121, v117, v119
	v_mov_b32_e32 v109, v121
	v_rcp_f32_e32 v118, v108
	s_nop 0
	v_mul_f32_e32 v120, v116, v118
	v_mov_b32_e32 v108, v120
	v_pk_add_f32 v[108:109], v[108:109], v[114:115]
	s_and_b64 vcc, exec, s[40:41]
	v_lshl_add_u64 v[114:115], v[126:127], 2, s[44:45]
	s_cbranch_vccnz .LBB0_1296
	global_store_dwordx4 v[114:115], v[110:113], off
	global_store_dwordx4 v[114:115], v[106:109], off offset:16
	s_cbranch_execnz .LBB0_1258

; __device__ __forceinline__ unsigned cvt_pk_bf16(float lo, float hi) { unsigned r; asm volatile("v_cvt_pk_bf16_f32 %0, %1, %2" : "=v"(r) : "v"(lo), "v"(hi)); return r; }
;     __device__ __forceinline__ void operator()(const f32x4 (&acc)[2][2][4][2], const Unit& u, int wr, int wc, int fr, int fq) const {
;     ...
;                 for (int m = 0; m < 4; ++m) { const size_t off = (size_t)(u.pm * BM + ai * HALF + wr * 64 + m * 16 + fr) * ldc + col0 + bj * HALF;
;                     const u32x4 xr = *(const u32x4*)(XB + off), pr = *(const u32x4*)(Pp + off); const f32x4 a0 = acc[ai][bj][m][0] + b0, a1 = acc[ai][bj][m][1] + b1;
;                     float x[8], p[8], o[8];
; #pragma unroll
;                     for (int e = 0; e < 4; ++e) { x[2 * e] = __uint_as_float(xr[e] << 16); x[2 * e + 1] = __uint_as_float(xr[e] & 0xffff0000u); p[2 * e] = __uint_as_float(pr[e] << 16); p[2 * e + 1] = __uint_as_float(pr[e] & 0xffff0000u); }
; #pragma unroll
;                     for (int e = 0; e < 4; ++e) { o[e] = x[e] + p[e] / (1.0f + __expf(-a0[e])); o[4 + e] = x[4 + e] + p[4 + e] / (1.0f + __expf(-a1[e])); }
;                     if (OutF) { *(f32x4*)(OutF + off) = (f32x4){o[0], o[1], o[2], o[3]}; *(f32x4*)(OutF + off + 4) = (f32x4){o[4], o[5], o[6], o[7]}; }
;                     else { u32x4 w; w.x = cvt_pk_bf16(o[0], o[1]); w.y = cvt_pk_bf16(o[2], o[3]); w.z = cvt_pk_bf16(o[4], o[5]); w.w = cvt_pk_bf16(o[6], o[7]); *(u32x4*)(XBout + off) = w; } } }
.LBB0_1258:
	s_nop 0
	v_add_u32_e32 v106, 0x80, v164
	v_ashrrev_i32_e32 v107, 31, v106
	v_lshlrev_b64 v[116:117], 10, v[106:107]
	v_lshl_add_u64 v[118:119], v[116:117], 0, v[158:159]
	v_lshlrev_b64 v[106:107], 1, v[118:119]
	v_lshl_add_u64 v[108:109], s[36:37], 0, v[106:107]
	v_lshl_add_u64 v[106:107], s[60:61], 0, v[106:107]
	global_load_dwordx4 v[110:113], v[108:109], off
	v_add_f32_e32 v102, v102, v82
	global_load_dwordx4 v[106:109], v[106:107], off
	v_add_f32_e32 v103, v103, v83
	v_mul_f32_e32 v102, 0xbfb8aa3b, v102
	v_mul_f32_e32 v103, 0xbfb8aa3b, v103
	v_exp_f32_e32 v102, v102
	v_exp_f32_e32 v103, v103
	v_add_f32_e32 v98, v98, v74
	v_add_f32_e32 v99, v99, v75
	v_mul_f32_e32 v98, 0xbfb8aa3b, v98
	v_pk_add_f32 v[102:103], v[102:103], 1.0 op_sel_hi:[1,0]
	v_mul_f32_e32 v99, 0xbfb8aa3b, v99
	v_exp_f32_e32 v98, v98
	v_exp_f32_e32 v99, v99
	v_add_f32_e32 v104, v104, v84
	v_mul_f32_e32 v104, 0xbfb8aa3b, v104
	v_add_f32_e32 v100, v100, v76
	v_pk_add_f32 v[98:99], v[98:99], 1.0 op_sel_hi:[1,0]
	v_add_f32_e32 v101, v101, v77
	v_mul_f32_e32 v100, 0xbfb8aa3b, v100
	v_mul_f32_e32 v101, 0xbfb8aa3b, v101
	v_exp_f32_e32 v100, v100
	v_exp_f32_e32 v101, v101
	s_waitcnt vmcnt(1)
	v_lshlrev_b32_e32 v120, 16, v110
	v_and_b32_e32 v121, 0xffff0000, v110
	s_waitcnt vmcnt(0)
	v_lshlrev_b32_e32 v110, 16, v106
	v_and_b32_e32 v106, 0xffff0000, v106
	v_rcp_f32_e32 v127, v103
	v_pk_add_f32 v[100:101], v[100:101], 1.0 op_sel_hi:[1,0]
	v_mul_f32_e32 v129, v106, v127
	v_mov_b32_e32 v103, v129
	v_rcp_f32_e32 v126, v102
	s_nop 0
	v_mul_f32_e32 v128, v110, v126
	v_mov_b32_e32 v102, v128
	v_lshlrev_b32_e32 v106, 16, v108
	v_and_b32_e32 v108, 0xffff0000, v108
	v_pk_add_f32 v[102:103], v[102:103], v[120:121]
	v_lshlrev_b32_e32 v120, 16, v112
	v_and_b32_e32 v121, 0xffff0000, v112
	v_rcp_f32_e32 v112, v99
	s_nop 0
	v_mul_f32_e32 v127, v108, v112
	v_mov_b32_e32 v99, v127
	v_rcp_f32_e32 v110, v98
	s_nop 0
	v_mul_f32_e32 v126, v106, v110
	v_mov_b32_e32 v98, v126
	v_pk_add_f32 v[98:99], v[98:99], v[120:121]
	v_exp_f32_e32 v120, v104
	v_add_f32_e32 v104, v105, v85
	v_mul_f32_e32 v104, 0xbfb8aa3b, v104
	v_exp_f32_e32 v121, v104
	v_lshlrev_b32_e32 v108, 16, v107
	v_and_b32_e32 v110, 0xffff0000, v107
	v_lshlrev_b32_e32 v104, 16, v111
	v_pk_add_f32 v[106:107], v[120:121], 1.0 op_sel_hi:[1,0]
	v_and_b32_e32 v105, 0xffff0000, v111
	v_rcp_f32_e32 v112, v107
	s_nop 0
	v_mul_f32_e32 v121, v110, v112
	v_mov_b32_e32 v107, v121
	v_rcp_f32_e32 v111, v106
	s_nop 0
	v_mul_f32_e32 v120, v108, v111
	v_mov_b32_e32 v106, v120
	v_lshlrev_b32_e32 v108, 16, v109
	v_and_b32_e32 v109, 0xffff0000, v109
	v_rcp_f32_e32 v111, v101
	v_pk_add_f32 v[104:105], v[106:107], v[104:105]
	v_lshlrev_b32_e32 v106, 16, v113
	v_and_b32_e32 v107, 0xffff0000, v113
	v_mul_f32_e32 v113, v109, v111
	v_mov_b32_e32 v101, v113
	v_rcp_f32_e32 v110, v100
	s_nop 0
	v_mul_f32_e32 v112, v108, v110
	v_mov_b32_e32 v100, v112
	v_pk_add_f32 v[100:101], v[100:101], v[106:107]
	s_and_b64 vcc, exec, s[40:41]
	v_lshl_add_u64 v[106:107], v[118:119], 2, s[44:45]
	s_cbranch_vccnz .LBB0_1297
	global_store_dwordx4 v[106:107], v[102:105], off
	global_store_dwordx4 v[106:107], v[98:101], off offset:16
	s_cbranch_execnz .LBB0_1261

; __device__ __forceinline__ unsigned cvt_pk_bf16(float lo, float hi) { unsigned r; asm volatile("v_cvt_pk_bf16_f32 %0, %1, %2" : "=v"(r) : "v"(lo), "v"(hi)); return r; }
;     __device__ __forceinline__ void operator()(const f32x4 (&acc)[2][2][4][2], const Unit& u, int wr, int wc, int fr, int fq) const {
;     ...
;                 for (int m = 0; m < 4; ++m) { const size_t off = (size_t)(u.pm * BM + ai * HALF + wr * 64 + m * 16 + fr) * ldc + col0 + bj * HALF;
;                     const u32x4 xr = *(const u32x4*)(XB + off), pr = *(const u32x4*)(Pp + off); const f32x4 a0 = acc[ai][bj][m][0] + b0, a1 = acc[ai][bj][m][1] + b1;
;                     float x[8], p[8], o[8];
; #pragma unroll
;                     for (int e = 0; e < 4; ++e) { x[2 * e] = __uint_as_float(xr[e] << 16); x[2 * e + 1] = __uint_as_float(xr[e] & 0xffff0000u); p[2 * e] = __uint_as_float(pr[e] << 16); p[2 * e + 1] = __uint_as_float(pr[e] & 0xffff0000u); }
; #pragma unroll
;                     for (int e = 0; e < 4; ++e) { o[e] = x[e] + p[e] / (1.0f + __expf(-a0[e])); o[4 + e] = x[4 + e] + p[4 + e] / (1.0f + __expf(-a1[e])); }
;                     if (OutF) { *(f32x4*)(OutF + off) = (f32x4){o[0], o[1], o[2], o[3]}; *(f32x4*)(OutF + off + 4) = (f32x4){o[4], o[5], o[6], o[7]}; }
;                     else { u32x4 w; w.x = cvt_pk_bf16(o[0], o[1]); w.y = cvt_pk_bf16(o[2], o[3]); w.z = cvt_pk_bf16(o[4], o[5]); w.w = cvt_pk_bf16(o[6], o[7]); *(u32x4*)(XBout + off) = w; } } }
.LBB0_1261:
	s_nop 0
	v_add_u32_e32 v98, 0x90, v164
	v_ashrrev_i32_e32 v99, 31, v98
	v_lshlrev_b64 v[108:109], 10, v[98:99]
	v_lshl_add_u64 v[110:111], v[108:109], 0, v[158:159]
	v_lshlrev_b64 v[98:99], 1, v[110:111]
	v_lshl_add_u64 v[100:101], s[36:37], 0, v[98:99]
	v_lshl_add_u64 v[98:99], s[60:61], 0, v[98:99]
	global_load_dwordx4 v[102:105], v[100:101], off
	v_add_f32_e32 v94, v94, v82
	global_load_dwordx4 v[98:101], v[98:99], off
	v_add_f32_e32 v95, v95, v83
	v_mul_f32_e32 v94, 0xbfb8aa3b, v94
	v_mul_f32_e32 v95, 0xbfb8aa3b, v95
	v_exp_f32_e32 v94, v94
	v_exp_f32_e32 v95, v95
	v_add_f32_e32 v90, v90, v74
	v_add_f32_e32 v91, v91, v75
	v_mul_f32_e32 v90, 0xbfb8aa3b, v90
	v_pk_add_f32 v[94:95], v[94:95], 1.0 op_sel_hi:[1,0]
	v_mul_f32_e32 v91, 0xbfb8aa3b, v91
	v_exp_f32_e32 v90, v90
	v_exp_f32_e32 v91, v91
	v_add_f32_e32 v96, v96, v84
	v_mul_f32_e32 v96, 0xbfb8aa3b, v96
	v_add_f32_e32 v92, v92, v76
	v_pk_add_f32 v[90:91], v[90:91], 1.0 op_sel_hi:[1,0]
	v_add_f32_e32 v93, v93, v77
	v_mul_f32_e32 v92, 0xbfb8aa3b, v92
	v_mul_f32_e32 v93, 0xbfb8aa3b, v93
	v_exp_f32_e32 v92, v92
	v_exp_f32_e32 v93, v93
	s_waitcnt vmcnt(1)
	v_lshlrev_b32_e32 v112, 16, v102
	v_and_b32_e32 v113, 0xffff0000, v102
	s_waitcnt vmcnt(0)
	v_lshlrev_b32_e32 v102, 16, v98
	v_and_b32_e32 v98, 0xffff0000, v98
	v_rcp_f32_e32 v119, v95
	v_pk_add_f32 v[92:93], v[92:93], 1.0 op_sel_hi:[1,0]
	v_mul_f32_e32 v121, v98, v119
	v_mov_b32_e32 v95, v121
	v_rcp_f32_e32 v118, v94
	s_nop 0
	v_mul_f32_e32 v120, v102, v118
	v_mov_b32_e32 v94, v120
	v_lshlrev_b32_e32 v98, 16, v100
	v_and_b32_e32 v100, 0xffff0000, v100
	v_pk_add_f32 v[94:95], v[94:95], v[112:113]
	v_lshlrev_b32_e32 v112, 16, v104
	v_and_b32_e32 v113, 0xffff0000, v104
	v_rcp_f32_e32 v104, v91
	s_nop 0
	v_mul_f32_e32 v119, v100, v104
	v_mov_b32_e32 v91, v119
	v_rcp_f32_e32 v102, v90
	s_nop 0
	v_mul_f32_e32 v118, v98, v102
	v_mov_b32_e32 v90, v118
	v_pk_add_f32 v[90:91], v[90:91], v[112:113]
	v_exp_f32_e32 v112, v96
	v_add_f32_e32 v96, v97, v85
	v_mul_f32_e32 v96, 0xbfb8aa3b, v96
	v_exp_f32_e32 v113, v96
	v_lshlrev_b32_e32 v100, 16, v99
	v_and_b32_e32 v102, 0xffff0000, v99
	v_lshlrev_b32_e32 v96, 16, v103
	v_pk_add_f32 v[98:99], v[112:113], 1.0 op_sel_hi:[1,0]
	v_and_b32_e32 v97, 0xffff0000, v103
	v_rcp_f32_e32 v104, v99
	s_nop 0
	v_mul_f32_e32 v113, v102, v104
	v_mov_b32_e32 v99, v113
	v_rcp_f32_e32 v103, v98
	s_nop 0
	v_mul_f32_e32 v112, v100, v103
	v_mov_b32_e32 v98, v112
	v_lshlrev_b32_e32 v100, 16, v101
	v_and_b32_e32 v101, 0xffff0000, v101
	v_rcp_f32_e32 v103, v93
	v_pk_add_f32 v[96:97], v[98:99], v[96:97]
	v_lshlrev_b32_e32 v98, 16, v105
	v_and_b32_e32 v99, 0xffff0000, v105
	v_mul_f32_e32 v105, v101, v103
	v_mov_b32_e32 v93, v105
	v_rcp_f32_e32 v102, v92
	s_nop 0
	v_mul_f32_e32 v104, v100, v102
	v_mov_b32_e32 v92, v104
	v_pk_add_f32 v[92:93], v[92:93], v[98:99]
	s_and_b64 vcc, exec, s[40:41]
	v_lshl_add_u64 v[98:99], v[110:111], 2, s[44:45]
	s_cbranch_vccnz .LBB0_1298
	global_store_dwordx4 v[98:99], v[94:97], off
	global_store_dwordx4 v[98:99], v[90:93], off offset:16
	s_cbranch_execnz .LBB0_1264

; __device__ __forceinline__ unsigned cvt_pk_bf16(float lo, float hi) { unsigned r; asm volatile("v_cvt_pk_bf16_f32 %0, %1, %2" : "=v"(r) : "v"(lo), "v"(hi)); return r; }
;     __device__ __forceinline__ void operator()(const f32x4 (&acc)[2][2][4][2], const Unit& u, int wr, int wc, int fr, int fq) const {
;     ...
;                 for (int m = 0; m < 4; ++m) { const size_t off = (size_t)(u.pm * BM + ai * HALF + wr * 64 + m * 16 + fr) * ldc + col0 + bj * HALF;
;                     const u32x4 xr = *(const u32x4*)(XB + off), pr = *(const u32x4*)(Pp + off); const f32x4 a0 = acc[ai][bj][m][0] + b0, a1 = acc[ai][bj][m][1] + b1;
;                     float x[8], p[8], o[8];
; #pragma unroll
;                     for (int e = 0; e < 4; ++e) { x[2 * e] = __uint_as_float(xr[e] << 16); x[2 * e + 1] = __uint_as_float(xr[e] & 0xffff0000u); p[2 * e] = __uint_as_float(pr[e] << 16); p[2 * e + 1] = __uint_as_float(pr[e] & 0xffff0000u); }
; #pragma unroll
;                     for (int e = 0; e < 4; ++e) { o[e] = x[e] + p[e] / (1.0f + __expf(-a0[e])); o[4 + e] = x[4 + e] + p[4 + e] / (1.0f + __expf(-a1[e])); }
;                     if (OutF) { *(f32x4*)(OutF + off) = (f32x4){o[0], o[1], o[2], o[3]}; *(f32x4*)(OutF + off + 4) = (f32x4){o[4], o[5], o[6], o[7]}; }
;                     else { u32x4 w; w.x = cvt_pk_bf16(o[0], o[1]); w.y = cvt_pk_bf16(o[2], o[3]); w.z = cvt_pk_bf16(o[4], o[5]); w.w = cvt_pk_bf16(o[6], o[7]); *(u32x4*)(XBout + off) = w; } } }
.LBB0_1264:
	s_nop 0
	v_add_u32_e32 v90, 0xa0, v164
	v_ashrrev_i32_e32 v91, 31, v90
	v_lshlrev_b64 v[100:101], 10, v[90:91]
	v_lshl_add_u64 v[102:103], v[100:101], 0, v[158:159]
	v_lshlrev_b64 v[90:91], 1, v[102:103]
	v_lshl_add_u64 v[92:93], s[36:37], 0, v[90:91]
	v_lshl_add_u64 v[90:91], s[60:61], 0, v[90:91]
	global_load_dwordx4 v[94:97], v[92:93], off
	v_add_f32_e32 v86, v86, v82
	global_load_dwordx4 v[90:93], v[90:91], off
	v_add_f32_e32 v87, v87, v83
	v_mul_f32_e32 v86, 0xbfb8aa3b, v86
	v_mul_f32_e32 v87, 0xbfb8aa3b, v87
	v_exp_f32_e32 v86, v86
	v_exp_f32_e32 v87, v87
	v_add_f32_e32 v78, v78, v74
	v_add_f32_e32 v79, v79, v75
	v_mul_f32_e32 v78, 0xbfb8aa3b, v78
	v_pk_add_f32 v[86:87], v[86:87], 1.0 op_sel_hi:[1,0]
	v_mul_f32_e32 v79, 0xbfb8aa3b, v79
	v_exp_f32_e32 v78, v78
	v_exp_f32_e32 v79, v79
	v_add_f32_e32 v88, v88, v84
	v_mul_f32_e32 v88, 0xbfb8aa3b, v88
	v_add_f32_e32 v80, v80, v76
	v_pk_add_f32 v[78:79], v[78:79], 1.0 op_sel_hi:[1,0]
	v_add_f32_e32 v81, v81, v77
	v_mul_f32_e32 v80, 0xbfb8aa3b, v80
	v_mul_f32_e32 v81, 0xbfb8aa3b, v81
	v_exp_f32_e32 v80, v80
	v_exp_f32_e32 v81, v81
	s_waitcnt vmcnt(1)
	v_lshlrev_b32_e32 v104, 16, v94
	v_and_b32_e32 v105, 0xffff0000, v94
	s_waitcnt vmcnt(0)
	v_lshlrev_b32_e32 v94, 16, v90
	v_and_b32_e32 v90, 0xffff0000, v90
	v_rcp_f32_e32 v111, v87
	v_pk_add_f32 v[80:81], v[80:81], 1.0 op_sel_hi:[1,0]
	v_mul_f32_e32 v113, v90, v111
	v_mov_b32_e32 v87, v113
	v_rcp_f32_e32 v110, v86
	s_nop 0
	v_mul_f32_e32 v112, v94, v110
	v_mov_b32_e32 v86, v112
	v_lshlrev_b32_e32 v90, 16, v92
	v_and_b32_e32 v92, 0xffff0000, v92
	v_pk_add_f32 v[86:87], v[86:87], v[104:105]
	v_lshlrev_b32_e32 v104, 16, v96
	v_and_b32_e32 v105, 0xffff0000, v96
	v_rcp_f32_e32 v96, v79
	s_nop 0
	v_mul_f32_e32 v111, v92, v96
	v_mov_b32_e32 v79, v111
	v_rcp_f32_e32 v94, v78
	s_nop 0
	v_mul_f32_e32 v110, v90, v94
	v_mov_b32_e32 v78, v110
	v_pk_add_f32 v[78:79], v[78:79], v[104:105]
	v_exp_f32_e32 v104, v88
	v_add_f32_e32 v88, v89, v85
	v_mul_f32_e32 v88, 0xbfb8aa3b, v88
	v_exp_f32_e32 v105, v88
	v_lshlrev_b32_e32 v92, 16, v91
	v_and_b32_e32 v94, 0xffff0000, v91
	v_lshlrev_b32_e32 v88, 16, v95
	v_pk_add_f32 v[90:91], v[104:105], 1.0 op_sel_hi:[1,0]
	v_and_b32_e32 v89, 0xffff0000, v95
	v_rcp_f32_e32 v96, v91
	s_nop 0
	v_mul_f32_e32 v105, v94, v96
	v_mov_b32_e32 v91, v105
	v_rcp_f32_e32 v95, v90
	s_nop 0
	v_mul_f32_e32 v104, v92, v95
	v_mov_b32_e32 v90, v104
	v_lshlrev_b32_e32 v92, 16, v93
	v_and_b32_e32 v93, 0xffff0000, v93
	v_rcp_f32_e32 v95, v81
	v_pk_add_f32 v[88:89], v[90:91], v[88:89]
	v_lshlrev_b32_e32 v90, 16, v97
	v_and_b32_e32 v91, 0xffff0000, v97
	v_mul_f32_e32 v97, v93, v95
	v_mov_b32_e32 v81, v97
	v_rcp_f32_e32 v94, v80
	s_nop 0
	v_mul_f32_e32 v96, v92, v94
	v_mov_b32_e32 v80, v96
	v_pk_add_f32 v[80:81], v[80:81], v[90:91]
	s_and_b64 vcc, exec, s[40:41]
	v_lshl_add_u64 v[90:91], v[102:103], 2, s[44:45]
	s_cbranch_vccnz .LBB0_1299
	global_store_dwordx4 v[90:91], v[86:89], off
	global_store_dwordx4 v[90:91], v[78:81], off offset:16
	s_cbranch_execnz .LBB0_1267

; __device__ __forceinline__ unsigned cvt_pk_bf16(float lo, float hi) { unsigned r; asm volatile("v_cvt_pk_bf16_f32 %0, %1, %2" : "=v"(r) : "v"(lo), "v"(hi)); return r; }
;     __device__ __forceinline__ void operator()(const f32x4 (&acc)[2][2][4][2], const Unit& u, int wr, int wc, int fr, int fq) const {
;     ...
;                 for (int m = 0; m < 4; ++m) { const size_t off = (size_t)(u.pm * BM + ai * HALF + wr * 64 + m * 16 + fr) * ldc + col0 + bj * HALF;
;                     const u32x4 xr = *(const u32x4*)(XB + off), pr = *(const u32x4*)(Pp + off); const f32x4 a0 = acc[ai][bj][m][0] + b0, a1 = acc[ai][bj][m][1] + b1;
;                     float x[8], p[8], o[8];
; #pragma unroll
;                     for (int e = 0; e < 4; ++e) { x[2 * e] = __uint_as_float(xr[e] << 16); x[2 * e + 1] = __uint_as_float(xr[e] & 0xffff0000u); p[2 * e] = __uint_as_float(pr[e] << 16); p[2 * e + 1] = __uint_as_float(pr[e] & 0xffff0000u); }
; #pragma unroll
;                     for (int e = 0; e < 4; ++e) { o[e] = x[e] + p[e] / (1.0f + __expf(-a0[e])); o[4 + e] = x[4 + e] + p[4 + e] / (1.0f + __expf(-a1[e])); }
;                     if (OutF) { *(f32x4*)(OutF + off) = (f32x4){o[0], o[1], o[2], o[3]}; *(f32x4*)(OutF + off + 4) = (f32x4){o[4], o[5], o[6], o[7]}; }
;                     else { u32x4 w; w.x = cvt_pk_bf16(o[0], o[1]); w.y = cvt_pk_bf16(o[2], o[3]); w.z = cvt_pk_bf16(o[4], o[5]); w.w = cvt_pk_bf16(o[6], o[7]); *(u32x4*)(XBout + off) = w; } } }
.LBB0_1267:
	s_nop 0
	v_add_u32_e32 v78, 0xb0, v164
	v_ashrrev_i32_e32 v79, 31, v78
	v_lshlrev_b64 v[92:93], 10, v[78:79]
	v_lshl_add_u64 v[94:95], v[92:93], 0, v[158:159]
	v_lshlrev_b64 v[78:79], 1, v[94:95]
	v_lshl_add_u64 v[80:81], s[36:37], 0, v[78:79]
	v_lshl_add_u64 v[78:79], s[60:61], 0, v[78:79]
	global_load_dwordx4 v[86:89], v[80:81], off
	v_add_f32_e32 v70, v70, v82
	global_load_dwordx4 v[78:81], v[78:79], off
	v_add_f32_e32 v71, v71, v83
	v_mul_f32_e32 v70, 0xbfb8aa3b, v70
	v_mul_f32_e32 v71, 0xbfb8aa3b, v71
	v_exp_f32_e32 v70, v70
	v_exp_f32_e32 v71, v71
	v_add_f32_e32 v66, v66, v74
	v_add_f32_e32 v67, v67, v75
	v_mul_f32_e32 v66, 0xbfb8aa3b, v66
	v_pk_add_f32 v[70:71], v[70:71], 1.0 op_sel_hi:[1,0]
	v_mul_f32_e32 v67, 0xbfb8aa3b, v67
	v_exp_f32_e32 v66, v66
	v_exp_f32_e32 v67, v67
	v_add_f32_e32 v72, v72, v84
	v_mul_f32_e32 v72, 0xbfb8aa3b, v72
	v_add_f32_e32 v68, v68, v76
	v_pk_add_f32 v[66:67], v[66:67], 1.0 op_sel_hi:[1,0]
	v_add_f32_e32 v69, v69, v77
	v_mul_f32_e32 v68, 0xbfb8aa3b, v68
	v_mul_f32_e32 v69, 0xbfb8aa3b, v69
	v_exp_f32_e32 v68, v68
	v_exp_f32_e32 v69, v69
	s_waitcnt vmcnt(1)
	v_lshlrev_b32_e32 v82, 16, v86
	v_and_b32_e32 v83, 0xffff0000, v86
	s_waitcnt vmcnt(0)
	v_lshlrev_b32_e32 v74, 16, v78
	v_and_b32_e32 v78, 0xffff0000, v78
	v_rcp_f32_e32 v96, v71
	v_and_b32_e32 v75, 0xffff0000, v88
	v_lshlrev_b32_e32 v76, 16, v79
	v_and_b32_e32 v77, 0xffff0000, v81
	v_mul_f32_e32 v102, v78, v96
	v_mov_b32_e32 v71, v102
	v_rcp_f32_e32 v86, v70
	v_pk_add_f32 v[68:69], v[68:69], 1.0 op_sel_hi:[1,0]
	v_mul_f32_e32 v97, v74, v86
	v_mov_b32_e32 v70, v97
	v_lshlrev_b32_e32 v78, 16, v80
	v_and_b32_e32 v80, 0xffff0000, v80
	v_pk_add_f32 v[70:71], v[70:71], v[82:83]
	v_rcp_f32_e32 v83, v67
	v_lshlrev_b32_e32 v74, 16, v88
	v_mul_f32_e32 v88, v80, v83
	v_mov_b32_e32 v67, v88
	v_rcp_f32_e32 v82, v66
	s_nop 0
	v_mul_f32_e32 v86, v78, v82
	v_mov_b32_e32 v66, v86
	v_pk_add_f32 v[66:67], v[66:67], v[74:75]
	v_exp_f32_e32 v74, v72
	v_add_f32_e32 v72, v73, v85
	v_mul_f32_e32 v72, 0xbfb8aa3b, v72
	v_exp_f32_e32 v75, v72
	v_and_b32_e32 v78, 0xffff0000, v79
	v_lshlrev_b32_e32 v72, 16, v87
	v_and_b32_e32 v73, 0xffff0000, v87
	v_pk_add_f32 v[74:75], v[74:75], 1.0 op_sel_hi:[1,0]
	s_nop 0
	v_rcp_f32_e32 v80, v75
	s_nop 0
	v_mul_f32_e32 v83, v78, v80
	v_mov_b32_e32 v75, v83
	v_rcp_f32_e32 v79, v74
	s_nop 0
	v_mul_f32_e32 v82, v76, v79
	v_mov_b32_e32 v74, v82
	v_rcp_f32_e32 v79, v69
	v_lshlrev_b32_e32 v76, 16, v81
	v_pk_add_f32 v[72:73], v[74:75], v[72:73]
	v_lshlrev_b32_e32 v74, 16, v89
	v_mul_f32_e32 v81, v77, v79
	v_mov_b32_e32 v69, v81
	v_rcp_f32_e32 v78, v68
	v_and_b32_e32 v75, 0xffff0000, v89
	v_lshl_add_u64 v[82:83], v[94:95], 2, s[44:45]
	v_mul_f32_e32 v80, v76, v78
	v_mov_b32_e32 v68, v80
	v_pk_add_f32 v[68:69], v[68:69], v[74:75]
	s_and_b64 vcc, exec, s[40:41]
	s_cbranch_vccnz .LBB0_1300
	global_store_dwordx4 v[82:83], v[70:73], off
	global_store_dwordx4 v[82:83], v[66:69], off offset:16
	s_cbranch_execnz .LBB0_1270

; __device__ __forceinline__ unsigned cvt_pk_bf16(float lo, float hi) { unsigned r; asm volatile("v_cvt_pk_bf16_f32 %0, %1, %2" : "=v"(r) : "v"(lo), "v"(hi)); return r; }
;     __device__ __forceinline__ void operator()(const f32x4 (&acc)[2][2][4][2], const Unit& u, int wr, int wc, int fr, int fq) const {
;     ...
;         for (int bj = 0; bj < 2; ++bj) { const f32x4 b0 = *(const f32x4*)(bg + col0 + bj * HALF), b1 = *(const f32x4*)(bg + col0 + bj * HALF + 4);
; #pragma unroll
;             for (int ai = 0; ai < 2; ++ai)
; #pragma unroll
;                 for (int m = 0; m < 4; ++m) { const size_t off = (size_t)(u.pm * BM + ai * HALF + wr * 64 + m * 16 + fr) * ldc + col0 + bj * HALF;
;                     const u32x4 xr = *(const u32x4*)(XB + off), pr = *(const u32x4*)(Pp + off); const f32x4 a0 = acc[ai][bj][m][0] + b0, a1 = acc[ai][bj][m][1] + b1;
;                     float x[8], p[8], o[8];
; #pragma unroll
;                     for (int e = 0; e < 4; ++e) { x[2 * e] = __uint_as_float(xr[e] << 16); x[2 * e + 1] = __uint_as_float(xr[e] & 0xffff0000u); p[2 * e] = __uint_as_float(pr[e] << 16); p[2 * e + 1] = __uint_as_float(pr[e] & 0xffff0000u); }
; #pragma unroll
;                     for (int e = 0; e < 4; ++e) { o[e] = x[e] + p[e] / (1.0f + __expf(-a0[e])); o[4 + e] = x[4 + e] + p[4 + e] / (1.0f + __expf(-a1[e])); }
;                     if (OutF) { *(f32x4*)(OutF + off) = (f32x4){o[0], o[1], o[2], o[3]}; *(f32x4*)(OutF + off + 4) = (f32x4){o[4], o[5], o[6], o[7]}; }
;                     else { u32x4 w; w.x = cvt_pk_bf16(o[0], o[1]); w.y = cvt_pk_bf16(o[2], o[3]); w.z = cvt_pk_bf16(o[4], o[5]); w.w = cvt_pk_bf16(o[6], o[7]); *(u32x4*)(XBout + off) = w; } } }
.LBB0_1270:
	global_load_dwordx4 v[66:69], v[160:161], off offset:528
	s_nop 0
	global_load_dwordx4 v[70:73], v[160:161], off offset:512
	v_or_b32_e32 v158, 0x80, v158
	v_lshl_add_u64 v[84:85], v[162:163], 0, v[158:159]
	v_lshlrev_b64 v[74:75], 1, v[84:85]
	v_lshl_add_u64 v[76:77], s[36:37], 0, v[74:75]
	v_lshl_add_u64 v[74:75], s[60:61], 0, v[74:75]
	global_load_dwordx4 v[78:81], v[76:77], off
	s_waitcnt vmcnt(2)
	v_add_f32_e32 v58, v58, v66
	global_load_dwordx4 v[74:77], v[74:75], off
	s_waitcnt vmcnt(2)
	v_add_f32_e32 v62, v62, v70
	v_add_f32_e32 v63, v63, v71
	v_mul_f32_e32 v62, 0xbfb8aa3b, v62
	v_mul_f32_e32 v63, 0xbfb8aa3b, v63
	v_exp_f32_e32 v62, v62
	v_exp_f32_e32 v63, v63
	s_waitcnt vmcnt(1)
	v_lshlrev_b32_e32 v86, 16, v78
	v_and_b32_e32 v87, 0xffff0000, v78
	v_add_f32_e32 v59, v59, v67
	v_pk_add_f32 v[62:63], v[62:63], 1.0 op_sel_hi:[1,0]
	v_mul_f32_e32 v58, 0xbfb8aa3b, v58
	v_mul_f32_e32 v59, 0xbfb8aa3b, v59
	v_exp_f32_e32 v58, v58
	v_exp_f32_e32 v59, v59
	v_add_f32_e32 v64, v64, v72
	v_mul_f32_e32 v64, 0xbfb8aa3b, v64
	v_add_f32_e32 v60, v60, v68
	v_pk_add_f32 v[58:59], v[58:59], 1.0 op_sel_hi:[1,0]
	v_add_f32_e32 v61, v61, v69
	v_mul_f32_e32 v60, 0xbfb8aa3b, v60
	v_mul_f32_e32 v61, 0xbfb8aa3b, v61
	v_exp_f32_e32 v60, v60
	v_exp_f32_e32 v61, v61
	s_waitcnt vmcnt(0)
	v_lshlrev_b32_e32 v78, 16, v74
	v_and_b32_e32 v74, 0xffff0000, v74
	v_rcp_f32_e32 v89, v63
	v_pk_add_f32 v[60:61], v[60:61], 1.0 op_sel_hi:[1,0]
	v_mul_f32_e32 v95, v74, v89
	v_mov_b32_e32 v63, v95
	v_rcp_f32_e32 v88, v62
	s_nop 0
	v_mul_f32_e32 v94, v78, v88
	v_mov_b32_e32 v62, v94
	v_lshlrev_b32_e32 v74, 16, v76
	v_and_b32_e32 v76, 0xffff0000, v76
	v_pk_add_f32 v[62:63], v[62:63], v[86:87]
	v_lshlrev_b32_e32 v86, 16, v80
	v_and_b32_e32 v87, 0xffff0000, v80
	v_rcp_f32_e32 v80, v59
	s_nop 0
	v_mul_f32_e32 v89, v76, v80
	v_mov_b32_e32 v59, v89
	v_rcp_f32_e32 v78, v58
	s_nop 0
	v_mul_f32_e32 v88, v74, v78
	v_mov_b32_e32 v58, v88
	v_pk_add_f32 v[58:59], v[58:59], v[86:87]
	v_exp_f32_e32 v86, v64
	v_add_f32_e32 v64, v65, v73
	v_mul_f32_e32 v64, 0xbfb8aa3b, v64
	v_exp_f32_e32 v87, v64
	v_lshlrev_b32_e32 v76, 16, v75
	v_and_b32_e32 v78, 0xffff0000, v75
	v_lshlrev_b32_e32 v64, 16, v79
	v_pk_add_f32 v[74:75], v[86:87], 1.0 op_sel_hi:[1,0]
	v_and_b32_e32 v65, 0xffff0000, v79
	v_rcp_f32_e32 v80, v75
	s_nop 0
	v_mul_f32_e32 v87, v78, v80
	v_mov_b32_e32 v75, v87
	v_rcp_f32_e32 v79, v74
	s_nop 0
	v_mul_f32_e32 v86, v76, v79
	v_mov_b32_e32 v74, v86
	v_lshlrev_b32_e32 v76, 16, v77
	v_and_b32_e32 v77, 0xffff0000, v77
	v_rcp_f32_e32 v79, v61
	v_pk_add_f32 v[64:65], v[74:75], v[64:65]
	v_lshlrev_b32_e32 v74, 16, v81
	v_and_b32_e32 v75, 0xffff0000, v81
	v_mul_f32_e32 v81, v77, v79
	v_mov_b32_e32 v61, v81
	v_rcp_f32_e32 v78, v60
	s_nop 0
	v_mul_f32_e32 v80, v76, v78
	v_mov_b32_e32 v60, v80
	v_pk_add_f32 v[60:61], v[60:61], v[74:75]
	s_and_b64 vcc, exec, s[40:41]
	s_cbranch_vccnz .LBB0_1301
	global_store_dwordx4 v[138:139], v[62:65], off offset:512
	global_store_dwordx4 v[138:139], v[58:61], off offset:528
	s_cbranch_execnz .LBB0_1273

; __device__ __forceinline__ unsigned cvt_pk_bf16(float lo, float hi) { unsigned r; asm volatile("v_cvt_pk_bf16_f32 %0, %1, %2" : "=v"(r) : "v"(lo), "v"(hi)); return r; }
;     __device__ __forceinline__ void operator()(const f32x4 (&acc)[2][2][4][2], const Unit& u, int wr, int wc, int fr, int fq) const {
;     ...
;                 for (int m = 0; m < 4; ++m) { const size_t off = (size_t)(u.pm * BM + ai * HALF + wr * 64 + m * 16 + fr) * ldc + col0 + bj * HALF;
;                     const u32x4 xr = *(const u32x4*)(XB + off), pr = *(const u32x4*)(Pp + off); const f32x4 a0 = acc[ai][bj][m][0] + b0, a1 = acc[ai][bj][m][1] + b1;
;                     float x[8], p[8], o[8];
; #pragma unroll
;                     for (int e = 0; e < 4; ++e) { x[2 * e] = __uint_as_float(xr[e] << 16); x[2 * e + 1] = __uint_as_float(xr[e] & 0xffff0000u); p[2 * e] = __uint_as_float(pr[e] << 16); p[2 * e + 1] = __uint_as_float(pr[e] & 0xffff0000u); }
; #pragma unroll
;                     for (int e = 0; e < 4; ++e) { o[e] = x[e] + p[e] / (1.0f + __expf(-a0[e])); o[4 + e] = x[4 + e] + p[4 + e] / (1.0f + __expf(-a1[e])); }
;                     if (OutF) { *(f32x4*)(OutF + off) = (f32x4){o[0], o[1], o[2], o[3]}; *(f32x4*)(OutF + off + 4) = (f32x4){o[4], o[5], o[6], o[7]}; }
;                     else { u32x4 w; w.x = cvt_pk_bf16(o[0], o[1]); w.y = cvt_pk_bf16(o[2], o[3]); w.z = cvt_pk_bf16(o[4], o[5]); w.w = cvt_pk_bf16(o[6], o[7]); *(u32x4*)(XBout + off) = w; } } }
.LBB0_1273:
	v_lshl_add_u64 v[74:75], v[140:141], 0, v[158:159]
	v_lshlrev_b64 v[58:59], 1, v[74:75]
	v_lshl_add_u64 v[60:61], s[36:37], 0, v[58:59]
	v_lshl_add_u64 v[58:59], s[60:61], 0, v[58:59]
	global_load_dwordx4 v[62:65], v[60:61], off
	v_add_f32_e32 v54, v54, v70
	global_load_dwordx4 v[58:61], v[58:59], off
	v_add_f32_e32 v55, v55, v71
	v_mul_f32_e32 v54, 0xbfb8aa3b, v54
	v_mul_f32_e32 v55, 0xbfb8aa3b, v55
	v_exp_f32_e32 v54, v54
	v_exp_f32_e32 v55, v55
	v_add_f32_e32 v50, v50, v66
	v_add_f32_e32 v51, v51, v67
	v_mul_f32_e32 v50, 0xbfb8aa3b, v50
	v_pk_add_f32 v[54:55], v[54:55], 1.0 op_sel_hi:[1,0]
	v_mul_f32_e32 v51, 0xbfb8aa3b, v51
	v_exp_f32_e32 v50, v50
	v_exp_f32_e32 v51, v51
	v_add_f32_e32 v56, v56, v72
	v_mul_f32_e32 v56, 0xbfb8aa3b, v56
	v_add_f32_e32 v52, v52, v68
	v_pk_add_f32 v[50:51], v[50:51], 1.0 op_sel_hi:[1,0]
	v_add_f32_e32 v53, v53, v69
	v_mul_f32_e32 v52, 0xbfb8aa3b, v52
	v_mul_f32_e32 v53, 0xbfb8aa3b, v53
	v_exp_f32_e32 v52, v52
	v_exp_f32_e32 v53, v53
	s_waitcnt vmcnt(1)
	v_lshlrev_b32_e32 v76, 16, v62
	v_and_b32_e32 v77, 0xffff0000, v62
	s_waitcnt vmcnt(0)
	v_lshlrev_b32_e32 v62, 16, v58
	v_and_b32_e32 v58, 0xffff0000, v58
	v_rcp_f32_e32 v79, v55
	v_pk_add_f32 v[52:53], v[52:53], 1.0 op_sel_hi:[1,0]
	v_mul_f32_e32 v81, v58, v79
	v_mov_b32_e32 v55, v81
	v_rcp_f32_e32 v78, v54
	s_nop 0
	v_mul_f32_e32 v80, v62, v78
	v_mov_b32_e32 v54, v80
	v_lshlrev_b32_e32 v58, 16, v60
	v_and_b32_e32 v60, 0xffff0000, v60
	v_pk_add_f32 v[54:55], v[54:55], v[76:77]
	v_lshlrev_b32_e32 v76, 16, v64
	v_and_b32_e32 v77, 0xffff0000, v64
	v_rcp_f32_e32 v64, v51
	s_nop 0
	v_mul_f32_e32 v79, v60, v64
	v_mov_b32_e32 v51, v79
	v_rcp_f32_e32 v62, v50
	s_nop 0
	v_mul_f32_e32 v78, v58, v62
	v_mov_b32_e32 v50, v78
	v_pk_add_f32 v[50:51], v[50:51], v[76:77]
	v_exp_f32_e32 v76, v56
	v_add_f32_e32 v56, v57, v73
	v_mul_f32_e32 v56, 0xbfb8aa3b, v56
	v_exp_f32_e32 v77, v56
	v_lshlrev_b32_e32 v60, 16, v59
	v_and_b32_e32 v62, 0xffff0000, v59
	v_lshlrev_b32_e32 v56, 16, v63
	v_pk_add_f32 v[58:59], v[76:77], 1.0 op_sel_hi:[1,0]
	v_and_b32_e32 v57, 0xffff0000, v63
	v_rcp_f32_e32 v64, v59
	s_nop 0
	v_mul_f32_e32 v77, v62, v64
	v_mov_b32_e32 v59, v77
	v_rcp_f32_e32 v63, v58
	s_nop 0
	v_mul_f32_e32 v76, v60, v63
	v_mov_b32_e32 v58, v76
	v_lshlrev_b32_e32 v60, 16, v61
	v_and_b32_e32 v61, 0xffff0000, v61
	v_rcp_f32_e32 v63, v53
	v_pk_add_f32 v[56:57], v[58:59], v[56:57]
	v_lshlrev_b32_e32 v58, 16, v65
	v_and_b32_e32 v59, 0xffff0000, v65
	v_mul_f32_e32 v65, v61, v63
	v_mov_b32_e32 v53, v65
	v_rcp_f32_e32 v62, v52
	s_nop 0
	v_mul_f32_e32 v64, v60, v62
	v_mov_b32_e32 v52, v64
	v_pk_add_f32 v[52:53], v[52:53], v[58:59]
	s_and_b64 vcc, exec, s[40:41]
	s_cbranch_vccnz .LBB0_1302
	global_store_dwordx4 v[130:131], v[54:57], off offset:512
	global_store_dwordx4 v[130:131], v[50:53], off offset:528
	s_cbranch_execnz .LBB0_1276

; __device__ __forceinline__ unsigned cvt_pk_bf16(float lo, float hi) { unsigned r; asm volatile("v_cvt_pk_bf16_f32 %0, %1, %2" : "=v"(r) : "v"(lo), "v"(hi)); return r; }
;     __device__ __forceinline__ void operator()(const f32x4 (&acc)[2][2][4][2], const Unit& u, int wr, int wc, int fr, int fq) const {
;     ...
;                 for (int m = 0; m < 4; ++m) { const size_t off = (size_t)(u.pm * BM + ai * HALF + wr * 64 + m * 16 + fr) * ldc + col0 + bj * HALF;
;                     const u32x4 xr = *(const u32x4*)(XB + off), pr = *(const u32x4*)(Pp + off); const f32x4 a0 = acc[ai][bj][m][0] + b0, a1 = acc[ai][bj][m][1] + b1;
;                     float x[8], p[8], o[8];
; #pragma unroll
;                     for (int e = 0; e < 4; ++e) { x[2 * e] = __uint_as_float(xr[e] << 16); x[2 * e + 1] = __uint_as_float(xr[e] & 0xffff0000u); p[2 * e] = __uint_as_float(pr[e] << 16); p[2 * e + 1] = __uint_as_float(pr[e] & 0xffff0000u); }
; #pragma unroll
;                     for (int e = 0; e < 4; ++e) { o[e] = x[e] + p[e] / (1.0f + __expf(-a0[e])); o[4 + e] = x[4 + e] + p[4 + e] / (1.0f + __expf(-a1[e])); }
;                     if (OutF) { *(f32x4*)(OutF + off) = (f32x4){o[0], o[1], o[2], o[3]}; *(f32x4*)(OutF + off + 4) = (f32x4){o[4], o[5], o[6], o[7]}; }
;                     else { u32x4 w; w.x = cvt_pk_bf16(o[0], o[1]); w.y = cvt_pk_bf16(o[2], o[3]); w.z = cvt_pk_bf16(o[4], o[5]); w.w = cvt_pk_bf16(o[6], o[7]); *(u32x4*)(XBout + off) = w; } } }
.LBB0_1276:
	v_lshl_add_u64 v[58:59], v[132:133], 0, v[158:159]
	v_lshlrev_b64 v[50:51], 1, v[58:59]
	v_lshl_add_u64 v[52:53], s[36:37], 0, v[50:51]
	v_lshl_add_u64 v[50:51], s[60:61], 0, v[50:51]
	global_load_dwordx4 v[54:57], v[52:53], off
	v_add_f32_e32 v44, v44, v70
	global_load_dwordx4 v[50:53], v[50:51], off
	v_add_f32_e32 v45, v45, v71
	v_mul_f32_e32 v44, 0xbfb8aa3b, v44
	v_mul_f32_e32 v45, 0xbfb8aa3b, v45
	v_exp_f32_e32 v44, v44
	v_exp_f32_e32 v45, v45
	v_add_f32_e32 v40, v40, v66
	v_add_f32_e32 v41, v41, v67
	v_mul_f32_e32 v40, 0xbfb8aa3b, v40
	v_pk_add_f32 v[44:45], v[44:45], 1.0 op_sel_hi:[1,0]
	v_mul_f32_e32 v41, 0xbfb8aa3b, v41
	v_exp_f32_e32 v40, v40
	v_exp_f32_e32 v41, v41
	v_add_f32_e32 v46, v46, v72
	v_mul_f32_e32 v46, 0xbfb8aa3b, v46
	v_add_f32_e32 v42, v42, v68
	v_pk_add_f32 v[40:41], v[40:41], 1.0 op_sel_hi:[1,0]
	v_add_f32_e32 v43, v43, v69
	v_mul_f32_e32 v42, 0xbfb8aa3b, v42
	v_mul_f32_e32 v43, 0xbfb8aa3b, v43
	v_exp_f32_e32 v42, v42
	v_exp_f32_e32 v43, v43
	s_waitcnt vmcnt(1)
	v_lshlrev_b32_e32 v60, 16, v54
	v_and_b32_e32 v61, 0xffff0000, v54
	s_waitcnt vmcnt(0)
	v_lshlrev_b32_e32 v54, 16, v50
	v_and_b32_e32 v50, 0xffff0000, v50
	v_rcp_f32_e32 v63, v45
	v_pk_add_f32 v[42:43], v[42:43], 1.0 op_sel_hi:[1,0]
	v_mul_f32_e32 v65, v50, v63
	v_mov_b32_e32 v45, v65
	v_rcp_f32_e32 v62, v44
	s_nop 0
	v_mul_f32_e32 v64, v54, v62
	v_mov_b32_e32 v44, v64
	v_lshlrev_b32_e32 v50, 16, v52
	v_and_b32_e32 v52, 0xffff0000, v52
	v_pk_add_f32 v[44:45], v[44:45], v[60:61]
	v_lshlrev_b32_e32 v60, 16, v56
	v_and_b32_e32 v61, 0xffff0000, v56
	v_rcp_f32_e32 v56, v41
	s_nop 0
	v_mul_f32_e32 v63, v52, v56
	v_mov_b32_e32 v41, v63
	v_rcp_f32_e32 v54, v40
	s_nop 0
	v_mul_f32_e32 v62, v50, v54
	v_mov_b32_e32 v40, v62
	v_pk_add_f32 v[40:41], v[40:41], v[60:61]
	v_exp_f32_e32 v60, v46
	v_add_f32_e32 v46, v47, v73
	v_mul_f32_e32 v46, 0xbfb8aa3b, v46
	v_exp_f32_e32 v61, v46
	v_lshlrev_b32_e32 v52, 16, v51
	v_and_b32_e32 v54, 0xffff0000, v51
	v_lshlrev_b32_e32 v46, 16, v55
	v_pk_add_f32 v[50:51], v[60:61], 1.0 op_sel_hi:[1,0]
	v_and_b32_e32 v47, 0xffff0000, v55
	v_rcp_f32_e32 v56, v51
	s_nop 0
	v_mul_f32_e32 v61, v54, v56
	v_mov_b32_e32 v51, v61
	v_rcp_f32_e32 v55, v50
	s_nop 0
	v_mul_f32_e32 v60, v52, v55
	v_mov_b32_e32 v50, v60
	v_lshlrev_b32_e32 v52, 16, v53
	v_and_b32_e32 v53, 0xffff0000, v53
	v_rcp_f32_e32 v55, v43
	v_pk_add_f32 v[46:47], v[50:51], v[46:47]
	v_lshlrev_b32_e32 v50, 16, v57
	v_and_b32_e32 v51, 0xffff0000, v57
	v_mul_f32_e32 v57, v53, v55
	v_mov_b32_e32 v43, v57
	v_rcp_f32_e32 v54, v42
	s_nop 0
	v_mul_f32_e32 v56, v52, v54
	v_mov_b32_e32 v42, v56
	v_pk_add_f32 v[42:43], v[42:43], v[50:51]
	s_and_b64 vcc, exec, s[40:41]
	s_cbranch_vccnz .LBB0_1303
	global_store_dwordx4 v[122:123], v[44:47], off offset:512
	global_store_dwordx4 v[122:123], v[40:43], off offset:528
	s_cbranch_execnz .LBB0_1279

; __device__ __forceinline__ unsigned cvt_pk_bf16(float lo, float hi) { unsigned r; asm volatile("v_cvt_pk_bf16_f32 %0, %1, %2" : "=v"(r) : "v"(lo), "v"(hi)); return r; }
;     __device__ __forceinline__ void operator()(const f32x4 (&acc)[2][2][4][2], const Unit& u, int wr, int wc, int fr, int fq) const {
;     ...
;                 for (int m = 0; m < 4; ++m) { const size_t off = (size_t)(u.pm * BM + ai * HALF + wr * 64 + m * 16 + fr) * ldc + col0 + bj * HALF;
;                     const u32x4 xr = *(const u32x4*)(XB + off), pr = *(const u32x4*)(Pp + off); const f32x4 a0 = acc[ai][bj][m][0] + b0, a1 = acc[ai][bj][m][1] + b1;
;                     float x[8], p[8], o[8];
; #pragma unroll
;                     for (int e = 0; e < 4; ++e) { x[2 * e] = __uint_as_float(xr[e] << 16); x[2 * e + 1] = __uint_as_float(xr[e] & 0xffff0000u); p[2 * e] = __uint_as_float(pr[e] << 16); p[2 * e + 1] = __uint_as_float(pr[e] & 0xffff0000u); }
; #pragma unroll
;                     for (int e = 0; e < 4; ++e) { o[e] = x[e] + p[e] / (1.0f + __expf(-a0[e])); o[4 + e] = x[4 + e] + p[4 + e] / (1.0f + __expf(-a1[e])); }
;                     if (OutF) { *(f32x4*)(OutF + off) = (f32x4){o[0], o[1], o[2], o[3]}; *(f32x4*)(OutF + off + 4) = (f32x4){o[4], o[5], o[6], o[7]}; }
;                     else { u32x4 w; w.x = cvt_pk_bf16(o[0], o[1]); w.y = cvt_pk_bf16(o[2], o[3]); w.z = cvt_pk_bf16(o[4], o[5]); w.w = cvt_pk_bf16(o[6], o[7]); *(u32x4*)(XBout + off) = w; } } }
.LBB0_1279:
	v_lshl_add_u64 v[50:51], v[124:125], 0, v[158:159]
	v_lshlrev_b64 v[40:41], 1, v[50:51]
	v_lshl_add_u64 v[42:43], s[36:37], 0, v[40:41]
	v_lshl_add_u64 v[40:41], s[60:61], 0, v[40:41]
	global_load_dwordx4 v[44:47], v[42:43], off
	v_add_f32_e32 v36, v36, v70
	global_load_dwordx4 v[40:43], v[40:41], off
	v_add_f32_e32 v37, v37, v71
	v_mul_f32_e32 v36, 0xbfb8aa3b, v36
	v_mul_f32_e32 v37, 0xbfb8aa3b, v37
	v_exp_f32_e32 v36, v36
	v_exp_f32_e32 v37, v37
	v_add_f32_e32 v32, v32, v66
	v_add_f32_e32 v33, v33, v67
	v_mul_f32_e32 v32, 0xbfb8aa3b, v32
	v_pk_add_f32 v[36:37], v[36:37], 1.0 op_sel_hi:[1,0]
	v_mul_f32_e32 v33, 0xbfb8aa3b, v33
	v_exp_f32_e32 v32, v32
	v_exp_f32_e32 v33, v33
	v_add_f32_e32 v38, v38, v72
	v_mul_f32_e32 v38, 0xbfb8aa3b, v38
	v_add_f32_e32 v34, v34, v68
	v_pk_add_f32 v[32:33], v[32:33], 1.0 op_sel_hi:[1,0]
	v_add_f32_e32 v35, v35, v69
	v_mul_f32_e32 v34, 0xbfb8aa3b, v34
	v_mul_f32_e32 v35, 0xbfb8aa3b, v35
	v_exp_f32_e32 v34, v34
	v_exp_f32_e32 v35, v35
	s_waitcnt vmcnt(1)
	v_lshlrev_b32_e32 v52, 16, v44
	v_and_b32_e32 v53, 0xffff0000, v44
	s_waitcnt vmcnt(0)
	v_lshlrev_b32_e32 v44, 16, v40
	v_and_b32_e32 v40, 0xffff0000, v40
	v_rcp_f32_e32 v55, v37
	v_pk_add_f32 v[34:35], v[34:35], 1.0 op_sel_hi:[1,0]
	v_mul_f32_e32 v57, v40, v55
	v_mov_b32_e32 v37, v57
	v_rcp_f32_e32 v54, v36
	s_nop 0
	v_mul_f32_e32 v56, v44, v54
	v_mov_b32_e32 v36, v56
	v_lshlrev_b32_e32 v40, 16, v42
	v_and_b32_e32 v42, 0xffff0000, v42
	v_pk_add_f32 v[36:37], v[36:37], v[52:53]
	v_lshlrev_b32_e32 v52, 16, v46
	v_and_b32_e32 v53, 0xffff0000, v46
	v_rcp_f32_e32 v46, v33
	s_nop 0
	v_mul_f32_e32 v55, v42, v46
	v_mov_b32_e32 v33, v55
	v_rcp_f32_e32 v44, v32
	s_nop 0
	v_mul_f32_e32 v54, v40, v44
	v_mov_b32_e32 v32, v54
	v_pk_add_f32 v[32:33], v[32:33], v[52:53]
	v_exp_f32_e32 v52, v38
	v_add_f32_e32 v38, v39, v73
	v_mul_f32_e32 v38, 0xbfb8aa3b, v38
	v_exp_f32_e32 v53, v38
	v_lshlrev_b32_e32 v42, 16, v41
	v_and_b32_e32 v44, 0xffff0000, v41
	v_lshlrev_b32_e32 v38, 16, v45
	v_pk_add_f32 v[40:41], v[52:53], 1.0 op_sel_hi:[1,0]
	v_and_b32_e32 v39, 0xffff0000, v45
	v_rcp_f32_e32 v46, v41
	s_nop 0
	v_mul_f32_e32 v53, v44, v46
	v_mov_b32_e32 v41, v53
	v_rcp_f32_e32 v45, v40
	s_nop 0
	v_mul_f32_e32 v52, v42, v45
	v_mov_b32_e32 v40, v52
	v_lshlrev_b32_e32 v42, 16, v43
	v_and_b32_e32 v43, 0xffff0000, v43
	v_rcp_f32_e32 v45, v35
	v_pk_add_f32 v[38:39], v[40:41], v[38:39]
	v_lshlrev_b32_e32 v40, 16, v47
	v_and_b32_e32 v41, 0xffff0000, v47
	v_mul_f32_e32 v47, v43, v45
	v_mov_b32_e32 v35, v47
	v_rcp_f32_e32 v44, v34
	s_nop 0
	v_mul_f32_e32 v46, v42, v44
	v_mov_b32_e32 v34, v46
	v_pk_add_f32 v[34:35], v[34:35], v[40:41]
	s_and_b64 vcc, exec, s[40:41]
	s_cbranch_vccnz .LBB0_1304
	global_store_dwordx4 v[114:115], v[36:39], off offset:512
	global_store_dwordx4 v[114:115], v[32:35], off offset:528
	s_cbranch_execnz .LBB0_1282

; __device__ __forceinline__ unsigned cvt_pk_bf16(float lo, float hi) { unsigned r; asm volatile("v_cvt_pk_bf16_f32 %0, %1, %2" : "=v"(r) : "v"(lo), "v"(hi)); return r; }
;     __device__ __forceinline__ void operator()(const f32x4 (&acc)[2][2][4][2], const Unit& u, int wr, int wc, int fr, int fq) const {
;     ...
;                 for (int m = 0; m < 4; ++m) { const size_t off = (size_t)(u.pm * BM + ai * HALF + wr * 64 + m * 16 + fr) * ldc + col0 + bj * HALF;
;                     const u32x4 xr = *(const u32x4*)(XB + off), pr = *(const u32x4*)(Pp + off); const f32x4 a0 = acc[ai][bj][m][0] + b0, a1 = acc[ai][bj][m][1] + b1;
;                     float x[8], p[8], o[8];
; #pragma unroll
;                     for (int e = 0; e < 4; ++e) { x[2 * e] = __uint_as_float(xr[e] << 16); x[2 * e + 1] = __uint_as_float(xr[e] & 0xffff0000u); p[2 * e] = __uint_as_float(pr[e] << 16); p[2 * e + 1] = __uint_as_float(pr[e] & 0xffff0000u); }
; #pragma unroll
;                     for (int e = 0; e < 4; ++e) { o[e] = x[e] + p[e] / (1.0f + __expf(-a0[e])); o[4 + e] = x[4 + e] + p[4 + e] / (1.0f + __expf(-a1[e])); }
;                     if (OutF) { *(f32x4*)(OutF + off) = (f32x4){o[0], o[1], o[2], o[3]}; *(f32x4*)(OutF + off + 4) = (f32x4){o[4], o[5], o[6], o[7]}; }
;                     else { u32x4 w; w.x = cvt_pk_bf16(o[0], o[1]); w.y = cvt_pk_bf16(o[2], o[3]); w.z = cvt_pk_bf16(o[4], o[5]); w.w = cvt_pk_bf16(o[6], o[7]); *(u32x4*)(XBout + off) = w; } } }
.LBB0_1282:
	v_lshl_add_u64 v[40:41], v[116:117], 0, v[158:159]
	v_lshlrev_b64 v[32:33], 1, v[40:41]
	v_lshl_add_u64 v[34:35], s[36:37], 0, v[32:33]
	v_lshl_add_u64 v[32:33], s[60:61], 0, v[32:33]
	global_load_dwordx4 v[36:39], v[34:35], off
	v_add_f32_e32 v28, v28, v70
	global_load_dwordx4 v[32:35], v[32:33], off
	v_add_f32_e32 v29, v29, v71
	v_mul_f32_e32 v28, 0xbfb8aa3b, v28
	v_mul_f32_e32 v29, 0xbfb8aa3b, v29
	v_exp_f32_e32 v28, v28
	v_exp_f32_e32 v29, v29
	v_add_f32_e32 v24, v24, v66
	v_add_f32_e32 v25, v25, v67
	v_mul_f32_e32 v24, 0xbfb8aa3b, v24
	v_pk_add_f32 v[28:29], v[28:29], 1.0 op_sel_hi:[1,0]
	v_mul_f32_e32 v25, 0xbfb8aa3b, v25
	v_exp_f32_e32 v24, v24
	v_exp_f32_e32 v25, v25
	v_add_f32_e32 v30, v30, v72
	v_mul_f32_e32 v30, 0xbfb8aa3b, v30
	v_add_f32_e32 v26, v26, v68
	v_pk_add_f32 v[24:25], v[24:25], 1.0 op_sel_hi:[1,0]
	v_add_f32_e32 v27, v27, v69
	v_mul_f32_e32 v26, 0xbfb8aa3b, v26
	v_mul_f32_e32 v27, 0xbfb8aa3b, v27
	v_exp_f32_e32 v26, v26
	v_exp_f32_e32 v27, v27
	s_waitcnt vmcnt(1)
	v_lshlrev_b32_e32 v42, 16, v36
	v_and_b32_e32 v43, 0xffff0000, v36
	s_waitcnt vmcnt(0)
	v_lshlrev_b32_e32 v36, 16, v32
	v_and_b32_e32 v32, 0xffff0000, v32
	v_rcp_f32_e32 v45, v29
	v_pk_add_f32 v[26:27], v[26:27], 1.0 op_sel_hi:[1,0]
	v_mul_f32_e32 v47, v32, v45
	v_mov_b32_e32 v29, v47
	v_rcp_f32_e32 v44, v28
	s_nop 0
	v_mul_f32_e32 v46, v36, v44
	v_mov_b32_e32 v28, v46
	v_lshlrev_b32_e32 v32, 16, v34
	v_and_b32_e32 v34, 0xffff0000, v34
	v_pk_add_f32 v[28:29], v[28:29], v[42:43]
	v_lshlrev_b32_e32 v42, 16, v38
	v_and_b32_e32 v43, 0xffff0000, v38
	v_rcp_f32_e32 v38, v25
	s_nop 0
	v_mul_f32_e32 v45, v34, v38
	v_mov_b32_e32 v25, v45
	v_rcp_f32_e32 v36, v24
	s_nop 0
	v_mul_f32_e32 v44, v32, v36
	v_mov_b32_e32 v24, v44
	v_pk_add_f32 v[24:25], v[24:25], v[42:43]
	v_exp_f32_e32 v42, v30
	v_add_f32_e32 v30, v31, v73
	v_mul_f32_e32 v30, 0xbfb8aa3b, v30
	v_exp_f32_e32 v43, v30
	v_lshlrev_b32_e32 v34, 16, v33
	v_and_b32_e32 v36, 0xffff0000, v33
	v_lshlrev_b32_e32 v30, 16, v37
	v_pk_add_f32 v[32:33], v[42:43], 1.0 op_sel_hi:[1,0]
	v_and_b32_e32 v31, 0xffff0000, v37
	v_rcp_f32_e32 v38, v33
	s_nop 0
	v_mul_f32_e32 v43, v36, v38
	v_mov_b32_e32 v33, v43
	v_rcp_f32_e32 v37, v32
	s_nop 0
	v_mul_f32_e32 v42, v34, v37
	v_mov_b32_e32 v32, v42
	v_lshlrev_b32_e32 v34, 16, v35
	v_and_b32_e32 v35, 0xffff0000, v35
	v_rcp_f32_e32 v37, v27
	v_pk_add_f32 v[30:31], v[32:33], v[30:31]
	v_lshlrev_b32_e32 v32, 16, v39
	v_and_b32_e32 v33, 0xffff0000, v39
	v_mul_f32_e32 v39, v35, v37
	v_mov_b32_e32 v27, v39
	v_rcp_f32_e32 v36, v26
	s_nop 0
	v_mul_f32_e32 v38, v34, v36
	v_mov_b32_e32 v26, v38
	v_pk_add_f32 v[26:27], v[26:27], v[32:33]
	s_and_b64 vcc, exec, s[40:41]
	s_cbranch_vccnz .LBB0_1305
	global_store_dwordx4 v[106:107], v[28:31], off offset:512
	global_store_dwordx4 v[106:107], v[24:27], off offset:528
	s_cbranch_execnz .LBB0_1285

; __device__ __forceinline__ unsigned cvt_pk_bf16(float lo, float hi) { unsigned r; asm volatile("v_cvt_pk_bf16_f32 %0, %1, %2" : "=v"(r) : "v"(lo), "v"(hi)); return r; }
;     __device__ __forceinline__ void operator()(const f32x4 (&acc)[2][2][4][2], const Unit& u, int wr, int wc, int fr, int fq) const {
;     ...
;                 for (int m = 0; m < 4; ++m) { const size_t off = (size_t)(u.pm * BM + ai * HALF + wr * 64 + m * 16 + fr) * ldc + col0 + bj * HALF;
;                     const u32x4 xr = *(const u32x4*)(XB + off), pr = *(const u32x4*)(Pp + off); const f32x4 a0 = acc[ai][bj][m][0] + b0, a1 = acc[ai][bj][m][1] + b1;
;                     float x[8], p[8], o[8];
; #pragma unroll
;                     for (int e = 0; e < 4; ++e) { x[2 * e] = __uint_as_float(xr[e] << 16); x[2 * e + 1] = __uint_as_float(xr[e] & 0xffff0000u); p[2 * e] = __uint_as_float(pr[e] << 16); p[2 * e + 1] = __uint_as_float(pr[e] & 0xffff0000u); }
; #pragma unroll
;                     for (int e = 0; e < 4; ++e) { o[e] = x[e] + p[e] / (1.0f + __expf(-a0[e])); o[4 + e] = x[4 + e] + p[4 + e] / (1.0f + __expf(-a1[e])); }
;                     if (OutF) { *(f32x4*)(OutF + off) = (f32x4){o[0], o[1], o[2], o[3]}; *(f32x4*)(OutF + off + 4) = (f32x4){o[4], o[5], o[6], o[7]}; }
;                     else { u32x4 w; w.x = cvt_pk_bf16(o[0], o[1]); w.y = cvt_pk_bf16(o[2], o[3]); w.z = cvt_pk_bf16(o[4], o[5]); w.w = cvt_pk_bf16(o[6], o[7]); *(u32x4*)(XBout + off) = w; } } }
.LBB0_1285:
	v_lshl_add_u64 v[32:33], v[108:109], 0, v[158:159]
	v_lshlrev_b64 v[24:25], 1, v[32:33]
	v_lshl_add_u64 v[26:27], s[36:37], 0, v[24:25]
	v_lshl_add_u64 v[24:25], s[60:61], 0, v[24:25]
	global_load_dwordx4 v[28:31], v[26:27], off
	v_add_f32_e32 v20, v20, v70
	global_load_dwordx4 v[24:27], v[24:25], off
	v_add_f32_e32 v21, v21, v71
	v_mul_f32_e32 v20, 0xbfb8aa3b, v20
	v_mul_f32_e32 v21, 0xbfb8aa3b, v21
	v_exp_f32_e32 v20, v20
	v_exp_f32_e32 v21, v21
	v_add_f32_e32 v16, v16, v66
	v_add_f32_e32 v17, v17, v67
	v_mul_f32_e32 v16, 0xbfb8aa3b, v16
	v_pk_add_f32 v[20:21], v[20:21], 1.0 op_sel_hi:[1,0]
	v_mul_f32_e32 v17, 0xbfb8aa3b, v17
	v_exp_f32_e32 v16, v16
	v_exp_f32_e32 v17, v17
	v_add_f32_e32 v22, v22, v72
	v_mul_f32_e32 v22, 0xbfb8aa3b, v22
	v_add_f32_e32 v18, v18, v68
	v_pk_add_f32 v[16:17], v[16:17], 1.0 op_sel_hi:[1,0]
	v_add_f32_e32 v19, v19, v69
	v_mul_f32_e32 v18, 0xbfb8aa3b, v18
	v_mul_f32_e32 v19, 0xbfb8aa3b, v19
	v_exp_f32_e32 v18, v18
	v_exp_f32_e32 v19, v19
	s_waitcnt vmcnt(1)
	v_lshlrev_b32_e32 v34, 16, v28
	v_and_b32_e32 v35, 0xffff0000, v28
	s_waitcnt vmcnt(0)
	v_lshlrev_b32_e32 v28, 16, v24
	v_and_b32_e32 v24, 0xffff0000, v24
	v_rcp_f32_e32 v37, v21
	v_pk_add_f32 v[18:19], v[18:19], 1.0 op_sel_hi:[1,0]
	v_mul_f32_e32 v39, v24, v37
	v_mov_b32_e32 v21, v39
	v_rcp_f32_e32 v36, v20
	s_nop 0
	v_mul_f32_e32 v38, v28, v36
	v_mov_b32_e32 v20, v38
	v_lshlrev_b32_e32 v24, 16, v26
	v_and_b32_e32 v26, 0xffff0000, v26
	v_pk_add_f32 v[20:21], v[20:21], v[34:35]
	v_lshlrev_b32_e32 v34, 16, v30
	v_and_b32_e32 v35, 0xffff0000, v30
	v_rcp_f32_e32 v30, v17
	s_nop 0
	v_mul_f32_e32 v37, v26, v30
	v_mov_b32_e32 v17, v37
	v_rcp_f32_e32 v28, v16
	s_nop 0
	v_mul_f32_e32 v36, v24, v28
	v_mov_b32_e32 v16, v36
	v_pk_add_f32 v[16:17], v[16:17], v[34:35]
	v_exp_f32_e32 v34, v22
	v_add_f32_e32 v22, v23, v73
	v_mul_f32_e32 v22, 0xbfb8aa3b, v22
	v_exp_f32_e32 v35, v22
	v_lshlrev_b32_e32 v26, 16, v25
	v_and_b32_e32 v28, 0xffff0000, v25
	v_lshlrev_b32_e32 v22, 16, v29
	v_pk_add_f32 v[24:25], v[34:35], 1.0 op_sel_hi:[1,0]
	v_and_b32_e32 v23, 0xffff0000, v29
	v_rcp_f32_e32 v30, v25
	s_nop 0
	v_mul_f32_e32 v35, v28, v30
	v_mov_b32_e32 v25, v35
	v_rcp_f32_e32 v29, v24
	s_nop 0
	v_mul_f32_e32 v34, v26, v29
	v_mov_b32_e32 v24, v34
	v_lshlrev_b32_e32 v26, 16, v27
	v_and_b32_e32 v27, 0xffff0000, v27
	v_rcp_f32_e32 v29, v19
	v_pk_add_f32 v[22:23], v[24:25], v[22:23]
	v_lshlrev_b32_e32 v24, 16, v31
	v_and_b32_e32 v25, 0xffff0000, v31
	v_mul_f32_e32 v31, v27, v29
	v_mov_b32_e32 v19, v31
	v_rcp_f32_e32 v28, v18
	s_nop 0
	v_mul_f32_e32 v30, v26, v28
	v_mov_b32_e32 v18, v30
	v_pk_add_f32 v[18:19], v[18:19], v[24:25]
	s_and_b64 vcc, exec, s[40:41]
	s_cbranch_vccnz .LBB0_1306
	global_store_dwordx4 v[98:99], v[20:23], off offset:512
	global_store_dwordx4 v[98:99], v[16:19], off offset:528
	s_cbranch_execnz .LBB0_1288

; __device__ __forceinline__ unsigned cvt_pk_bf16(float lo, float hi) { unsigned r; asm volatile("v_cvt_pk_bf16_f32 %0, %1, %2" : "=v"(r) : "v"(lo), "v"(hi)); return r; }
;     __device__ __forceinline__ void operator()(const f32x4 (&acc)[2][2][4][2], const Unit& u, int wr, int wc, int fr, int fq) const {
;     ...
;                 for (int m = 0; m < 4; ++m) { const size_t off = (size_t)(u.pm * BM + ai * HALF + wr * 64 + m * 16 + fr) * ldc + col0 + bj * HALF;
;                     const u32x4 xr = *(const u32x4*)(XB + off), pr = *(const u32x4*)(Pp + off); const f32x4 a0 = acc[ai][bj][m][0] + b0, a1 = acc[ai][bj][m][1] + b1;
;                     float x[8], p[8], o[8];
; #pragma unroll
;                     for (int e = 0; e < 4; ++e) { x[2 * e] = __uint_as_float(xr[e] << 16); x[2 * e + 1] = __uint_as_float(xr[e] & 0xffff0000u); p[2 * e] = __uint_as_float(pr[e] << 16); p[2 * e + 1] = __uint_as_float(pr[e] & 0xffff0000u); }
; #pragma unroll
;                     for (int e = 0; e < 4; ++e) { o[e] = x[e] + p[e] / (1.0f + __expf(-a0[e])); o[4 + e] = x[4 + e] + p[4 + e] / (1.0f + __expf(-a1[e])); }
;                     if (OutF) { *(f32x4*)(OutF + off) = (f32x4){o[0], o[1], o[2], o[3]}; *(f32x4*)(OutF + off + 4) = (f32x4){o[4], o[5], o[6], o[7]}; }
;                     else { u32x4 w; w.x = cvt_pk_bf16(o[0], o[1]); w.y = cvt_pk_bf16(o[2], o[3]); w.z = cvt_pk_bf16(o[4], o[5]); w.w = cvt_pk_bf16(o[6], o[7]); *(u32x4*)(XBout + off) = w; } } }
.LBB0_1288:
	v_lshl_add_u64 v[24:25], v[100:101], 0, v[158:159]
	v_lshlrev_b64 v[16:17], 1, v[24:25]
	v_lshl_add_u64 v[18:19], s[36:37], 0, v[16:17]
	v_lshl_add_u64 v[16:17], s[60:61], 0, v[16:17]
	global_load_dwordx4 v[20:23], v[18:19], off
	v_add_f32_e32 v12, v12, v70
	global_load_dwordx4 v[16:19], v[16:17], off
	v_add_f32_e32 v13, v13, v71
	v_mul_f32_e32 v12, 0xbfb8aa3b, v12
	v_mul_f32_e32 v13, 0xbfb8aa3b, v13
	v_exp_f32_e32 v12, v12
	v_exp_f32_e32 v13, v13
	v_add_f32_e32 v8, v8, v66
	v_add_f32_e32 v9, v9, v67
	v_mul_f32_e32 v8, 0xbfb8aa3b, v8
	v_pk_add_f32 v[12:13], v[12:13], 1.0 op_sel_hi:[1,0]
	v_mul_f32_e32 v9, 0xbfb8aa3b, v9
	v_exp_f32_e32 v8, v8
	v_exp_f32_e32 v9, v9
	v_add_f32_e32 v14, v14, v72
	v_mul_f32_e32 v14, 0xbfb8aa3b, v14
	v_add_f32_e32 v10, v10, v68
	v_pk_add_f32 v[8:9], v[8:9], 1.0 op_sel_hi:[1,0]
	v_add_f32_e32 v11, v11, v69
	v_mul_f32_e32 v10, 0xbfb8aa3b, v10
	v_mul_f32_e32 v11, 0xbfb8aa3b, v11
	v_exp_f32_e32 v10, v10
	v_exp_f32_e32 v11, v11
	s_waitcnt vmcnt(1)
	v_lshlrev_b32_e32 v26, 16, v20
	v_and_b32_e32 v27, 0xffff0000, v20
	s_waitcnt vmcnt(0)
	v_lshlrev_b32_e32 v20, 16, v16
	v_and_b32_e32 v16, 0xffff0000, v16
	v_rcp_f32_e32 v29, v13
	v_pk_add_f32 v[10:11], v[10:11], 1.0 op_sel_hi:[1,0]
	v_mul_f32_e32 v31, v16, v29
	v_mov_b32_e32 v13, v31
	v_rcp_f32_e32 v28, v12
	s_nop 0
	v_mul_f32_e32 v30, v20, v28
	v_mov_b32_e32 v12, v30
	v_lshlrev_b32_e32 v16, 16, v18
	v_and_b32_e32 v18, 0xffff0000, v18
	v_pk_add_f32 v[12:13], v[12:13], v[26:27]
	v_lshlrev_b32_e32 v26, 16, v22
	v_and_b32_e32 v27, 0xffff0000, v22
	v_rcp_f32_e32 v22, v9
	s_nop 0
	v_mul_f32_e32 v29, v18, v22
	v_mov_b32_e32 v9, v29
	v_rcp_f32_e32 v20, v8
	s_nop 0
	v_mul_f32_e32 v28, v16, v20
	v_mov_b32_e32 v8, v28
	v_pk_add_f32 v[8:9], v[8:9], v[26:27]
	v_exp_f32_e32 v26, v14
	v_add_f32_e32 v14, v15, v73
	v_mul_f32_e32 v14, 0xbfb8aa3b, v14
	v_exp_f32_e32 v27, v14
	v_lshlrev_b32_e32 v18, 16, v17
	v_and_b32_e32 v20, 0xffff0000, v17
	v_lshlrev_b32_e32 v14, 16, v21
	v_pk_add_f32 v[16:17], v[26:27], 1.0 op_sel_hi:[1,0]
	v_and_b32_e32 v15, 0xffff0000, v21
	v_rcp_f32_e32 v22, v17
	s_nop 0
	v_mul_f32_e32 v27, v20, v22
	v_mov_b32_e32 v17, v27
	v_rcp_f32_e32 v21, v16
	s_nop 0
	v_mul_f32_e32 v26, v18, v21
	v_mov_b32_e32 v16, v26
	v_lshlrev_b32_e32 v18, 16, v19
	v_and_b32_e32 v19, 0xffff0000, v19
	v_rcp_f32_e32 v21, v11
	v_pk_add_f32 v[14:15], v[16:17], v[14:15]
	v_lshlrev_b32_e32 v16, 16, v23
	v_and_b32_e32 v17, 0xffff0000, v23
	v_mul_f32_e32 v23, v19, v21
	v_mov_b32_e32 v11, v23
	v_rcp_f32_e32 v20, v10
	s_nop 0
	v_mul_f32_e32 v22, v18, v20
	v_mov_b32_e32 v10, v22
	v_pk_add_f32 v[10:11], v[10:11], v[16:17]
	s_and_b64 vcc, exec, s[40:41]
	s_cbranch_vccnz .LBB0_1307
	global_store_dwordx4 v[90:91], v[12:15], off offset:512
	global_store_dwordx4 v[90:91], v[8:11], off offset:528
	s_cbranch_execnz .LBB0_1291

; __device__ __forceinline__ unsigned cvt_pk_bf16(float lo, float hi) { unsigned r; asm volatile("v_cvt_pk_bf16_f32 %0, %1, %2" : "=v"(r) : "v"(lo), "v"(hi)); return r; }
;     __device__ __forceinline__ void operator()(const f32x4 (&acc)[2][2][4][2], const Unit& u, int wr, int wc, int fr, int fq) const {
;     ...
;                 for (int m = 0; m < 4; ++m) { const size_t off = (size_t)(u.pm * BM + ai * HALF + wr * 64 + m * 16 + fr) * ldc + col0 + bj * HALF;
;                     const u32x4 xr = *(const u32x4*)(XB + off), pr = *(const u32x4*)(Pp + off); const f32x4 a0 = acc[ai][bj][m][0] + b0, a1 = acc[ai][bj][m][1] + b1;
;                     float x[8], p[8], o[8];
; #pragma unroll
;                     for (int e = 0; e < 4; ++e) { x[2 * e] = __uint_as_float(xr[e] << 16); x[2 * e + 1] = __uint_as_float(xr[e] & 0xffff0000u); p[2 * e] = __uint_as_float(pr[e] << 16); p[2 * e + 1] = __uint_as_float(pr[e] & 0xffff0000u); }
; #pragma unroll
;                     for (int e = 0; e < 4; ++e) { o[e] = x[e] + p[e] / (1.0f + __expf(-a0[e])); o[4 + e] = x[4 + e] + p[4 + e] / (1.0f + __expf(-a1[e])); }
;                     if (OutF) { *(f32x4*)(OutF + off) = (f32x4){o[0], o[1], o[2], o[3]}; *(f32x4*)(OutF + off + 4) = (f32x4){o[4], o[5], o[6], o[7]}; }
;                     else { u32x4 w; w.x = cvt_pk_bf16(o[0], o[1]); w.y = cvt_pk_bf16(o[2], o[3]); w.z = cvt_pk_bf16(o[4], o[5]); w.w = cvt_pk_bf16(o[6], o[7]); *(u32x4*)(XBout + off) = w; } } }
.LBB0_1291:
	v_lshl_add_u64 v[16:17], v[92:93], 0, v[158:159]
	v_lshlrev_b64 v[8:9], 1, v[16:17]
	v_lshl_add_u64 v[10:11], s[36:37], 0, v[8:9]
	v_lshl_add_u64 v[8:9], s[60:61], 0, v[8:9]
	global_load_dwordx4 v[12:15], v[10:11], off
	v_add_f32_e32 v4, v4, v70
	global_load_dwordx4 v[8:11], v[8:9], off
	v_add_f32_e32 v5, v5, v71
	v_mul_f32_e32 v4, 0xbfb8aa3b, v4
	v_mul_f32_e32 v5, 0xbfb8aa3b, v5
	v_exp_f32_e32 v4, v4
	v_exp_f32_e32 v5, v5
	v_add_f32_e32 v0, v0, v66
	v_add_f32_e32 v1, v1, v67
	v_mul_f32_e32 v0, 0xbfb8aa3b, v0
	v_pk_add_f32 v[4:5], v[4:5], 1.0 op_sel_hi:[1,0]
	v_mul_f32_e32 v1, 0xbfb8aa3b, v1
	v_exp_f32_e32 v0, v0
	v_exp_f32_e32 v1, v1
	v_add_f32_e32 v6, v6, v72
	v_mul_f32_e32 v6, 0xbfb8aa3b, v6
	v_add_f32_e32 v2, v2, v68
	v_pk_add_f32 v[0:1], v[0:1], 1.0 op_sel_hi:[1,0]
	v_add_f32_e32 v3, v3, v69
	v_mul_f32_e32 v2, 0xbfb8aa3b, v2
	v_mul_f32_e32 v3, 0xbfb8aa3b, v3
	v_exp_f32_e32 v2, v2
	v_exp_f32_e32 v3, v3
	s_waitcnt vmcnt(1)
	v_lshlrev_b32_e32 v18, 16, v12
	v_and_b32_e32 v19, 0xffff0000, v12
	s_waitcnt vmcnt(0)
	v_lshlrev_b32_e32 v12, 16, v8
	v_and_b32_e32 v8, 0xffff0000, v8
	v_rcp_f32_e32 v21, v5
	v_pk_add_f32 v[2:3], v[2:3], 1.0 op_sel_hi:[1,0]
	v_mul_f32_e32 v23, v8, v21
	v_mov_b32_e32 v5, v23
	v_rcp_f32_e32 v20, v4
	s_nop 0
	v_mul_f32_e32 v22, v12, v20
	v_mov_b32_e32 v4, v22
	v_lshlrev_b32_e32 v8, 16, v10
	v_and_b32_e32 v10, 0xffff0000, v10
	v_pk_add_f32 v[4:5], v[4:5], v[18:19]
	v_lshlrev_b32_e32 v18, 16, v14
	v_and_b32_e32 v19, 0xffff0000, v14
	v_rcp_f32_e32 v14, v1
	s_nop 0
	v_mul_f32_e32 v21, v10, v14
	v_mov_b32_e32 v1, v21
	v_rcp_f32_e32 v12, v0
	s_nop 0
	v_mul_f32_e32 v20, v8, v12
	v_mov_b32_e32 v0, v20
	v_pk_add_f32 v[0:1], v[0:1], v[18:19]
	v_exp_f32_e32 v18, v6
	v_add_f32_e32 v6, v7, v73
	v_mul_f32_e32 v6, 0xbfb8aa3b, v6
	v_exp_f32_e32 v19, v6
	v_lshlrev_b32_e32 v10, 16, v9
	v_and_b32_e32 v12, 0xffff0000, v9
	v_lshlrev_b32_e32 v6, 16, v13
	v_pk_add_f32 v[8:9], v[18:19], 1.0 op_sel_hi:[1,0]
	v_and_b32_e32 v7, 0xffff0000, v13
	v_rcp_f32_e32 v14, v9
	s_nop 0
	v_mul_f32_e32 v19, v12, v14
	v_mov_b32_e32 v9, v19
	v_rcp_f32_e32 v13, v8
	s_nop 0
	v_mul_f32_e32 v18, v10, v13
	v_mov_b32_e32 v8, v18
	v_lshlrev_b32_e32 v10, 16, v11
	v_and_b32_e32 v11, 0xffff0000, v11
	v_rcp_f32_e32 v13, v3
	v_pk_add_f32 v[6:7], v[8:9], v[6:7]
	v_lshlrev_b32_e32 v8, 16, v15
	v_and_b32_e32 v9, 0xffff0000, v15
	v_mul_f32_e32 v15, v11, v13
	v_mov_b32_e32 v3, v15
	v_rcp_f32_e32 v12, v2
	s_nop 0
	v_mul_f32_e32 v14, v10, v12
	v_mov_b32_e32 v2, v14
	v_pk_add_f32 v[2:3], v[2:3], v[8:9]
	s_and_b64 vcc, exec, s[40:41]
	s_cbranch_vccnz .LBB0_1308
	s_mov_b64 s[6:7], 0
	global_store_dwordx4 v[82:83], v[4:7], off offset:512
	global_store_dwordx4 v[82:83], v[0:3], off offset:528
	s_branch .LBB0_1309
